# k11: k9 + chunk-pass end-of-unit store drains relaxed to lgkmcnt only
# speedup vs baseline: 1.0123x; 1.0015x over previous
; template <bool GLA>
; __device__ __forceinline__ void chunk_tile(const ChunkRaw& raw, const bf16x8 (&wfr)[2], const f32x4 (&bfr)[2], int h, int it, int row, int kq, float lg, float (&carry)[8], float (&bq)[8], float (&qv)[8], float (&kv)[8]) {
;     ...
;     if (GLA) {
;         const u32x4 gsel = (kq == 0) ? raw.g0 : (kq == 1) ? raw.g1 : (u32x4){0u, 0u, 0u, 0u};
;         const bf16x8 gfr = __builtin_bit_cast(bf16x8, gsel);
;         const f32x4 z0 = __builtin_amdgcn_mfma_f32_16x16x32_bf16(wfr[0], gfr, bfr[0], 0, 0, 0), z1 = __builtin_amdgcn_mfma_f32_16x16x32_bf16(wfr[1], gfr, bfr[1], 0, 0, 0);
;         const float z[8] = {z0[0], z0[1], z0[2], z0[3], z1[0], z1[1], z1[2], z1[3]};
; #pragma unroll
;         for (int j = 0; j < 8; ++j) {
;             float la = (fminf(z[j], 0.f) - __logf(1.0f + __expf(-fabsf(z[j])))) * (1.0f / 16.0f);
;             la += __int_as_float(__builtin_amdgcn_update_dpp(0, __float_as_int(la), 0x111, 0xf, 0xf, false));
;             la += __int_as_float(__builtin_amdgcn_update_dpp(0, __float_as_int(la), 0x112, 0xf, 0xf, false));
;             la += __int_as_float(__builtin_amdgcn_update_dpp(0, __float_as_int(la), 0x114, 0xf, 0xf, false));
;             la += __int_as_float(__builtin_amdgcn_update_dpp(0, __float_as_int(la), 0x118, 0xf, 0xf, false));
;             bq[j] = la + carry[j];
;             carry[j] += __int_as_float(__builtin_amdgcn_ds_bpermute((16 * kq + 15) * 4, __float_as_int(la)));
;             qv[j] = q[j] * qs; kv[j] = k[j];
; template <bool GLA>
; __device__ __forceinline__ void chunk_pass_c(const ChunkIn& ci, const float* wgl, int unit, unsigned char* wl, int lane, const float* Sb, const float* ng, bf16_t* omix) {
;     ...
;         float a[8], bneg[8], cpos[8], dneg[8];
; #pragma unroll
;         for (int j = 0; j < 8; ++j) { const float eb = __expf(bq[j]), enb = __expf(-bq[j]); a[j] = qv[j] * eb; bneg[j] = kv[j] * enb; cpos[j] = qv[j] * enb; dneg[j] = kv[j] * eb; }
;         qf[it] = __builtin_bit_cast(bf16x8, (u32x4){cvtpk(a[0], a[1]), cvtpk(a[2], a[3]), cvtpk(a[4], a[5]), cvtpk(a[6], a[7])});
;         kf[it] = __builtin_bit_cast(bf16x8, (u32x4){cvtpk(bneg[0], bneg[1]), cvtpk(bneg[2], bneg[3]), cvtpk(bneg[4], bneg[5]), cvtpk(bneg[6], bneg[7])});
;         qb[it] = __builtin_bit_cast(bf16x8, (u32x4){cvtpk(cpos[0], cpos[1]), cvtpk(cpos[2], cpos[3]), cvtpk(cpos[4], cpos[5]), cvtpk(cpos[6], cpos[7])});
.LBB0_213:
	s_andn2_saveexec_b64 s[6:7], s[6:7]
	s_or_b64 exec, exec, s[6:7]
	s_waitcnt vmcnt(1)
	v_mfma_f32_16x16x32_bf16 v[16:19], v[16:19], v[4:7], v[8:11]
	s_waitcnt vmcnt(0)
	v_lshlrev_b32_e32 v0, 16, v82
	v_and_b32_e32 v1, 0xffff0000, v82
	s_mov_b32 s8, 0x3e3504f3
	v_pk_mul_f32 v[138:139], v[0:1], s[8:9] op_sel_hi:[1,0]
	v_lshlrev_b32_e32 v0, 16, v83
	v_and_b32_e32 v1, 0xffff0000, v83
	s_mov_b32 s7, 0xbfb8aa3b
	v_pk_mul_f32 v[82:83], v[0:1], s[8:9] op_sel_hi:[1,0]
	v_lshlrev_b32_e32 v0, 16, v78
	v_and_b32_e32 v1, 0xffff0000, v78
	v_mfma_f32_16x16x32_bf16 v[10:13], v[20:23], v[4:7], v[12:15]
	v_mul_f32_e64 v5, |v16|, s7
	v_pk_mul_f32 v[126:127], v[0:1], s[8:9] op_sel_hi:[1,0]
	v_lshlrev_b32_e32 v0, 16, v79
	v_and_b32_e32 v1, 0xffff0000, v79
	v_exp_f32_e32 v5, v5
	v_pk_mul_f32 v[118:119], v[0:1], s[8:9] op_sel_hi:[1,0]
	v_lshlrev_b32_e32 v0, 16, v70
	v_and_b32_e32 v1, 0xffff0000, v70
	v_pk_mul_f32 v[140:141], v[0:1], s[8:9] op_sel_hi:[1,0]
	v_lshlrev_b32_e32 v0, 16, v71
	v_and_b32_e32 v1, 0xffff0000, v71
	v_lshlrev_b32_e32 v124, 16, v72
	v_and_b32_e32 v125, 0xffff0000, v72
	v_lshlrev_b32_e32 v26, 16, v73
	v_and_b32_e32 v27, 0xffff0000, v73
	v_pk_mul_f32 v[72:73], v[0:1], s[8:9] op_sel_hi:[1,0]
	v_lshlrev_b32_e32 v0, 16, v68
	v_and_b32_e32 v1, 0xffff0000, v68
	v_pk_mul_f32 v[70:71], v[0:1], s[8:9] op_sel_hi:[1,0]
	v_lshlrev_b32_e32 v0, 16, v69
	v_and_b32_e32 v1, 0xffff0000, v69
	v_add_f32_e32 v5, 1.0, v5
	v_pk_mul_f32 v[30:31], v[0:1], s[8:9] op_sel_hi:[1,0]
	v_add_f32_e32 v0, 0, v53
	v_cmp_gt_f32_e32 vcc, s96, v5
	v_mul_f32_e32 v1, 0x3fb8aa3b, v0
	v_exp_f32_e32 v68, v1
	v_cndmask_b32_e64 v6, 0, 32, vcc
	v_add_f32_e32 v1, 0, v55
	v_ldexp_f32 v5, v5, v6
	v_mul_f32_e32 v2, 0x3fb8aa3b, v1
	v_log_f32_e32 v5, v5
	v_exp_f32_e32 v69, v2
	v_add_f32_e32 v2, 0, v63
	v_mul_f32_e32 v3, 0x3fb8aa3b, v2
	v_lshlrev_b32_e32 v136, 16, v76
	v_and_b32_e32 v137, 0xffff0000, v76
	v_exp_f32_e32 v76, v3
	v_add_f32_e32 v3, 0, v75
	v_mul_f32_e32 v53, 0x3fb8aa3b, v3
	v_mul_f32_e32 v6, 0x3f317217, v5
	v_lshlrev_b32_e32 v78, 16, v77
	v_and_b32_e32 v79, 0xffff0000, v77
	v_exp_f32_e32 v77, v53
	v_add_f32_e32 v53, 0, v81
	v_fma_f32 v6, v5, s3, -v6
	v_mul_f32_e32 v55, 0x3fb8aa3b, v53
	v_fmac_f32_e32 v6, 0x3377d1cf, v5
	s_mov_b32 s6, 0x7f800000
	v_lshlrev_b32_e32 v122, 16, v84
	v_and_b32_e32 v123, 0xffff0000, v84
	v_exp_f32_e32 v84, v55
	v_add_f32_e32 v55, 0, v91
	v_fmac_f32_e32 v6, 0x3f317217, v5
	v_cmp_lt_f32_e64 s[42:43], |v5|, s6
	v_mul_f32_e32 v63, 0x3fb8aa3b, v55
	v_max_f32_e32 v4, v16, v16
	v_cndmask_b32_e64 v5, v5, v6, s[42:43]
	v_cndmask_b32_e32 v6, 0, v237, vcc
	v_lshlrev_b32_e32 v116, 16, v85
	v_and_b32_e32 v117, 0xffff0000, v85
	v_exp_f32_e32 v85, v63
	v_add_f32_e32 v63, 0, v93
	v_min_f32_e32 v4, 0, v4
	v_sub_f32_e32 v5, v5, v6
	v_mul_f32_e32 v75, 0x3fb8aa3b, v63
	v_sub_f32_e32 v4, v4, v5
	v_exp_f32_e32 v144, v75
	v_add_f32_e32 v75, 0, v99
	v_mul_f32_e32 v6, 0x3d800000, v4
	v_mov_b32_e32 v5, v211
	v_mul_f32_e32 v81, 0x3fb8aa3b, v75
	v_exp_f32_e32 v145, v81
	v_mov_b32_dpp v5, v6 row_shr:1 row_mask:0xf bank_mask:0xf
	v_fmac_f32_e32 v5, 0x3d800000, v4
	v_mov_b32_e32 v81, v211
	v_mov_b32_e32 v4, v211
	v_mov_b32_e32 v93, v211
	v_mov_b32_dpp v81, v5 row_shr:2 row_mask:0xf bank_mask:0xf
	s_waitcnt lgkmcnt(14)
	v_pk_add_f32 v[4:5], v[4:5], v[80:81]
	v_mov_b32_e32 v99, v211
	v_mul_f32_e32 v0, 0xbfb8aa3b, v0
	v_mov_b32_dpp v93, v5 row_shr:4 row_mask:0xf bank_mask:0xf
	v_pk_add_f32 v[6:7], v[4:5], v[92:93]
	v_add_f32_e32 v4, v4, v89
	v_add_f32_e32 v5, v6, v133
	v_mul_f32_e32 v8, 0x3fb8aa3b, v5
	v_mul_f32_e32 v5, 0xbfb8aa3b, v5
	v_exp_f32_e32 v16, v5
	v_mul_f32_e32 v5, 0x3fb8aa3b, v4
	v_mul_f32_e32 v4, 0xbfb8aa3b, v4
	v_mov_b32_dpp v99, v7 row_shr:8 row_mask:0xf bank_mask:0xf
	v_exp_f32_e32 v20, v5
	v_exp_f32_e32 v22, v4
	s_waitcnt lgkmcnt(7)
	v_pk_add_f32 v[4:5], v[6:7], v[98:99]
	v_exp_f32_e32 v102, v0
	v_add_f32_e32 v14, v4, v5
	v_mul_f32_e64 v5, |v17|, s7
	v_exp_f32_e32 v5, v5
	v_mul_f32_e32 v0, 0xbfb8aa3b, v1
	v_exp_f32_e32 v103, v0
	v_mul_f32_e32 v0, 0xbfb8aa3b, v2
	v_add_f32_e32 v5, 1.0, v5
	v_exp_f32_e32 v104, v0
	v_mul_f32_e32 v0, 0xbfb8aa3b, v3
	v_cmp_gt_f32_e32 vcc, s96, v5
	v_exp_f32_e32 v105, v0
	v_mul_f32_e32 v0, 0xbfb8aa3b, v53
	v_cndmask_b32_e64 v6, 0, 32, vcc
	v_exp_f32_e32 v112, v0
	v_mul_f32_e32 v0, 0xbfb8aa3b, v55
	v_ldexp_f32 v5, v5, v6
	v_exp_f32_e32 v113, v0
	v_mul_f32_e32 v0, 0xbfb8aa3b, v63
	v_log_f32_e32 v5, v5
	v_exp_f32_e32 v148, v0
	v_mul_f32_e32 v0, 0xbfb8aa3b, v75
	v_exp_f32_e32 v149, v0
	v_lshlrev_b32_e32 v0, 16, v66
	v_and_b32_e32 v1, 0xffff0000, v66
	v_pk_mul_f32 v[2:3], v[68:69], v[0:1]
	v_mul_f32_e32 v6, 0x3f317217, v5
	v_cvt_pk_bf16_f32 v106, v2, v3
	v_lshlrev_b32_e32 v2, 16, v67
	v_and_b32_e32 v3, 0xffff0000, v67
	v_pk_mul_f32 v[0:1], v[102:103], v[0:1]
	v_pk_mul_f32 v[66:67], v[76:77], v[2:3]
	v_pk_mul_f32 v[2:3], v[104:105], v[2:3]
	v_fma_f32 v6, v5, s3, -v6
	v_cvt_pk_bf16_f32 v0, v0, v1
	v_cvt_pk_bf16_f32 v1, v2, v3
	v_lshlrev_b32_e32 v2, 16, v64
	v_and_b32_e32 v3, 0xffff0000, v64
	v_fmac_f32_e32 v6, 0x3377d1cf, v5
	v_cvt_pk_bf16_f32 v107, v66, v67
	v_pk_mul_f32 v[66:67], v[84:85], v[2:3]
	v_lshlrev_b32_e32 v64, 16, v65
	v_and_b32_e32 v65, 0xffff0000, v65
	v_fmac_f32_e32 v6, 0x3f317217, v5
	v_cmp_lt_f32_e64 s[42:43], |v5|, s6
	v_cvt_pk_bf16_f32 v108, v66, v67
	v_pk_mul_f32 v[2:3], v[112:113], v[2:3]
	v_pk_mul_f32 v[66:67], v[144:145], v[64:65]
	v_pk_mul_f32 v[64:65], v[148:149], v[64:65]
	v_max_f32_e32 v4, v17, v17
	v_cndmask_b32_e64 v5, v5, v6, s[42:43]
	v_cndmask_b32_e32 v6, 0, v237, vcc
	v_cvt_pk_bf16_f32 v2, v2, v3
	v_cvt_pk_bf16_f32 v3, v64, v65
	v_lshlrev_b32_e32 v64, 16, v60
	v_and_b32_e32 v65, 0xffff0000, v60
; __device__ __forceinline__ unsigned cvtpk(float lo, float hi) { f32x2_t v = {lo, hi}; bf16x2_t b = __builtin_convertvector(v, bf16x2_t); return __builtin_bit_cast(unsigned, b); }
; template <bool GLA>
; __device__ __forceinline__ void chunk_tile(const ChunkRaw& raw, const bf16x8 (&wfr)[2], const f32x4 (&bfr)[2], int h, int it, int row, int kq, float lg, float (&carry)[8], float (&bq)[8], float (&qv)[8], float (&kv)[8]) {
;     ...
;         for (int j = 0; j < 8; ++j) {
;             float la = (fminf(z[j], 0.f) - __logf(1.0f + __expf(-fabsf(z[j])))) * (1.0f / 16.0f);
;             la += __int_as_float(__builtin_amdgcn_update_dpp(0, __float_as_int(la), 0x111, 0xf, 0xf, false));
;             la += __int_as_float(__builtin_amdgcn_update_dpp(0, __float_as_int(la), 0x112, 0xf, 0xf, false));
;             la += __int_as_float(__builtin_amdgcn_update_dpp(0, __float_as_int(la), 0x114, 0xf, 0xf, false));
;             la += __int_as_float(__builtin_amdgcn_update_dpp(0, __float_as_int(la), 0x118, 0xf, 0xf, false));
;             bq[j] = la + carry[j];
;             carry[j] += __int_as_float(__builtin_amdgcn_ds_bpermute((16 * kq + 15) * 4, __float_as_int(la)));
;             qv[j] = q[j] * qs; kv[j] = k[j];
; template <bool GLA>
; __device__ __forceinline__ void chunk_pass_c(const ChunkIn& ci, const float* wgl, int unit, unsigned char* wl, int lane, const float* Sb, const float* ng, bf16_t* omix) {
;     ...
;         float a[8], bneg[8], cpos[8], dneg[8];
; #pragma unroll
;         for (int j = 0; j < 8; ++j) { const float eb = __expf(bq[j]), enb = __expf(-bq[j]); a[j] = qv[j] * eb; bneg[j] = kv[j] * enb; cpos[j] = qv[j] * enb; dneg[j] = kv[j] * eb; }
;         qf[it] = __builtin_bit_cast(bf16x8, (u32x4){cvtpk(a[0], a[1]), cvtpk(a[2], a[3]), cvtpk(a[4], a[5]), cvtpk(a[6], a[7])});
;         kf[it] = __builtin_bit_cast(bf16x8, (u32x4){cvtpk(bneg[0], bneg[1]), cvtpk(bneg[2], bneg[3]), cvtpk(bneg[4], bneg[5]), cvtpk(bneg[6], bneg[7])});
;         qb[it] = __builtin_bit_cast(bf16x8, (u32x4){cvtpk(cpos[0], cpos[1]), cvtpk(cpos[2], cpos[3]), cvtpk(cpos[4], cpos[5]), cvtpk(cpos[6], cpos[7])});
;         kb[it] = __builtin_bit_cast(bf16x8, (u32x4){cvtpk(dneg[0], dneg[1]), cvtpk(dneg[2], dneg[3]), cvtpk(dneg[4], dneg[5]), cvtpk(dneg[6], dneg[7])});
	v_min_f32_e32 v4, 0, v4
	v_sub_f32_e32 v5, v5, v6
	v_pk_mul_f32 v[64:65], v[64:65], s[8:9] op_sel_hi:[1,0]
	v_lshlrev_b32_e32 v60, 16, v61
	v_and_b32_e32 v61, 0xffff0000, v61
	v_sub_f32_e32 v4, v4, v5
	v_cvt_pk_bf16_f32 v109, v66, v67
	v_pk_mul_f32 v[66:67], v[64:65], v[102:103]
	v_pk_mul_f32 v[64:65], v[64:65], v[68:69]
	v_pk_mul_f32 v[60:61], v[60:61], s[8:9] op_sel_hi:[1,0]
	v_mul_f32_e32 v6, 0x3d800000, v4
	v_mov_b32_e32 v5, v211
	v_cvt_pk_bf16_f32 v102, v64, v65
	v_pk_mul_f32 v[64:65], v[60:61], v[104:105]
	v_pk_mul_f32 v[60:61], v[60:61], v[76:77]
	v_mov_b32_dpp v5, v6 row_shr:1 row_mask:0xf bank_mask:0xf
	v_cvt_pk_bf16_f32 v103, v60, v61
	v_lshlrev_b32_e32 v60, 16, v58
	v_and_b32_e32 v61, 0xffff0000, v58
	v_fmac_f32_e32 v5, 0x3d800000, v4
	v_mov_b32_e32 v75, v211
	v_pk_mul_f32 v[60:61], v[60:61], s[8:9] op_sel_hi:[1,0]
	v_lshlrev_b32_e32 v58, 16, v59
	v_and_b32_e32 v59, 0xffff0000, v59
	v_mov_b32_dpp v75, v5 row_shr:2 row_mask:0xf bank_mask:0xf
	v_mov_b32_e32 v4, v211
	v_cvt_pk_bf16_f32 v111, v64, v65
	v_pk_mul_f32 v[64:65], v[60:61], v[112:113]
	v_pk_mul_f32 v[60:61], v[60:61], v[84:85]
	v_pk_mul_f32 v[58:59], v[58:59], s[8:9] op_sel_hi:[1,0]
	v_pk_add_f32 v[6:7], v[4:5], v[74:75]
	v_mov_b32_e32 v89, v211
	v_cvt_pk_bf16_f32 v104, v60, v61
	v_pk_mul_f32 v[60:61], v[58:59], v[148:149]
	v_pk_mul_f32 v[58:59], v[58:59], v[144:145]
	v_mov_b32_dpp v89, v7 row_shr:4 row_mask:0xf bank_mask:0xf
	v_cvt_pk_bf16_f32 v105, v58, v59
	v_pk_add_f32 v[58:59], v[6:7], v[88:89]
	v_exp_f32_e32 v8, v8
	v_add_f32_e32 v4, v58, v131
	v_mul_f32_e32 v5, 0x3fb8aa3b, v4
	v_exp_f32_e32 v9, v5
	v_mul_f32_e32 v4, 0xbfb8aa3b, v4
	v_exp_f32_e32 v17, v4
	v_lshlrev_b32_e32 v134, 16, v86
	v_and_b32_e32 v135, 0xffff0000, v86
	v_pk_mul_f32 v[4:5], v[8:9], v[134:135]
	v_pk_mul_f32 v[8:9], v[138:139], v[8:9]
	v_cvt_pk_bf16_f32 v84, v4, v5
	v_pk_mul_f32 v[4:5], v[16:17], v[134:135]
	v_cvt_pk_bf16_f32 v76, v8, v9
	v_cvt_pk_bf16_f32 v4, v4, v5
	v_add_f32_e32 v5, v6, v57
	v_mul_f32_e32 v6, 0x3fb8aa3b, v5
	v_exp_f32_e32 v21, v6
	v_mul_f32_e32 v5, 0xbfb8aa3b, v5
	v_exp_f32_e32 v23, v5
	v_mov_b32_e32 v133, v211
	v_pk_mul_f32 v[6:7], v[20:21], v[136:137]
	v_max_f32_e32 v5, v18, v18
	v_cvt_pk_bf16_f32 v98, v6, v7
	v_pk_mul_f32 v[6:7], v[22:23], v[136:137]
	v_mov_b32_dpp v133, v59 row_shr:8 row_mask:0xf bank_mask:0xf
	v_cvt_pk_bf16_f32 v8, v6, v7
	v_pk_mul_f32 v[6:7], v[140:141], v[22:23]
	v_min_f32_e32 v5, 0, v5
	v_cvt_pk_bf16_f32 v92, v6, v7
	v_pk_mul_f32 v[6:7], v[140:141], v[20:21]
	v_mov_b32_e32 v63, v211
	v_cvt_pk_bf16_f32 v88, v6, v7
	s_waitcnt lgkmcnt(6)
	v_pk_add_f32 v[6:7], v[58:59], v[132:133]
	v_mov_b32_e32 v95, v211
	v_add_f32_e32 v15, v6, v7
	v_mul_f32_e64 v6, |v18|, s7
	v_exp_f32_e32 v6, v6
	v_pk_mul_f32 v[16:17], v[138:139], v[16:17]
	v_mov_b32_e32 v131, v211
	v_cvt_pk_bf16_f32 v80, v16, v17
	v_add_f32_e32 v6, 1.0, v6
	v_cmp_gt_f32_e32 vcc, s96, v6
	v_mov_b32_e32 v57, v211
	v_mov_b32_e32 v91, v211
	v_cndmask_b32_e64 v7, 0, 32, vcc
	v_ldexp_f32 v6, v6, v7
	v_log_f32_e32 v6, v6
	v_mov_b32_e32 v55, v211
	v_lshlrev_b32_e32 v86, 16, v87
	v_and_b32_e32 v87, 0xffff0000, v87
	v_mul_f32_e32 v7, 0x3f317217, v6
	v_fma_f32 v7, v6, s3, -v7
	v_fmac_f32_e32 v7, 0x3377d1cf, v6
	v_fmac_f32_e32 v7, 0x3f317217, v6
	v_cmp_lt_f32_e64 s[42:43], |v6|, s6
	v_cvt_pk_bf16_f32 v113, v60, v61
	v_mov_b32_e32 v53, v211
	v_cndmask_b32_e64 v6, v6, v7, s[42:43]
	v_cndmask_b32_e32 v7, 0, v237, vcc
	v_sub_f32_e32 v6, v6, v7
	v_sub_f32_e32 v5, v5, v6
	v_mul_f32_e32 v6, 0x3d800000, v5
	v_mov_b32_e32 v7, v211
	s_waitcnt vmcnt(0) expcnt(0) lgkmcnt(0)
	v_cvt_pk_bf16_f32 v110, v66, v67
	v_mov_b32_dpp v7, v6 row_shr:1 row_mask:0xf bank_mask:0xf
	v_fmac_f32_e32 v7, 0x3d800000, v5
	v_mov_b32_e32 v6, v211
	v_cvt_pk_bf16_f32 v112, v64, v65
	v_mov_b32_dpp v63, v7 row_shr:2 row_mask:0xf bank_mask:0xf
	v_pk_add_f32 v[6:7], v[6:7], v[62:63]
	s_add_u32 s44, s44, s56
	s_addc_u32 s45, s45, s57
	v_mov_b32_dpp v95, v7 row_shr:4 row_mask:0xf bank_mask:0xf
	v_pk_add_f32 v[16:17], v[6:7], v[94:95]
	v_mfma_f32_16x16x32_bf16 v[106:109], v[106:109], v[110:113], 0
	v_add_f32_e32 v5, v16, v129
	v_mul_f32_e32 v7, 0x3fb8aa3b, v5
	v_exp_f32_e32 v18, v7
	v_mul_f32_e64 v7, |v19|, s7
	v_exp_f32_e32 v7, v7
	v_mul_f32_e32 v5, 0xbfb8aa3b, v5
	v_exp_f32_e32 v22, v5
	v_add_f32_e32 v5, v6, v43
	v_add_f32_e32 v7, 1.0, v7
	v_cmp_gt_f32_e32 vcc, s96, v7
	v_mul_f32_e32 v6, 0x3fb8aa3b, v5
	v_mul_f32_e32 v5, 0xbfb8aa3b, v5
	v_cndmask_b32_e64 v9, 0, 32, vcc
	v_ldexp_f32 v7, v7, v9
	v_log_f32_e32 v7, v7
	v_exp_f32_e32 v58, v5
	v_max_f32_e32 v5, v19, v19
	v_mov_b32_dpp v131, v17 row_shr:8 row_mask:0xf bank_mask:0xf
	v_mul_f32_e32 v9, 0x3f317217, v7
	v_fma_f32 v9, v7, s3, -v9
	v_fmac_f32_e32 v9, 0x3377d1cf, v7
	v_fmac_f32_e32 v9, 0x3f317217, v7
	v_cmp_lt_f32_e64 s[42:43], |v7|, s6
	v_min_f32_e32 v5, 0, v5
	v_pk_add_f32 v[16:17], v[16:17], v[130:131]
	v_cndmask_b32_e64 v7, v7, v9, s[42:43]
	v_cndmask_b32_e32 v9, 0, v237, vcc
	v_sub_f32_e32 v7, v7, v9
	v_sub_f32_e32 v5, v5, v7
	v_add_f32_e32 v20, v16, v17
	v_mul_f32_e32 v7, 0x3d800000, v5
	v_mov_b32_e32 v17, v211
	v_mov_b32_e32 v16, v211
	v_exp_f32_e32 v6, v6
	v_mov_b32_dpp v17, v7 row_shr:1 row_mask:0xf bank_mask:0xf
	v_fmac_f32_e32 v17, 0x3d800000, v5
	v_mov_b32_e32 v129, v211
	v_mov_b32_e32 v43, v211
	v_mov_b32_dpp v57, v17 row_shr:2 row_mask:0xf bank_mask:0xf
	v_pk_add_f32 v[16:17], v[16:17], v[56:57]
	v_lshlrev_b32_e32 v210, 1, v156
	v_add_f32_e32 v9, v16, v39
	v_mov_b32_dpp v91, v17 row_shr:4 row_mask:0xf bank_mask:0xf
	v_pk_add_f32 v[56:57], v[16:17], v[90:91]
	v_mov_b32_e32 v39, v211
	v_add_f32_e32 v5, v56, v121
	v_mul_f32_e32 v7, 0x3fb8aa3b, v5
	v_exp_f32_e32 v19, v7
	v_mul_f32_e32 v7, 0x3fb8aa3b, v9
; __device__ __forceinline__ unsigned cvtpk(float lo, float hi) { f32x2_t v = {lo, hi}; bf16x2_t b = __builtin_convertvector(v, bf16x2_t); return __builtin_bit_cast(unsigned, b); }
; template <bool GLA>
; __device__ __forceinline__ void chunk_tile(const ChunkRaw& raw, const bf16x8 (&wfr)[2], const f32x4 (&bfr)[2], int h, int it, int row, int kq, float lg, float (&carry)[8], float (&bq)[8], float (&qv)[8], float (&kv)[8]) {
;     ...
;         for (int j = 0; j < 8; ++j) {
;             float la = (fminf(z[j], 0.f) - __logf(1.0f + __expf(-fabsf(z[j])))) * (1.0f / 16.0f);
;             la += __int_as_float(__builtin_amdgcn_update_dpp(0, __float_as_int(la), 0x111, 0xf, 0xf, false));
;             la += __int_as_float(__builtin_amdgcn_update_dpp(0, __float_as_int(la), 0x112, 0xf, 0xf, false));
;             la += __int_as_float(__builtin_amdgcn_update_dpp(0, __float_as_int(la), 0x114, 0xf, 0xf, false));
;             la += __int_as_float(__builtin_amdgcn_update_dpp(0, __float_as_int(la), 0x118, 0xf, 0xf, false));
;             bq[j] = la + carry[j];
;             carry[j] += __int_as_float(__builtin_amdgcn_ds_bpermute((16 * kq + 15) * 4, __float_as_int(la)));
;             qv[j] = q[j] * qs; kv[j] = k[j];
; template <bool GLA>
; __device__ __forceinline__ void chunk_pass_c(const ChunkIn& ci, const float* wgl, int unit, unsigned char* wl, int lane, const float* Sb, const float* ng, bf16_t* omix) {
;     ...
;         float a[8], bneg[8], cpos[8], dneg[8];
; #pragma unroll
;         for (int j = 0; j < 8; ++j) { const float eb = __expf(bq[j]), enb = __expf(-bq[j]); a[j] = qv[j] * eb; bneg[j] = kv[j] * enb; cpos[j] = qv[j] * enb; dneg[j] = kv[j] * eb; }
;         qf[it] = __builtin_bit_cast(bf16x8, (u32x4){cvtpk(a[0], a[1]), cvtpk(a[2], a[3]), cvtpk(a[4], a[5]), cvtpk(a[6], a[7])});
;         kf[it] = __builtin_bit_cast(bf16x8, (u32x4){cvtpk(bneg[0], bneg[1]), cvtpk(bneg[2], bneg[3]), cvtpk(bneg[4], bneg[5]), cvtpk(bneg[6], bneg[7])});
;         qb[it] = __builtin_bit_cast(bf16x8, (u32x4){cvtpk(cpos[0], cpos[1]), cvtpk(cpos[2], cpos[3]), cvtpk(cpos[4], cpos[5]), cvtpk(cpos[6], cpos[7])});
;         kb[it] = __builtin_bit_cast(bf16x8, (u32x4){cvtpk(dneg[0], dneg[1]), cvtpk(dneg[2], dneg[3]), cvtpk(dneg[4], dneg[5]), cvtpk(dneg[6], dneg[7])});
	v_exp_f32_e32 v7, v7
	v_mov_b32_dpp v129, v57 row_shr:8 row_mask:0xf bank_mask:0xf
	v_mul_f32_e32 v9, 0xbfb8aa3b, v9
	v_exp_f32_e32 v59, v9
	v_pk_mul_f32 v[16:17], v[6:7], v[78:79]
	v_pk_mul_f32 v[6:7], v[72:73], v[6:7]
	v_cvt_pk_bf16_f32 v99, v16, v17
	v_cvt_pk_bf16_f32 v89, v6, v7
	v_pk_add_f32 v[6:7], v[56:57], v[128:129]
	v_pk_mul_f32 v[16:17], v[58:59], v[78:79]
	v_add_f32_e32 v21, v6, v7
	v_mul_f32_e64 v7, |v10|, s7
	v_exp_f32_e32 v7, v7
	v_max_f32_e32 v6, v10, v10
	v_min_f32_e32 v6, 0, v6
	v_mul_f32_e32 v5, 0xbfb8aa3b, v5
	v_add_f32_e32 v7, 1.0, v7
	v_cmp_gt_f32_e32 vcc, s96, v7
	v_cvt_pk_bf16_f32 v9, v16, v17
	v_pk_mul_f32 v[16:17], v[72:73], v[58:59]
	v_cndmask_b32_e64 v10, 0, 32, vcc
	v_ldexp_f32 v7, v7, v10
	v_log_f32_e32 v7, v7
	v_exp_f32_e32 v23, v5
	v_cvt_pk_bf16_f32 v93, v16, v17
	v_pk_mul_f32 v[60:61], v[18:19], v[86:87]
	v_mul_f32_e32 v10, 0x3f317217, v7
	v_fma_f32 v10, v7, s3, -v10
	v_fmac_f32_e32 v10, 0x3377d1cf, v7
	v_fmac_f32_e32 v10, 0x3f317217, v7
	v_cmp_lt_f32_e64 s[42:43], |v7|, s6
	v_pk_mul_f32 v[18:19], v[82:83], v[18:19]
	v_cvt_pk_bf16_f32 v85, v60, v61
	v_cndmask_b32_e64 v7, v7, v10, s[42:43]
	v_cndmask_b32_e32 v10, 0, v237, vcc
	v_sub_f32_e32 v7, v7, v10
	v_sub_f32_e32 v6, v6, v7
	v_mul_f32_e32 v10, 0x3d800000, v6
	v_mov_b32_e32 v7, v211
	v_cvt_pk_bf16_f32 v77, v18, v19
	v_pk_mul_f32 v[60:61], v[22:23], v[86:87]
	v_mov_b32_dpp v7, v10 row_shr:1 row_mask:0xf bank_mask:0xf
	v_fmac_f32_e32 v7, 0x3d800000, v6
	v_mov_b32_e32 v6, v211
	v_pk_mul_f32 v[22:23], v[82:83], v[22:23]
	v_mov_b32_dpp v55, v7 row_shr:2 row_mask:0xf bank_mask:0xf
	v_pk_add_f32 v[6:7], v[6:7], v[54:55]
	v_cvt_pk_bf16_f32 v81, v22, v23
	v_mov_b32_e32 v121, v211
	v_mov_b32_dpp v39, v7 row_shr:4 row_mask:0xf bank_mask:0xf
	v_pk_add_f32 v[16:17], v[6:7], v[38:39]
	v_add_f32_e32 v6, v6, v37
	v_add_f32_e32 v7, v16, v101
	v_mul_f32_e32 v10, 0x3fb8aa3b, v7
	v_mul_f32_e32 v7, 0xbfb8aa3b, v7
	v_mov_b32_e32 v101, v211
	v_exp_f32_e32 v18, v7
	v_mul_f32_e32 v7, 0x3fb8aa3b, v6
	v_mul_f32_e32 v6, 0xbfb8aa3b, v6
	v_mov_b32_dpp v101, v17 row_shr:8 row_mask:0xf bank_mask:0xf
	v_exp_f32_e32 v38, v7
	v_exp_f32_e32 v54, v6
	v_pk_add_f32 v[6:7], v[16:17], v[100:101]
	v_mov_b32_e32 v37, v211
	v_add_f32_e32 v22, v6, v7
	v_mul_f32_e64 v7, |v11|, s7
	v_exp_f32_e32 v7, v7
	v_max_f32_e32 v6, v11, v11
	v_min_f32_e32 v6, 0, v6
	v_exp_f32_e32 v10, v10
	v_add_f32_e32 v7, 1.0, v7
	v_cmp_gt_f32_e32 vcc, s96, v7
	v_cvt_pk_bf16_f32 v5, v60, v61
	s_nop 0
	v_cndmask_b32_e64 v11, 0, 32, vcc
	v_ldexp_f32 v7, v7, v11
	v_log_f32_e32 v7, v7
	s_nop 0
	v_mul_f32_e32 v11, 0x3f317217, v7
	v_fma_f32 v11, v7, s3, -v11
	v_fmac_f32_e32 v11, 0x3377d1cf, v7
	v_fmac_f32_e32 v11, 0x3f317217, v7
	v_cmp_lt_f32_e64 s[42:43], |v7|, s6
	s_nop 1
	v_cndmask_b32_e64 v7, v7, v11, s[42:43]
	v_cndmask_b32_e32 v11, 0, v237, vcc
	v_sub_f32_e32 v7, v7, v11
	v_sub_f32_e32 v6, v6, v7
	v_mul_f32_e32 v11, 0x3d800000, v6
	v_mov_b32_e32 v7, v211
	s_nop 1
	v_mov_b32_dpp v7, v11 row_shr:1 row_mask:0xf bank_mask:0xf
	v_fmac_f32_e32 v7, 0x3d800000, v6
	v_mov_b32_e32 v6, v211
	s_nop 0
	v_mov_b32_dpp v53, v7 row_shr:2 row_mask:0xf bank_mask:0xf
	v_pk_add_f32 v[16:17], v[6:7], v[52:53]
	s_nop 1
	v_mov_b32_dpp v37, v17 row_shr:4 row_mask:0xf bank_mask:0xf
	v_pk_add_f32 v[36:37], v[16:17], v[36:37]
	s_nop 0
	v_add_f32_e32 v6, v36, v35
	v_mul_f32_e32 v7, 0x3fb8aa3b, v6
	v_exp_f32_e32 v11, v7
	v_mul_f32_e32 v6, 0xbfb8aa3b, v6
	v_exp_f32_e32 v19, v6
	v_mov_b32_dpp v121, v37 row_shr:8 row_mask:0xf bank_mask:0xf
	v_pk_mul_f32 v[6:7], v[10:11], v[122:123]
	v_pk_mul_f32 v[10:11], v[126:127], v[10:11]
	v_cvt_pk_bf16_f32 v86, v6, v7
	v_pk_mul_f32 v[6:7], v[18:19], v[122:123]
	v_cvt_pk_bf16_f32 v78, v10, v11
	v_cvt_pk_bf16_f32 v6, v6, v7
	v_add_f32_e32 v7, v16, v41
	v_mul_f32_e32 v10, 0x3fb8aa3b, v7
	v_exp_f32_e32 v39, v10
	v_mul_f32_e32 v7, 0xbfb8aa3b, v7
	v_exp_f32_e32 v55, v7
	v_max_f32_e32 v7, v12, v12
	v_pk_mul_f32 v[10:11], v[38:39], v[124:125]
	v_min_f32_e32 v7, 0, v7
	v_cvt_pk_bf16_f32 v100, v10, v11
	v_pk_mul_f32 v[10:11], v[54:55], v[124:125]
	v_pk_mul_f32 v[16:17], v[70:71], v[54:55]
	v_cvt_pk_bf16_f32 v10, v10, v11
	v_mul_f32_e64 v11, |v12|, s7
	v_exp_f32_e32 v11, v11
	v_cvt_pk_bf16_f32 v94, v16, v17
	v_pk_mul_f32 v[16:17], v[70:71], v[38:39]
	v_mov_b32_e32 v35, v211
	v_add_f32_e32 v11, 1.0, v11
	v_cmp_gt_f32_e32 vcc, s96, v11
	v_cvt_pk_bf16_f32 v90, v16, v17
	v_pk_add_f32 v[16:17], v[36:37], v[120:121]
	v_cndmask_b32_e64 v12, 0, 32, vcc
	v_ldexp_f32 v11, v11, v12
	v_log_f32_e32 v11, v11
	v_add_f32_e32 v23, v16, v17
	v_mov_b32_e32 v17, v211
	v_mov_b32_e32 v16, v211
	v_mul_f32_e32 v12, 0x3f317217, v11
	v_fma_f32 v12, v11, s3, -v12
	v_fmac_f32_e32 v12, 0x3377d1cf, v11
	v_fmac_f32_e32 v12, 0x3f317217, v11
	v_cmp_lt_f32_e64 s[42:43], |v11|, s6
	v_pk_mul_f32 v[18:19], v[126:127], v[18:19]
	v_mov_b32_e32 v41, v211
	v_cndmask_b32_e64 v11, v11, v12, s[42:43]
	v_cndmask_b32_e32 v12, 0, v237, vcc
	v_sub_f32_e32 v11, v11, v12
	v_sub_f32_e32 v7, v7, v11
	v_mul_f32_e32 v11, 0x3d800000, v7
	v_cvt_pk_bf16_f32 v82, v18, v19
	s_nop 0
	v_mov_b32_dpp v17, v11 row_shr:1 row_mask:0xf bank_mask:0xf
	v_fmac_f32_e32 v17, 0x3d800000, v7
	s_nop 1
	v_mov_b32_dpp v43, v17 row_shr:2 row_mask:0xf bank_mask:0xf
	v_pk_add_f32 v[16:17], v[16:17], v[42:43]
	s_nop 1
	v_mov_b32_dpp v35, v17 row_shr:4 row_mask:0xf bank_mask:0xf
	v_pk_add_f32 v[18:19], v[16:17], v[34:35]
	s_nop 0
	v_add_f32_e32 v7, v18, v29
	v_mul_f32_e32 v11, 0x3fb8aa3b, v7
	v_mul_f32_e32 v7, 0xbfb8aa3b, v7
	v_exp_f32_e32 v34, v7
	v_add_f32_e32 v7, v16, v33
	v_exp_f32_e32 v12, v11
	v_mul_f32_e32 v11, 0x3fb8aa3b, v7
	v_exp_f32_e32 v16, v11
	v_mul_f32_e64 v11, |v13|, s7
	v_exp_f32_e32 v11, v11
; __device__ __forceinline__ unsigned cvtpk(float lo, float hi) { f32x2_t v = {lo, hi}; bf16x2_t b = __builtin_convertvector(v, bf16x2_t); return __builtin_bit_cast(unsigned, b); }
; template <bool GLA>
; __device__ __forceinline__ void chunk_pass_c(const ChunkIn& ci, const float* wgl, int unit, unsigned char* wl, int lane, const float* Sb, const float* ng, bf16_t* omix) {
;     ...
;         float a[8], bneg[8], cpos[8], dneg[8];
; #pragma unroll
;         for (int j = 0; j < 8; ++j) { const float eb = __expf(bq[j]), enb = __expf(-bq[j]); a[j] = qv[j] * eb; bneg[j] = kv[j] * enb; cpos[j] = qv[j] * enb; dneg[j] = kv[j] * eb; }
;         qf[it] = __builtin_bit_cast(bf16x8, (u32x4){cvtpk(a[0], a[1]), cvtpk(a[2], a[3]), cvtpk(a[4], a[5]), cvtpk(a[6], a[7])});
;         kf[it] = __builtin_bit_cast(bf16x8, (u32x4){cvtpk(bneg[0], bneg[1]), cvtpk(bneg[2], bneg[3]), cvtpk(bneg[4], bneg[5]), cvtpk(bneg[6], bneg[7])});
;         qb[it] = __builtin_bit_cast(bf16x8, (u32x4){cvtpk(cpos[0], cpos[1]), cvtpk(cpos[2], cpos[3]), cvtpk(cpos[4], cpos[5]), cvtpk(cpos[6], cpos[7])});
;         kb[it] = __builtin_bit_cast(bf16x8, (u32x4){cvtpk(dneg[0], dneg[1]), cvtpk(dneg[2], dneg[3]), cvtpk(dneg[4], dneg[5]), cvtpk(dneg[6], dneg[7])});
;         asm volatile("" ::: "memory");
;     }
;     __builtin_amdgcn_s_waitcnt(0); asm volatile("" ::: "memory");
;     bf16x8 vfr[4][2], sfr[4];
; #pragma unroll
;     for (int et = 0; et < 4; ++et) {
; #pragma unroll
;         for (int p = 0; p < 2; ++p) {
;             const u32x2 lo = *(const u32x2*)(wl + (16 * et + row) * GP + (32 * p + 4 * kq) * 2), hh = *(const u32x2*)(wl + (16 * et + row) * GP + (32 * p + 16 + 4 * kq) * 2);
;             vfr[et][p] = __builtin_bit_cast(bf16x8, (u32x4){lo.x, lo.y, hh.x, hh.y});
;         }
;         sfr[et] = *(const bf16x8*)(sst + (16 * et + row) * 64 + kq * 16);
;     }
	v_mul_f32_e32 v7, 0xbfb8aa3b, v7
	v_exp_f32_e32 v36, v7
	v_max_f32_e32 v7, v13, v13
	v_add_f32_e32 v11, 1.0, v11
	v_cmp_gt_f32_e32 vcc, s96, v11
	v_mov_b32_e32 v29, v211
	v_min_f32_e32 v7, 0, v7
	v_cndmask_b32_e64 v13, 0, 32, vcc
	v_ldexp_f32 v11, v11, v13
	v_log_f32_e32 v11, v11
	v_mov_b32_dpp v29, v19 row_shr:8 row_mask:0xf bank_mask:0xf
	v_pk_add_f32 v[18:19], v[18:19], v[28:29]
	v_mov_b32_e32 v33, v211
	v_mul_f32_e32 v13, 0x3f317217, v11
	v_fma_f32 v13, v11, s3, -v13
	v_fmac_f32_e32 v13, 0x3377d1cf, v11
	v_fmac_f32_e32 v13, 0x3f317217, v11
	v_cmp_lt_f32_e64 s[42:43], |v11|, s6
	v_add_f32_e32 v38, v18, v19
	v_mov_b32_e32 v19, v211
	v_cndmask_b32_e64 v11, v11, v13, s[42:43]
	v_cndmask_b32_e32 v13, 0, v237, vcc
	v_sub_f32_e32 v11, v11, v13
	v_sub_f32_e32 v7, v7, v11
	v_mul_f32_e32 v11, 0x3d800000, v7
	v_mov_b32_e32 v18, v211
	v_readlane_b32 s3, v254, 60
	v_mov_b32_dpp v19, v11 row_shr:1 row_mask:0xf bank_mask:0xf
	v_fmac_f32_e32 v19, 0x3d800000, v7
	v_cmp_gt_u32_e32 vcc, v97, v156
	v_cmp_lt_u32_e64 s[42:43], v97, v156
	v_mov_b32_dpp v41, v19 row_shr:2 row_mask:0xf bank_mask:0xf
	v_pk_add_f32 v[18:19], v[18:19], v[40:41]
	v_lshlrev_b32_e32 v40, 16, v47
	v_and_b32_e32 v41, 0xffff0000, v47
	v_mov_b32_dpp v33, v19 row_shr:4 row_mask:0xf bank_mask:0xf
	v_pk_add_f32 v[28:29], v[18:19], v[32:33]
	v_pk_mul_f32 v[40:41], v[40:41], s[8:9] op_sel_hi:[1,0]
	v_add_f32_e32 v7, v28, v25
	v_mul_f32_e32 v11, 0x3fb8aa3b, v7
	v_exp_f32_e32 v13, v11
	v_add_f32_e32 v11, v18, v143
	v_mov_b32_e32 v25, v211
	v_mul_f32_e32 v7, 0xbfb8aa3b, v7
	v_pk_mul_f32 v[32:33], v[12:13], v[116:117]
	v_pk_mul_f32 v[12:13], v[118:119], v[12:13]
	v_mov_b32_dpp v25, v29 row_shr:8 row_mask:0xf bank_mask:0xf
	v_cvt_pk_bf16_f32 v79, v12, v13
	v_mul_f32_e32 v12, 0x3fb8aa3b, v11
	v_exp_f32_e32 v17, v12
	v_mul_f32_e32 v11, 0xbfb8aa3b, v11
	v_exp_f32_e32 v37, v11
	v_exp_f32_e32 v35, v7
	v_pk_mul_f32 v[12:13], v[16:17], v[26:27]
	v_cvt_pk_bf16_f32 v87, v32, v33
	v_cvt_pk_bf16_f32 v101, v12, v13
	v_pk_mul_f32 v[12:13], v[36:37], v[26:27]
	v_pk_mul_f32 v[32:33], v[34:35], v[116:117]
	v_cvt_pk_bf16_f32 v11, v12, v13
	v_pk_mul_f32 v[12:13], v[30:31], v[36:37]
	v_cvt_pk_bf16_f32 v7, v32, v33
	v_cvt_pk_bf16_f32 v95, v12, v13
	v_pk_mul_f32 v[12:13], v[30:31], v[16:17]
	v_lshlrev_b32_e32 v30, 16, v49
	v_cvt_pk_bf16_f32 v91, v12, v13
	v_pk_add_f32 v[12:13], v[28:29], v[24:25]
	v_lshlrev_b32_e32 v24, 16, v48
	v_add_f32_e32 v39, v12, v13
	v_mul_f32_e32 v12, 0x3fb8aa3b, v14
	v_exp_f32_e32 v16, v12
	v_mul_f32_e32 v12, 0xbfb8aa3b, v14
	v_exp_f32_e32 v14, v12
	v_mul_f32_e32 v12, 0x3fb8aa3b, v15
	v_exp_f32_e32 v17, v12
	v_mul_f32_e32 v12, 0xbfb8aa3b, v15
	v_exp_f32_e32 v15, v12
	v_lshlrev_b32_e32 v12, 16, v50
	v_and_b32_e32 v13, 0xffff0000, v50
	v_pk_mul_f32 v[18:19], v[12:13], s[8:9] op_sel_hi:[1,0]
	v_and_b32_e32 v25, 0xffff0000, v48
	v_pk_mul_f32 v[12:13], v[18:19], v[16:17]
	v_pk_mul_f32 v[18:19], v[18:19], v[14:15]
	v_pk_mul_f32 v[26:27], v[14:15], v[24:25]
	v_mul_f32_e32 v15, 0xbfb8aa3b, v20
	v_mul_f32_e32 v14, 0x3fb8aa3b, v20
	v_exp_f32_e32 v20, v15
	v_mul_f32_e32 v15, 0x3fb8aa3b, v21
	v_mul_f32_e32 v21, 0xbfb8aa3b, v21
	v_exp_f32_e32 v14, v14
	v_exp_f32_e32 v15, v15
	v_exp_f32_e32 v21, v21
	v_pk_mul_f32 v[16:17], v[16:17], v[24:25]
	v_lshlrev_b32_e32 v24, 16, v51
	v_and_b32_e32 v25, 0xffff0000, v51
	v_pk_mul_f32 v[24:25], v[24:25], s[8:9] op_sel_hi:[1,0]
	v_and_b32_e32 v31, 0xffff0000, v49
	v_pk_mul_f32 v[28:29], v[24:25], v[14:15]
	v_pk_mul_f32 v[24:25], v[24:25], v[20:21]
	v_pk_mul_f32 v[20:21], v[20:21], v[30:31]
	v_pk_mul_f32 v[30:31], v[14:15], v[30:31]
	v_mul_f32_e32 v15, 0xbfb8aa3b, v22
	v_mul_f32_e32 v14, 0x3fb8aa3b, v22
	v_exp_f32_e32 v22, v15
	v_mul_f32_e32 v15, 0x3fb8aa3b, v23
	v_mul_f32_e32 v23, 0xbfb8aa3b, v23
	v_exp_f32_e32 v14, v14
	v_exp_f32_e32 v15, v15
	v_exp_f32_e32 v23, v23
	v_pk_mul_f32 v[32:33], v[118:119], v[34:35]
	v_lshlrev_b32_e32 v36, 16, v44
	v_cvt_pk_bf16_f32 v83, v32, v33
	v_lshlrev_b32_e32 v32, 16, v46
	v_and_b32_e32 v33, 0xffff0000, v46
	v_pk_mul_f32 v[32:33], v[32:33], s[8:9] op_sel_hi:[1,0]
	v_and_b32_e32 v37, 0xffff0000, v44
	v_pk_mul_f32 v[34:35], v[32:33], v[14:15]
	v_pk_mul_f32 v[32:33], v[32:33], v[22:23]
	v_pk_mul_f32 v[22:23], v[22:23], v[36:37]
	v_pk_mul_f32 v[36:37], v[14:15], v[36:37]
	v_mul_f32_e32 v15, 0xbfb8aa3b, v38
	v_mul_f32_e32 v14, 0x3fb8aa3b, v38
	v_exp_f32_e32 v38, v15
	v_mul_f32_e32 v15, 0x3fb8aa3b, v39
	v_mul_f32_e32 v39, 0xbfb8aa3b, v39
	v_exp_f32_e32 v14, v14
	v_exp_f32_e32 v15, v15
	v_exp_f32_e32 v39, v39
	v_cvt_pk_bf16_f32 v72, v16, v17
	v_mul_u32_u24_e32 v17, 0x90, v156
	v_lshlrev_b32_e32 v44, 16, v45
	v_and_b32_e32 v45, 0xffff0000, v45
	v_lshlrev_b32_e32 v16, 6, v156
	v_add3_u32 v17, s3, v17, v114
	v_pk_mul_f32 v[42:43], v[40:41], v[14:15]
	v_pk_mul_f32 v[40:41], v[40:41], v[38:39]
	v_pk_mul_f32 v[38:39], v[38:39], v[44:45]
	v_pk_mul_f32 v[44:45], v[14:15], v[44:45]
	v_cvt_pk_bf16_f32 v52, v18, v19
	ds_read2_b64 v[64:67], v17 offset1:4
	ds_read2_b64 v[60:63], v17 offset0:8 offset1:12
	v_add3_u32 v16, s3, v142, v16
	v_add_u32_e32 v18, 0x800, v17
	v_add_u32_e32 v17, 0x1000, v17
	v_or_b32_e32 v142, 48, v147
	v_cvt_pk_bf16_f32 v12, v12, v13
	v_cvt_pk_bf16_f32 v13, v28, v29
	v_cvt_pk_bf16_f32 v14, v34, v35
	v_cvt_pk_bf16_f32 v15, v42, v43
	v_cvt_pk_bf16_f32 v59, v38, v39
	v_cvt_pk_bf16_f32 v54, v32, v33
	v_cvt_pk_bf16_f32 v55, v40, v41
	v_cvt_pk_bf16_f32 v73, v30, v31
	v_cvt_pk_bf16_f32 v74, v36, v37
	v_cvt_pk_bf16_f32 v75, v44, v45
	ds_read_b128 v[68:71], v16 offset:9216
	ds_read2_b64 v[48:51], v18 offset0:32 offset1:36
	ds_read2_b64 v[44:47], v18 offset0:40 offset1:44
	ds_read_b128 v[40:43], v16 offset:10240
; template <bool GLA>
; __device__ __forceinline__ void chunk_pass_c(const ChunkIn& ci, const float* wgl, int unit, unsigned char* wl, int lane, const float* Sb, const float* ng, bf16_t* omix) {
;     ...
;     for (int it = 0; it < 4; ++it) {
;         f32x4 st[4];
; #pragma unroll
;         for (int jt = 0; jt < 4; ++jt) {
;             const f32x4 z = {0.f, 0.f, 0.f, 0.f};
;             if (jt < it) st[jt] = __builtin_amdgcn_mfma_f32_16x16x32_bf16(kf[jt], qf[it], z, 0, 0, 0);
;             else if (jt > it) st[jt] = __builtin_amdgcn_mfma_f32_16x16x32_bf16(kb[jt], qb[it], z, 0, 0, 0);
;             else {
;                 const f32x4 lo = __builtin_amdgcn_mfma_f32_16x16x32_bf16(kf[jt], qf[it], z, 0, 0, 0), up = __builtin_amdgcn_mfma_f32_16x16x32_bf16(kb[jt], qb[it], z, 0, 0, 0);
; #pragma unroll
;                 for (int r = 0; r < 4; ++r) st[jt][r] = (4 * kq + r <= row) ? lo[r] : up[r];
;             }
;         }
;         bf16x8 af[2];
; #pragma unroll
;         for (int p = 0; p < 2; ++p)
;             af[p] = __builtin_bit_cast(bf16x8, (u32x4){cvtpk(st[2 * p][0], st[2 * p][1]), cvtpk(st[2 * p][2], st[2 * p][3]), cvtpk(st[2 * p + 1][0], st[2 * p + 1][1]), cvtpk(st[2 * p + 1][2], st[2 * p + 1][3])});
;         f32x4 o[4]; float ss[4] = {0.f, 0.f, 0.f, 0.f};
; #pragma unroll
;         for (int et = 0; et < 4; ++et) {
;             f32x4 acc = {0.f, 0.f, 0.f, 0.f};
;             acc = __builtin_amdgcn_mfma_f32_16x16x32_bf16(af[0], vfr[et][0], acc, 0, 0, 0);
;             acc = __builtin_amdgcn_mfma_f32_16x16x32_bf16(af[1], vfr[et][1], acc, 0, 0, 0);
;             acc = __builtin_amdgcn_mfma_f32_16x16x32_bf16(qf[it], sfr[et], acc, 0, 0, 0);
;             o[et] = acc;
; #pragma unroll
;             for (int r = 0; r < 4; ++r) ss[r] += acc[r] * acc[r];
;         }
; #pragma unroll
;         for (int r = 0; r < 4; ++r) {
;             ss[r] += swz_xor<1>(ss[r]); ss[r] += swz_xor<2>(ss[r]); ss[r] += swz_xor<4>(ss[r]); ss[r] += swz_xor<8>(ss[r]);
;             const float rs = rsqrtf(ss[r] * (1.0f / 64.0f) + EPS);
;             const int t = t0 + 16 * it + 4 * kq + r;
; #pragma unroll
;             for (int et = 0; et < 4; ++et) {
;                 const int e = 16 * et + row;
;                 const float gt = __uint_as_float((unsigned)ci.proj[(size_t)t * DINP + gcol + e] << 16);
;                 const float val = o[et][r] * rs * gn[et] * pg8::silu_f(gt);
	ds_read2_b64 v[36:39], v17 offset0:64 offset1:68
	ds_read2_b64 v[32:35], v17 offset0:72 offset1:76
	ds_read_b128 v[28:31], v16 offset:11264
	v_mul_u32_u24_e32 v17, 0x90, v142
	v_add3_u32 v17, s3, v17, v114
	v_lshlrev_b32_e32 v114, 2, v142
	v_cvt_pk_bf16_f32 v56, v26, v27
	v_cvt_pk_bf16_f32 v57, v20, v21
	v_cvt_pk_bf16_f32 v58, v22, v23
	v_cvt_pk_bf16_f32 v53, v24, v25
	ds_read2_b64 v[24:27], v17 offset1:4
	ds_read2_b64 v[20:23], v17 offset0:8 offset1:12
	ds_read_b128 v[16:19], v16 offset:12288
	global_load_dword v149, v115, s[44:45]
	global_load_dword v148, v115, s[44:45] offset:64
	global_load_dword v147, v115, s[44:45] offset:128
	global_load_dword v146, v114, s[44:45]
	v_mfma_f32_16x16x32_bf16 v[114:117], v[0:3], v[102:105], 0
	s_mov_b32 s6, 0x358637bd
	v_mfma_f32_16x16x32_bf16 v[56:59], v[56:59], v[12:15], 0
	v_mfma_f32_16x16x32_bf16 v[52:55], v[72:75], v[52:55], 0
	s_nop 4
	v_cndmask_b32_e32 v118, v114, v106, vcc
	v_or_b32_e32 v106, 2, v97
	v_cmp_gt_u32_e64 s[44:45], v106, v156
	v_or_b32_e32 v106, 3, v97
	v_cmp_gt_u32_e64 s[46:47], v106, v156
	v_cndmask_b32_e64 v119, v107, v115, s[42:43]
	v_cndmask_b32_e64 v120, v116, v108, s[44:45]
	v_cndmask_b32_e64 v121, v117, v109, s[46:47]
	v_mfma_f32_16x16x32_bf16 v[106:109], v[98:101], v[110:113], 0
	v_cvt_pk_bf16_f32 v122, v118, v119
	v_cvt_pk_bf16_f32 v123, v120, v121
	v_cndmask_b32_e64 v59, v59, v55, s[46:47]
	v_mfma_f32_16x16x32_bf16 v[114:117], v[84:87], v[110:113], 0
	v_cndmask_b32_e32 v56, v56, v52, vcc
	s_nop 2
	v_cvt_pk_bf16_f32 v124, v106, v107
	v_cvt_pk_bf16_f32 v125, v108, v109
	v_mfma_f32_16x16x32_bf16 v[110:113], v[72:75], v[110:113], 0
	v_cndmask_b32_e64 v57, v53, v57, s[42:43]
	v_cvt_pk_bf16_f32 v130, v114, v115
	v_cvt_pk_bf16_f32 v131, v116, v117
	s_waitcnt lgkmcnt(11)
	v_mfma_f32_16x16x32_bf16 v[106:109], v[122:125], v[64:67], 0
	v_cndmask_b32_e64 v58, v58, v54, s[44:45]
	s_nop 1
	v_cvt_pk_bf16_f32 v132, v110, v111
	v_cvt_pk_bf16_f32 v133, v112, v113
	v_mfma_f32_16x16x32_bf16 v[98:101], v[98:101], v[92:95], 0
	s_waitcnt lgkmcnt(10)
	v_mfma_f32_16x16x32_bf16 v[106:109], v[130:133], v[60:63], v[106:109]
	s_waitcnt lgkmcnt(9)
	v_mfma_f32_16x16x32_bf16 v[114:117], v[102:105], v[68:71], v[106:109]
	s_waitcnt lgkmcnt(8)
	v_mfma_f32_16x16x32_bf16 v[106:109], v[122:125], v[48:51], 0
	s_waitcnt lgkmcnt(7)
	v_mfma_f32_16x16x32_bf16 v[106:109], v[130:133], v[44:47], v[106:109]
	s_nop 3
	v_mov_b32_e32 v110, v114
	s_waitcnt lgkmcnt(6)
	v_mfma_f32_16x16x32_bf16 v[106:109], v[102:105], v[40:43], v[106:109]
	s_nop 7
	v_mov_b32_e32 v111, v106
	v_pk_mul_f32 v[120:121], v[110:111], v[110:111]
	v_mov_b32_e32 v110, v115
	v_mov_b32_e32 v111, v107
	v_pk_mul_f32 v[134:135], v[110:111], v[110:111]
	v_mov_b32_e32 v110, v116
	v_mov_b32_e32 v111, v108
	v_pk_mul_f32 v[126:127], v[110:111], v[110:111]
	v_mov_b32_e32 v110, v117
	v_mov_b32_e32 v111, v109
	v_pk_mul_f32 v[128:129], v[110:111], v[110:111]
	s_waitcnt lgkmcnt(5)
	v_mfma_f32_16x16x32_bf16 v[110:113], v[122:125], v[36:39], 0
	s_waitcnt lgkmcnt(2)
	v_mfma_f32_16x16x32_bf16 v[122:125], v[122:125], v[24:27], 0
	v_mfma_f32_16x16x32_bf16 v[110:113], v[130:133], v[32:35], v[110:113]
	s_waitcnt lgkmcnt(1)
	v_mfma_f32_16x16x32_bf16 v[122:125], v[130:133], v[20:23], v[122:125]
	v_mfma_f32_16x16x32_bf16 v[110:113], v[102:105], v[28:31], v[110:113]
	s_waitcnt lgkmcnt(0)
	v_mfma_f32_16x16x32_bf16 v[102:105], v[102:105], v[16:19], v[122:125]
	s_nop 4
	v_or_b32_e32 v122, s5, v97
	v_mov_b32_e32 v118, v110
	s_nop 0
	v_mov_b32_e32 v119, v102
	v_pk_mul_f32 v[136:137], v[118:119], v[118:119]
	v_mov_b32_e32 v118, v111
	v_mov_b32_e32 v119, v103
	v_pk_mul_f32 v[138:139], v[118:119], v[118:119]
	v_mov_b32_e32 v118, v112
	v_mov_b32_e32 v119, v104
	v_pk_mul_f32 v[124:125], v[118:119], v[118:119]
	v_mov_b32_e32 v118, v113
	v_mov_b32_e32 v119, v105
	v_ashrrev_i32_e32 v123, 31, v122
	v_pk_mul_f32 v[130:131], v[118:119], v[118:119]
	v_lshlrev_b64 v[118:119], 12, v[122:123]
	v_lshl_add_u64 v[132:133], s[58:59], 0, v[118:119]
	v_lshlrev_b64 v[118:119], 11, v[122:123]
	v_lshl_add_u64 v[144:145], v[132:133], 0, v[210:211]
	v_lshl_add_u64 v[150:151], s[60:61], 0, v[118:119]
	global_load_ushort v118, v[144:145], off offset:1888
	v_lshl_add_u64 v[140:141], v[150:151], 0, v[210:211]
	s_waitcnt vmcnt(0)
	v_lshlrev_b32_e32 v118, 16, v118
	v_mul_f32_e32 v119, 0xbfb8aa3b, v118
	v_exp_f32_e32 v119, v119
	s_nop 0
	v_add_f32_e32 v119, 1.0, v119
	v_rcp_f32_e32 v119, v119
	s_nop 0
	v_mul_f32_e32 v123, v119, v118
	v_lshlrev_b32_e32 v118, 1, v142
	v_mov_b32_e32 v119, v211
	v_lshl_add_u64 v[142:143], v[132:133], 0, v[118:119]
	v_lshl_add_u64 v[132:133], v[150:151], 0, v[118:119]
	v_mov_b32_e32 v150, v134
	v_mov_b32_e32 v151, v120
	v_mov_b32_e32 v120, v135
	v_pk_add_f32 v[120:121], v[150:151], v[120:121]
	v_mov_b32_e32 v134, v138
	v_mov_b32_e32 v135, v136
	v_pk_add_f32 v[120:121], v[120:121], v[134:135]
	v_mov_b32_e32 v136, v139
	v_pk_add_f32 v[120:121], v[120:121], v[136:137]
	ds_swizzle_b32 v135, v121 offset:swizzle(SWAP,1)
	ds_swizzle_b32 v134, v120 offset:swizzle(SWAP,1)
	s_waitcnt lgkmcnt(0)
	v_pk_add_f32 v[120:121], v[120:121], v[134:135]
	ds_swizzle_b32 v135, v121 offset:swizzle(SWAP,2)
	ds_swizzle_b32 v134, v120 offset:swizzle(SWAP,2)
	s_waitcnt lgkmcnt(0)
	v_pk_add_f32 v[120:121], v[120:121], v[134:135]
	ds_swizzle_b32 v135, v121 offset:swizzle(SWAP,4)
	ds_swizzle_b32 v134, v120 offset:swizzle(SWAP,4)
	s_waitcnt lgkmcnt(0)
	v_pk_add_f32 v[120:121], v[120:121], v[134:135]
	ds_swizzle_b32 v135, v121 offset:swizzle(SWAP,8)
	ds_swizzle_b32 v134, v120 offset:swizzle(SWAP,8)
	s_waitcnt lgkmcnt(0)
; __device__ __forceinline__ unsigned cvtpk(float lo, float hi) { f32x2_t v = {lo, hi}; bf16x2_t b = __builtin_convertvector(v, bf16x2_t); return __builtin_bit_cast(unsigned, b); }
; template <int X> __device__ __forceinline__ float swz_xor(float v) { return __int_as_float(__builtin_amdgcn_ds_swizzle(__float_as_int(v), (X << 10) | 0x1F)); }
; __device__ __forceinline__ float silu_f(float g) { return g * __builtin_amdgcn_rcpf(1.0f + __expf(-g)); }
; template <bool GLA>
; __device__ __forceinline__ void chunk_pass_c(const ChunkIn& ci, const float* wgl, int unit, unsigned char* wl, int lane, const float* Sb, const float* ng, bf16_t* omix) {
;     ...
; #pragma unroll
;         for (int r = 0; r < 4; ++r) {
;             ss[r] += swz_xor<1>(ss[r]); ss[r] += swz_xor<2>(ss[r]); ss[r] += swz_xor<4>(ss[r]); ss[r] += swz_xor<8>(ss[r]);
;             const float rs = rsqrtf(ss[r] * (1.0f / 64.0f) + EPS);
;             const int t = t0 + 16 * it + 4 * kq + r;
; #pragma unroll
;             for (int et = 0; et < 4; ++et) {
;                 const int e = 16 * et + row;
;                 const float gt = __uint_as_float((unsigned)ci.proj[(size_t)t * DINP + gcol + e] << 16);
;                 const float val = o[et][r] * rs * gn[et] * pg8::silu_f(gt);
;                 omix[(size_t)t * 1024 + ocol + e] = (bf16_t)(cvtpk(val, 0.f) & 0xffffu);
;             }
	v_pk_add_f32 v[134:135], v[120:121], v[134:135]
	v_mov_b64_e32 v[120:121], s[6:7]
	s_mov_b32 s6, 0x3c800000
	v_pk_fma_f32 v[134:135], v[134:135], s[6:7], v[120:121] op_sel_hi:[1,0,0]
	s_nop 0
	v_mul_f32_e32 v136, 0x4b800000, v135
	v_cmp_gt_f32_e64 s[50:51], s96, v135
	v_cmp_gt_f32_e64 s[48:49], s96, v134
	s_nop 0
	v_cndmask_b32_e64 v135, v135, v136, s[50:51]
	v_rsq_f32_e32 v135, v135
	s_nop 0
	v_mul_f32_e32 v136, 0x45800000, v135
	v_cndmask_b32_e64 v135, v135, v136, s[50:51]
	v_mul_f32_e32 v114, v114, v135
	v_mul_f32_e32 v114, v149, v114
	v_mul_f32_e32 v114, v123, v114
	v_cvt_pk_bf16_f32 v114, v114, s0
	global_store_short v[140:141], v114, off offset:1024
	global_load_ushort v114, v[144:145], off offset:1920
	v_mul_f32_e32 v106, v106, v135
	v_mul_f32_e32 v106, v148, v106
	v_mul_f32_e32 v110, v110, v135
	v_mul_f32_e32 v110, v147, v110
	v_mul_f32_e32 v102, v102, v135
	v_mul_f32_e32 v102, v146, v102
	s_waitcnt vmcnt(0)
	v_lshlrev_b32_e32 v114, 16, v114
	v_mul_f32_e32 v123, 0xbfb8aa3b, v114
	v_exp_f32_e32 v123, v123
	s_nop 0
	v_add_f32_e32 v123, 1.0, v123
	v_rcp_f32_e32 v123, v123
	s_nop 0
	v_mul_f32_e32 v114, v123, v114
	v_mul_f32_e32 v106, v114, v106
	v_cvt_pk_bf16_f32 v106, v106, s0
	global_store_short v[140:141], v106, off offset:1056
	global_load_ushort v106, v[144:145], off offset:1952
	s_waitcnt vmcnt(0)
	v_lshlrev_b32_e32 v106, 16, v106
	v_mul_f32_e32 v114, 0xbfb8aa3b, v106
	v_exp_f32_e32 v114, v114
	s_nop 0
	v_add_f32_e32 v114, 1.0, v114
	v_rcp_f32_e32 v114, v114
	s_nop 0
	v_mul_f32_e32 v106, v114, v106
	v_mul_f32_e32 v106, v110, v106
	v_cvt_pk_bf16_f32 v106, v106, s0
	global_store_short v[140:141], v106, off offset:1088
	global_load_ushort v106, v[142:143], off offset:1888
	s_waitcnt vmcnt(0)
	v_lshlrev_b32_e32 v106, 16, v106
	v_mul_f32_e32 v110, 0xbfb8aa3b, v106
	v_exp_f32_e32 v110, v110
	s_nop 0
	v_add_f32_e32 v110, 1.0, v110
	v_rcp_f32_e32 v110, v110
	s_nop 0
	v_mul_f32_e32 v106, v110, v106
	v_mul_f32_e32 v102, v102, v106
	v_cvt_pk_bf16_f32 v102, v102, s0
	global_store_short v[132:133], v102, off offset:1024
	v_mul_f32_e32 v102, 0x4b800000, v134
	v_cndmask_b32_e64 v102, v134, v102, s[48:49]
	v_rsq_f32_e32 v102, v102
	v_or_b32_e32 v132, 1, v122
	v_ashrrev_i32_e32 v133, 31, v132
	v_lshlrev_b64 v[134:135], 12, v[132:133]
	v_lshl_add_u64 v[134:135], s[58:59], 0, v[134:135]
	v_mul_f32_e32 v106, 0x45800000, v102
	v_lshl_add_u64 v[136:137], v[134:135], 0, v[210:211]
	v_cndmask_b32_e64 v102, v102, v106, s[48:49]
	global_load_ushort v106, v[136:137], off offset:1888
	v_mul_f32_e32 v110, v115, v102
	v_lshlrev_b64 v[132:133], 11, v[132:133]
	v_mul_f32_e32 v110, v149, v110
	v_lshl_add_u64 v[132:133], s[60:61], 0, v[132:133]
	v_mul_f32_e32 v107, v107, v102
	v_mul_f32_e32 v107, v148, v107
	s_waitcnt vmcnt(0)
	v_lshlrev_b32_e32 v106, 16, v106
	v_mul_f32_e32 v114, 0xbfb8aa3b, v106
	v_exp_f32_e32 v114, v114
	s_nop 0
	v_add_f32_e32 v114, 1.0, v114
	v_rcp_f32_e32 v114, v114
	s_nop 0
	v_mul_f32_e32 v106, v114, v106
	v_mul_f32_e32 v106, v106, v110
	v_cvt_pk_bf16_f32 v106, v106, s0
	v_lshl_add_u64 v[114:115], v[132:133], 0, v[210:211]
	global_store_short v[114:115], v106, off offset:1024
	global_load_ushort v106, v[136:137], off offset:1920
	s_waitcnt vmcnt(0)
	v_lshlrev_b32_e32 v106, 16, v106
	v_mul_f32_e32 v110, 0xbfb8aa3b, v106
	v_exp_f32_e32 v110, v110
	s_nop 0
	v_add_f32_e32 v110, 1.0, v110
	v_rcp_f32_e32 v110, v110
	s_nop 0
	v_mul_f32_e32 v106, v110, v106
	v_mul_f32_e32 v106, v107, v106
	v_cvt_pk_bf16_f32 v106, v106, s0
	global_store_short v[114:115], v106, off offset:1056
	global_load_ushort v106, v[136:137], off offset:1952
	v_mul_f32_e32 v107, v111, v102
	v_mul_f32_e32 v107, v147, v107
	v_mul_f32_e32 v102, v103, v102
	v_mul_f32_e32 v102, v146, v102
	s_waitcnt vmcnt(0)
	v_lshlrev_b32_e32 v106, 16, v106
	v_mul_f32_e32 v110, 0xbfb8aa3b, v106
	v_exp_f32_e32 v110, v110
	s_nop 0
	v_add_f32_e32 v110, 1.0, v110
	v_rcp_f32_e32 v110, v110
	s_nop 0
	v_mul_f32_e32 v106, v110, v106
	v_mul_f32_e32 v106, v107, v106
	v_cvt_pk_bf16_f32 v106, v106, s0
	global_store_short v[114:115], v106, off offset:1088
	v_lshl_add_u64 v[106:107], v[134:135], 0, v[118:119]
	global_load_ushort v106, v[106:107], off offset:1888
	s_waitcnt vmcnt(0)
	v_lshlrev_b32_e32 v106, 16, v106
	v_mul_f32_e32 v103, 0xbfb8aa3b, v106
	v_exp_f32_e32 v103, v103
	s_nop 0
	v_add_f32_e32 v103, 1.0, v103
	v_rcp_f32_e32 v103, v103
	s_nop 0
	v_mul_f32_e32 v103, v103, v106
	v_mul_f32_e32 v102, v102, v103
	v_cvt_pk_bf16_f32 v106, v102, s0
	v_lshl_add_u64 v[102:103], v[132:133], 0, v[118:119]
	global_store_short v[102:103], v106, off offset:1024
	v_or_b32_e32 v102, 2, v122
	v_ashrrev_i32_e32 v103, 31, v102
	v_lshlrev_b64 v[106:107], 12, v[102:103]
	v_lshl_add_u64 v[106:107], s[58:59], 0, v[106:107]
	v_lshl_add_u64 v[110:111], v[106:107], 0, v[210:211]
	global_load_ushort v114, v[110:111], off offset:1888
	v_mov_b32_e32 v132, v128
	v_mov_b32_e32 v133, v126
	v_mov_b32_e32 v126, v129
	v_pk_add_f32 v[126:127], v[132:133], v[126:127]
	v_mov_b32_e32 v128, v130
	v_mov_b32_e32 v129, v124
	v_pk_add_f32 v[126:127], v[126:127], v[128:129]
	v_mov_b32_e32 v124, v131
	v_pk_add_f32 v[124:125], v[126:127], v[124:125]
	ds_swizzle_b32 v127, v125 offset:swizzle(SWAP,1)
	ds_swizzle_b32 v126, v124 offset:swizzle(SWAP,1)
	v_lshlrev_b64 v[102:103], 11, v[102:103]
	v_lshl_add_u64 v[102:103], s[60:61], 0, v[102:103]
	v_lshl_add_u64 v[106:107], v[106:107], 0, v[118:119]
	s_waitcnt lgkmcnt(0)
	v_pk_add_f32 v[124:125], v[124:125], v[126:127]
	ds_swizzle_b32 v127, v125 offset:swizzle(SWAP,2)
	ds_swizzle_b32 v126, v124 offset:swizzle(SWAP,2)
	s_waitcnt lgkmcnt(0)
; __device__ __forceinline__ unsigned cvtpk(float lo, float hi) { f32x2_t v = {lo, hi}; bf16x2_t b = __builtin_convertvector(v, bf16x2_t); return __builtin_bit_cast(unsigned, b); }
; template <int X> __device__ __forceinline__ float swz_xor(float v) { return __int_as_float(__builtin_amdgcn_ds_swizzle(__float_as_int(v), (X << 10) | 0x1F)); }
; __device__ __forceinline__ float silu_f(float g) { return g * __builtin_amdgcn_rcpf(1.0f + __expf(-g)); }
; template <bool GLA>
; __device__ __forceinline__ void chunk_pass_c(const ChunkIn& ci, const float* wgl, int unit, unsigned char* wl, int lane, const float* Sb, const float* ng, bf16_t* omix) {
;     ...
; #pragma unroll
;         for (int r = 0; r < 4; ++r) {
;             ss[r] += swz_xor<1>(ss[r]); ss[r] += swz_xor<2>(ss[r]); ss[r] += swz_xor<4>(ss[r]); ss[r] += swz_xor<8>(ss[r]);
;             const float rs = rsqrtf(ss[r] * (1.0f / 64.0f) + EPS);
;             const int t = t0 + 16 * it + 4 * kq + r;
; #pragma unroll
;             for (int et = 0; et < 4; ++et) {
;                 const int e = 16 * et + row;
;                 const float gt = __uint_as_float((unsigned)ci.proj[(size_t)t * DINP + gcol + e] << 16);
;                 const float val = o[et][r] * rs * gn[et] * pg8::silu_f(gt);
;                 omix[(size_t)t * 1024 + ocol + e] = (bf16_t)(cvtpk(val, 0.f) & 0xffffu);
;             }
	v_pk_add_f32 v[124:125], v[124:125], v[126:127]
	ds_swizzle_b32 v127, v125 offset:swizzle(SWAP,4)
	ds_swizzle_b32 v126, v124 offset:swizzle(SWAP,4)
	s_waitcnt lgkmcnt(0)
	v_pk_add_f32 v[124:125], v[124:125], v[126:127]
	ds_swizzle_b32 v127, v125 offset:swizzle(SWAP,8)
	ds_swizzle_b32 v126, v124 offset:swizzle(SWAP,8)
	s_waitcnt lgkmcnt(0)
	v_pk_add_f32 v[124:125], v[124:125], v[126:127]
	s_nop 0
	v_pk_fma_f32 v[124:125], v[124:125], s[6:7], v[120:121] op_sel_hi:[1,0,0]
	s_waitcnt vmcnt(0)
	v_lshlrev_b32_e32 v114, 16, v114
	v_mul_f32_e32 v115, 0xbfb8aa3b, v114
	v_exp_f32_e32 v115, v115
	v_mul_f32_e32 v126, 0x4b800000, v125
	v_cmp_gt_f32_e64 s[50:51], s96, v125
	v_cmp_gt_f32_e64 s[48:49], s96, v124
	v_add_f32_e32 v115, 1.0, v115
	v_cndmask_b32_e64 v125, v125, v126, s[50:51]
	v_rsq_f32_e32 v125, v125
	v_rcp_f32_e32 v115, v115
	v_mul_f32_e32 v126, 0x45800000, v125
	v_cndmask_b32_e64 v125, v125, v126, s[50:51]
	v_mul_f32_e32 v116, v116, v125
	v_mul_f32_e32 v123, v115, v114
	v_mul_f32_e32 v116, v149, v116
	v_mul_f32_e32 v116, v123, v116
	v_lshl_add_u64 v[114:115], v[102:103], 0, v[210:211]
	v_cvt_pk_bf16_f32 v116, v116, s0
	global_store_short v[114:115], v116, off offset:1024
	global_load_ushort v116, v[110:111], off offset:1920
	v_mul_f32_e32 v108, v108, v125
	v_mul_f32_e32 v108, v148, v108
	v_mul_f32_e32 v104, v104, v125
	v_mul_f32_e32 v104, v146, v104
	v_lshl_add_u64 v[102:103], v[102:103], 0, v[118:119]
	s_waitcnt vmcnt(0)
	v_lshlrev_b32_e32 v116, 16, v116
	v_mul_f32_e32 v123, 0xbfb8aa3b, v116
	v_exp_f32_e32 v123, v123
	s_nop 0
	v_add_f32_e32 v123, 1.0, v123
	v_rcp_f32_e32 v123, v123
	s_nop 0
	v_mul_f32_e32 v116, v123, v116
	v_mul_f32_e32 v108, v108, v116
	v_cvt_pk_bf16_f32 v108, v108, s0
	global_store_short v[114:115], v108, off offset:1056
	global_load_ushort v108, v[110:111], off offset:1952
	v_mul_f32_e32 v110, v112, v125
	v_mul_f32_e32 v110, v147, v110
	s_waitcnt vmcnt(0)
	v_lshlrev_b32_e32 v108, 16, v108
	v_mul_f32_e32 v111, 0xbfb8aa3b, v108
	v_exp_f32_e32 v111, v111
	s_nop 0
	v_add_f32_e32 v111, 1.0, v111
	v_rcp_f32_e32 v111, v111
	s_nop 0
	v_mul_f32_e32 v108, v111, v108
	v_mul_f32_e32 v108, v110, v108
	v_cvt_pk_bf16_f32 v108, v108, s0
	global_store_short v[114:115], v108, off offset:1088
	global_load_ushort v106, v[106:107], off offset:1888
	s_waitcnt vmcnt(0)
	v_lshlrev_b32_e32 v106, 16, v106
	v_mul_f32_e32 v107, 0xbfb8aa3b, v106
	v_exp_f32_e32 v107, v107
	s_nop 0
	v_add_f32_e32 v107, 1.0, v107
	v_rcp_f32_e32 v107, v107
	s_nop 0
	v_mul_f32_e32 v106, v107, v106
	v_mul_f32_e32 v104, v104, v106
	v_cvt_pk_bf16_f32 v104, v104, s0
	global_store_short v[102:103], v104, off offset:1024
	v_mul_f32_e32 v102, 0x4b800000, v124
	v_cndmask_b32_e64 v102, v124, v102, s[48:49]
	v_rsq_f32_e32 v102, v102
	s_nop 0
	v_mul_f32_e32 v103, 0x45800000, v102
	v_cndmask_b32_e64 v104, v102, v103, s[48:49]
	v_or_b32_e32 v102, 3, v122
	v_ashrrev_i32_e32 v103, 31, v102
	v_lshlrev_b64 v[106:107], 12, v[102:103]
	v_lshl_add_u64 v[106:107], s[58:59], 0, v[106:107]
	v_lshl_add_u64 v[110:111], v[106:107], 0, v[210:211]
	global_load_ushort v108, v[110:111], off offset:1888
	v_mul_f32_e32 v112, v117, v104
	v_lshlrev_b64 v[102:103], 11, v[102:103]
	v_mul_f32_e32 v112, v149, v112
	v_lshl_add_u64 v[102:103], s[60:61], 0, v[102:103]
	v_mul_f32_e32 v109, v109, v104
	v_mul_f32_e32 v109, v148, v109
	v_lshl_add_u64 v[106:107], v[106:107], 0, v[118:119]
	s_waitcnt vmcnt(0)
	v_lshlrev_b32_e32 v108, 16, v108
	v_mul_f32_e32 v114, 0xbfb8aa3b, v108
	v_exp_f32_e32 v114, v114
	s_nop 0
	v_add_f32_e32 v114, 1.0, v114
	v_rcp_f32_e32 v114, v114
	s_nop 0
	v_mul_f32_e32 v108, v114, v108
	v_mul_f32_e32 v108, v108, v112
	v_cvt_pk_bf16_f32 v108, v108, s0
	v_lshl_add_u64 v[114:115], v[102:103], 0, v[210:211]
	global_store_short v[114:115], v108, off offset:1024
	global_load_ushort v108, v[110:111], off offset:1920
	v_lshl_add_u64 v[102:103], v[102:103], 0, v[118:119]
	s_waitcnt vmcnt(0)
	v_lshlrev_b32_e32 v108, 16, v108
	v_mul_f32_e32 v112, 0xbfb8aa3b, v108
	v_exp_f32_e32 v112, v112
	s_nop 0
	v_add_f32_e32 v112, 1.0, v112
	v_rcp_f32_e32 v112, v112
	s_nop 0
	v_mul_f32_e32 v108, v112, v108
	v_mul_f32_e32 v108, v109, v108
	v_cvt_pk_bf16_f32 v108, v108, s0
	global_store_short v[114:115], v108, off offset:1056
	global_load_ushort v108, v[110:111], off offset:1952
	v_mul_f32_e32 v109, v113, v104
	v_mul_f32_e32 v109, v147, v109
	v_mul_f32_e32 v104, v105, v104
	v_mul_f32_e32 v104, v146, v104
	s_waitcnt vmcnt(0)
	v_lshlrev_b32_e32 v108, 16, v108
	v_mul_f32_e32 v110, 0xbfb8aa3b, v108
	v_exp_f32_e32 v110, v110
	s_nop 0
	v_add_f32_e32 v110, 1.0, v110
	v_rcp_f32_e32 v110, v110
	s_nop 0
	v_mul_f32_e32 v108, v110, v108
	v_mul_f32_e32 v108, v109, v108
	v_cvt_pk_bf16_f32 v108, v108, s0
	global_store_short v[114:115], v108, off offset:1088
	global_load_ushort v106, v[106:107], off offset:1888
	s_waitcnt vmcnt(0)
; template <bool GLA>
; __device__ __forceinline__ void chunk_pass_c(const ChunkIn& ci, const float* wgl, int unit, unsigned char* wl, int lane, const float* Sb, const float* ng, bf16_t* omix) {
;     ...
;     for (int it = 0; it < 4; ++it) {
;         f32x4 st[4];
; #pragma unroll
;         for (int jt = 0; jt < 4; ++jt) {
;             const f32x4 z = {0.f, 0.f, 0.f, 0.f};
;             if (jt < it) st[jt] = __builtin_amdgcn_mfma_f32_16x16x32_bf16(kf[jt], qf[it], z, 0, 0, 0);
;             else if (jt > it) st[jt] = __builtin_amdgcn_mfma_f32_16x16x32_bf16(kb[jt], qb[it], z, 0, 0, 0);
;             else {
;                 const f32x4 lo = __builtin_amdgcn_mfma_f32_16x16x32_bf16(kf[jt], qf[it], z, 0, 0, 0), up = __builtin_amdgcn_mfma_f32_16x16x32_bf16(kb[jt], qb[it], z, 0, 0, 0);
; #pragma unroll
;                 for (int r = 0; r < 4; ++r) st[jt][r] = (4 * kq + r <= row) ? lo[r] : up[r];
;             }
;         }
;         bf16x8 af[2];
; #pragma unroll
;         for (int p = 0; p < 2; ++p)
;             af[p] = __builtin_bit_cast(bf16x8, (u32x4){cvtpk(st[2 * p][0], st[2 * p][1]), cvtpk(st[2 * p][2], st[2 * p][3]), cvtpk(st[2 * p + 1][0], st[2 * p + 1][1]), cvtpk(st[2 * p + 1][2], st[2 * p + 1][3])});
;         f32x4 o[4]; float ss[4] = {0.f, 0.f, 0.f, 0.f};
; #pragma unroll
;         for (int et = 0; et < 4; ++et) {
;             f32x4 acc = {0.f, 0.f, 0.f, 0.f};
;             acc = __builtin_amdgcn_mfma_f32_16x16x32_bf16(af[0], vfr[et][0], acc, 0, 0, 0);
;             acc = __builtin_amdgcn_mfma_f32_16x16x32_bf16(af[1], vfr[et][1], acc, 0, 0, 0);
;             acc = __builtin_amdgcn_mfma_f32_16x16x32_bf16(qf[it], sfr[et], acc, 0, 0, 0);
;             o[et] = acc;
; #pragma unroll
;             for (int r = 0; r < 4; ++r) ss[r] += acc[r] * acc[r];
;         }
; #pragma unroll
;         for (int r = 0; r < 4; ++r) {
;             ss[r] += swz_xor<1>(ss[r]); ss[r] += swz_xor<2>(ss[r]); ss[r] += swz_xor<4>(ss[r]); ss[r] += swz_xor<8>(ss[r]);
;             const float rs = rsqrtf(ss[r] * (1.0f / 64.0f) + EPS);
;             const int t = t0 + 16 * it + 4 * kq + r;
; #pragma unroll
;             for (int et = 0; et < 4; ++et) {
;                 const int e = 16 * et + row;
;                 const float gt = __uint_as_float((unsigned)ci.proj[(size_t)t * DINP + gcol + e] << 16);
;                 const float val = o[et][r] * rs * gn[et] * pg8::silu_f(gt);
	v_lshlrev_b32_e32 v106, 16, v106
	v_mul_f32_e32 v105, 0xbfb8aa3b, v106
	v_exp_f32_e32 v105, v105
	s_nop 0
	v_add_f32_e32 v105, 1.0, v105
	v_rcp_f32_e32 v105, v105
	s_nop 0
	v_mul_f32_e32 v105, v105, v106
	v_mul_f32_e32 v104, v104, v105
	v_cvt_pk_bf16_f32 v104, v104, s0
	v_mfma_f32_16x16x32_bf16 v[106:109], v[8:11], v[88:91], 0
	global_store_short v[102:103], v104, off offset:1024
	v_mfma_f32_16x16x32_bf16 v[102:105], v[0:3], v[88:91], 0
	s_nop 5
	v_cndmask_b32_e32 v106, v106, v98, vcc
	v_cndmask_b32_e64 v107, v99, v107, s[42:43]
	v_cndmask_b32_e64 v108, v108, v100, s[44:45]
	v_cndmask_b32_e64 v109, v109, v101, s[46:47]
	v_mfma_f32_16x16x32_bf16 v[98:101], v[84:87], v[92:95], 0
	v_cvt_pk_bf16_f32 v110, v102, v103
	v_cvt_pk_bf16_f32 v111, v104, v105
	v_cvt_pk_bf16_f32 v112, v106, v107
	v_mfma_f32_16x16x32_bf16 v[92:95], v[72:75], v[92:95], 0
	v_cvt_pk_bf16_f32 v113, v108, v109
	s_nop 2
	v_cvt_pk_bf16_f32 v124, v98, v99
	v_cvt_pk_bf16_f32 v125, v100, v101
	v_mfma_f32_16x16x32_bf16 v[84:87], v[84:87], v[80:83], 0
	v_mfma_f32_16x16x32_bf16 v[80:83], v[72:75], v[80:83], 0
	v_cvt_pk_bf16_f32 v126, v92, v93
	v_cvt_pk_bf16_f32 v127, v94, v95
	v_mfma_f32_16x16x32_bf16 v[92:95], v[110:113], v[64:67], 0
	s_nop 0
	v_mfma_f32_16x16x32_bf16 v[92:95], v[124:127], v[60:63], v[92:95]
	v_mfma_f32_16x16x32_bf16 v[98:101], v[88:91], v[68:71], v[92:95]
	v_mfma_f32_16x16x32_bf16 v[92:95], v[110:113], v[48:51], 0
	v_mfma_f32_16x16x32_bf16 v[92:95], v[124:127], v[44:47], v[92:95]
	s_nop 5
	v_mov_b32_e32 v102, v98
	v_mfma_f32_16x16x32_bf16 v[92:95], v[88:91], v[40:43], v[92:95]
	s_nop 7
	v_mov_b32_e32 v103, v92
	v_pk_mul_f32 v[116:117], v[102:103], v[102:103]
	v_mov_b32_e32 v102, v99
	v_mov_b32_e32 v103, v93
	v_pk_mul_f32 v[122:123], v[102:103], v[102:103]
	v_mov_b32_e32 v102, v100
	v_mov_b32_e32 v103, v94
	v_pk_mul_f32 v[106:107], v[102:103], v[102:103]
	v_mov_b32_e32 v102, v101
	v_mov_b32_e32 v103, v95
	v_pk_mul_f32 v[108:109], v[102:103], v[102:103]
	v_mfma_f32_16x16x32_bf16 v[102:105], v[110:113], v[36:39], 0
	v_mfma_f32_16x16x32_bf16 v[110:113], v[110:113], v[24:27], 0
	v_mfma_f32_16x16x32_bf16 v[102:105], v[124:127], v[32:35], v[102:105]
	v_mfma_f32_16x16x32_bf16 v[110:113], v[124:127], v[20:23], v[110:113]
	v_mfma_f32_16x16x32_bf16 v[102:105], v[88:91], v[28:31], v[102:105]
	v_mfma_f32_16x16x32_bf16 v[88:91], v[88:91], v[16:19], v[110:113]
	s_nop 6
	v_mov_b32_e32 v110, v102
	v_mov_b32_e32 v111, v88
	v_pk_mul_f32 v[124:125], v[110:111], v[110:111]
	v_mov_b32_e32 v110, v103
	v_mov_b32_e32 v111, v89
	v_pk_mul_f32 v[126:127], v[110:111], v[110:111]
	v_mov_b32_e32 v110, v104
	v_mov_b32_e32 v111, v90
	v_pk_mul_f32 v[112:113], v[110:111], v[110:111]
	v_mov_b32_e32 v110, v105
	v_mov_b32_e32 v111, v91
	v_pk_mul_f32 v[114:115], v[110:111], v[110:111]
	v_or_b32_e32 v110, s4, v97
	v_ashrrev_i32_e32 v111, 31, v110
	v_lshlrev_b64 v[128:129], 12, v[110:111]
	v_lshl_add_u64 v[130:131], s[58:59], 0, v[128:129]
	v_lshlrev_b64 v[128:129], 11, v[110:111]
	v_lshl_add_u64 v[132:133], s[60:61], 0, v[128:129]
	v_lshl_add_u64 v[128:129], v[130:131], 0, v[210:211]
	global_load_ushort v111, v[128:129], off offset:1888
	v_lshl_add_u64 v[136:137], v[130:131], 0, v[118:119]
	v_lshl_add_u64 v[130:131], v[132:133], 0, v[118:119]
	s_waitcnt vmcnt(0)
	v_lshlrev_b32_e32 v111, 16, v111
	v_mul_f32_e32 v134, 0xbfb8aa3b, v111
	v_exp_f32_e32 v134, v134
	s_nop 0
	v_add_f32_e32 v134, 1.0, v134
	v_rcp_f32_e32 v134, v134
	s_nop 0
	v_mul_f32_e32 v111, v134, v111
	v_lshl_add_u64 v[134:135], v[132:133], 0, v[210:211]
	v_mov_b32_e32 v132, v122
	v_mov_b32_e32 v133, v116
	v_mov_b32_e32 v116, v123
	v_pk_add_f32 v[116:117], v[132:133], v[116:117]
	v_mov_b32_e32 v122, v126
	v_mov_b32_e32 v123, v124
	v_pk_add_f32 v[116:117], v[116:117], v[122:123]
	v_mov_b32_e32 v124, v127
	v_pk_add_f32 v[116:117], v[116:117], v[124:125]
	ds_swizzle_b32 v123, v117 offset:swizzle(SWAP,1)
	ds_swizzle_b32 v122, v116 offset:swizzle(SWAP,1)
	s_waitcnt lgkmcnt(0)
	v_pk_add_f32 v[116:117], v[116:117], v[122:123]
	ds_swizzle_b32 v123, v117 offset:swizzle(SWAP,2)
	ds_swizzle_b32 v122, v116 offset:swizzle(SWAP,2)
	s_waitcnt lgkmcnt(0)
	v_pk_add_f32 v[116:117], v[116:117], v[122:123]
	ds_swizzle_b32 v123, v117 offset:swizzle(SWAP,4)
	ds_swizzle_b32 v122, v116 offset:swizzle(SWAP,4)
	s_waitcnt lgkmcnt(0)
	v_pk_add_f32 v[116:117], v[116:117], v[122:123]
	ds_swizzle_b32 v123, v117 offset:swizzle(SWAP,8)
	ds_swizzle_b32 v122, v116 offset:swizzle(SWAP,8)
	s_waitcnt lgkmcnt(0)
	v_pk_add_f32 v[116:117], v[116:117], v[122:123]
	s_nop 0
	v_pk_fma_f32 v[116:117], v[116:117], s[6:7], v[120:121] op_sel_hi:[1,0,0]
	s_nop 0
	v_mul_f32_e32 v122, 0x4b800000, v117
	v_cmp_gt_f32_e64 s[50:51], s96, v117
	v_cmp_gt_f32_e64 s[48:49], s96, v116
	s_nop 0
	v_cndmask_b32_e64 v117, v117, v122, s[50:51]
	v_rsq_f32_e32 v117, v117
	s_nop 0
	v_mul_f32_e32 v122, 0x45800000, v117
	v_cndmask_b32_e64 v117, v117, v122, s[50:51]
	v_mul_f32_e32 v98, v98, v117
	v_mul_f32_e32 v98, v149, v98
	v_mul_f32_e32 v98, v111, v98
	v_cvt_pk_bf16_f32 v98, v98, s0
	global_store_short v[134:135], v98, off offset:1024
	global_load_ushort v98, v[128:129], off offset:1920
	v_mul_f32_e32 v92, v92, v117
	v_mul_f32_e32 v92, v148, v92
	v_mul_f32_e32 v88, v88, v117
	v_mul_f32_e32 v88, v146, v88
	s_waitcnt vmcnt(0)
	v_lshlrev_b32_e32 v98, 16, v98
	v_mul_f32_e32 v111, 0xbfb8aa3b, v98
	v_exp_f32_e32 v111, v111
	s_nop 0
	v_add_f32_e32 v111, 1.0, v111
	v_rcp_f32_e32 v111, v111
	s_nop 0
	v_mul_f32_e32 v98, v111, v98
	v_mul_f32_e32 v92, v98, v92
	v_cvt_pk_bf16_f32 v92, v92, s0
	global_store_short v[134:135], v92, off offset:1056
	global_load_ushort v92, v[128:129], off offset:1952
	v_mul_f32_e32 v98, v102, v117
	v_mul_f32_e32 v98, v147, v98
	s_waitcnt vmcnt(0)
; __device__ __forceinline__ unsigned cvtpk(float lo, float hi) { f32x2_t v = {lo, hi}; bf16x2_t b = __builtin_convertvector(v, bf16x2_t); return __builtin_bit_cast(unsigned, b); }
; template <int X> __device__ __forceinline__ float swz_xor(float v) { return __int_as_float(__builtin_amdgcn_ds_swizzle(__float_as_int(v), (X << 10) | 0x1F)); }
; __device__ __forceinline__ float silu_f(float g) { return g * __builtin_amdgcn_rcpf(1.0f + __expf(-g)); }
; template <bool GLA>
; __device__ __forceinline__ void chunk_pass_c(const ChunkIn& ci, const float* wgl, int unit, unsigned char* wl, int lane, const float* Sb, const float* ng, bf16_t* omix) {
;     ...
; #pragma unroll
;         for (int r = 0; r < 4; ++r) {
;             ss[r] += swz_xor<1>(ss[r]); ss[r] += swz_xor<2>(ss[r]); ss[r] += swz_xor<4>(ss[r]); ss[r] += swz_xor<8>(ss[r]);
;             const float rs = rsqrtf(ss[r] * (1.0f / 64.0f) + EPS);
;             const int t = t0 + 16 * it + 4 * kq + r;
; #pragma unroll
;             for (int et = 0; et < 4; ++et) {
;                 const int e = 16 * et + row;
;                 const float gt = __uint_as_float((unsigned)ci.proj[(size_t)t * DINP + gcol + e] << 16);
;                 const float val = o[et][r] * rs * gn[et] * pg8::silu_f(gt);
;                 omix[(size_t)t * 1024 + ocol + e] = (bf16_t)(cvtpk(val, 0.f) & 0xffffu);
;             }
	v_lshlrev_b32_e32 v92, 16, v92
	v_mul_f32_e32 v102, 0xbfb8aa3b, v92
	v_exp_f32_e32 v102, v102
	s_nop 0
	v_add_f32_e32 v102, 1.0, v102
	v_rcp_f32_e32 v102, v102
	s_nop 0
	v_mul_f32_e32 v92, v102, v92
	v_mul_f32_e32 v92, v98, v92
	v_cvt_pk_bf16_f32 v92, v92, s0
	global_store_short v[134:135], v92, off offset:1088
	global_load_ushort v92, v[136:137], off offset:1888
	s_waitcnt vmcnt(0)
	v_lshlrev_b32_e32 v92, 16, v92
	v_mul_f32_e32 v98, 0xbfb8aa3b, v92
	v_exp_f32_e32 v98, v98
	s_nop 0
	v_add_f32_e32 v98, 1.0, v98
	v_rcp_f32_e32 v98, v98
	s_nop 0
	v_mul_f32_e32 v92, v98, v92
	v_mul_f32_e32 v88, v88, v92
	v_cvt_pk_bf16_f32 v88, v88, s0
	global_store_short v[130:131], v88, off offset:1024
	v_mul_f32_e32 v88, 0x4b800000, v116
	v_cndmask_b32_e64 v88, v116, v88, s[48:49]
	v_rsq_f32_e32 v88, v88
	v_or_b32_e32 v116, 1, v110
	v_ashrrev_i32_e32 v117, 31, v116
	v_lshlrev_b64 v[122:123], 12, v[116:117]
	v_lshl_add_u64 v[122:123], s[58:59], 0, v[122:123]
	v_mul_f32_e32 v92, 0x45800000, v88
	v_lshl_add_u64 v[124:125], v[122:123], 0, v[210:211]
	v_cndmask_b32_e64 v88, v88, v92, s[48:49]
	global_load_ushort v92, v[124:125], off offset:1888
	v_mul_f32_e32 v98, v99, v88
	v_lshlrev_b64 v[116:117], 11, v[116:117]
	v_mul_f32_e32 v98, v149, v98
	v_lshl_add_u64 v[116:117], s[60:61], 0, v[116:117]
	v_mul_f32_e32 v93, v93, v88
	v_mul_f32_e32 v93, v148, v93
	s_waitcnt vmcnt(0)
	v_lshlrev_b32_e32 v92, 16, v92
	v_mul_f32_e32 v99, 0xbfb8aa3b, v92
	v_exp_f32_e32 v99, v99
	s_nop 0
	v_add_f32_e32 v99, 1.0, v99
	v_rcp_f32_e32 v99, v99
	s_nop 0
	v_mul_f32_e32 v92, v99, v92
	v_mul_f32_e32 v92, v92, v98
	v_cvt_pk_bf16_f32 v92, v92, s0
	v_lshl_add_u64 v[98:99], v[116:117], 0, v[210:211]
	global_store_short v[98:99], v92, off offset:1024
	global_load_ushort v92, v[124:125], off offset:1920
	s_waitcnt vmcnt(0)
	v_lshlrev_b32_e32 v92, 16, v92
	v_mul_f32_e32 v102, 0xbfb8aa3b, v92
	v_exp_f32_e32 v102, v102
	s_nop 0
	v_add_f32_e32 v102, 1.0, v102
	v_rcp_f32_e32 v102, v102
	s_nop 0
	v_mul_f32_e32 v92, v102, v92
	v_mul_f32_e32 v92, v93, v92
	v_cvt_pk_bf16_f32 v92, v92, s0
	global_store_short v[98:99], v92, off offset:1056
	global_load_ushort v92, v[124:125], off offset:1952
	v_mul_f32_e32 v93, v103, v88
	v_mul_f32_e32 v93, v147, v93
	v_mul_f32_e32 v88, v89, v88
	v_mul_f32_e32 v88, v146, v88
	s_waitcnt vmcnt(0)
	v_lshlrev_b32_e32 v92, 16, v92
	v_mul_f32_e32 v102, 0xbfb8aa3b, v92
	v_exp_f32_e32 v102, v102
	s_nop 0
	v_add_f32_e32 v102, 1.0, v102
	v_rcp_f32_e32 v102, v102
	s_nop 0
	v_mul_f32_e32 v92, v102, v92
	v_mul_f32_e32 v92, v93, v92
	v_cvt_pk_bf16_f32 v92, v92, s0
	global_store_short v[98:99], v92, off offset:1088
	v_lshl_add_u64 v[92:93], v[122:123], 0, v[118:119]
	global_load_ushort v92, v[92:93], off offset:1888
	s_waitcnt vmcnt(0)
	v_lshlrev_b32_e32 v92, 16, v92
	v_mul_f32_e32 v89, 0xbfb8aa3b, v92
	v_exp_f32_e32 v89, v89
	s_nop 0
	v_add_f32_e32 v89, 1.0, v89
	v_rcp_f32_e32 v89, v89
	s_nop 0
	v_mul_f32_e32 v89, v89, v92
	v_mul_f32_e32 v88, v88, v89
	v_cvt_pk_bf16_f32 v92, v88, s0
	v_lshl_add_u64 v[88:89], v[116:117], 0, v[118:119]
	global_store_short v[88:89], v92, off offset:1024
	v_or_b32_e32 v88, 2, v110
	v_ashrrev_i32_e32 v89, 31, v88
	v_lshlrev_b64 v[92:93], 12, v[88:89]
	v_lshl_add_u64 v[92:93], s[58:59], 0, v[92:93]
	v_lshl_add_u64 v[98:99], v[92:93], 0, v[210:211]
	global_load_ushort v102, v[98:99], off offset:1888
	v_mov_b32_e32 v116, v108
	v_mov_b32_e32 v117, v106
	v_mov_b32_e32 v106, v109
	v_pk_add_f32 v[106:107], v[116:117], v[106:107]
	v_mov_b32_e32 v108, v114
	v_mov_b32_e32 v109, v112
	v_pk_add_f32 v[106:107], v[106:107], v[108:109]
	v_mov_b32_e32 v112, v115
	v_pk_add_f32 v[106:107], v[106:107], v[112:113]
	ds_swizzle_b32 v109, v107 offset:swizzle(SWAP,1)
	ds_swizzle_b32 v108, v106 offset:swizzle(SWAP,1)
	v_lshlrev_b64 v[88:89], 11, v[88:89]
	v_lshl_add_u64 v[88:89], s[60:61], 0, v[88:89]
	v_lshl_add_u64 v[92:93], v[92:93], 0, v[118:119]
	s_waitcnt lgkmcnt(0)
	v_pk_add_f32 v[106:107], v[106:107], v[108:109]
	ds_swizzle_b32 v109, v107 offset:swizzle(SWAP,2)
	ds_swizzle_b32 v108, v106 offset:swizzle(SWAP,2)
	s_waitcnt lgkmcnt(0)
	v_pk_add_f32 v[106:107], v[106:107], v[108:109]
	ds_swizzle_b32 v109, v107 offset:swizzle(SWAP,4)
	ds_swizzle_b32 v108, v106 offset:swizzle(SWAP,4)
	s_waitcnt lgkmcnt(0)
	v_pk_add_f32 v[106:107], v[106:107], v[108:109]
	ds_swizzle_b32 v109, v107 offset:swizzle(SWAP,8)
	ds_swizzle_b32 v108, v106 offset:swizzle(SWAP,8)
	s_waitcnt lgkmcnt(0)
	v_pk_add_f32 v[106:107], v[106:107], v[108:109]
	s_nop 0
	v_pk_fma_f32 v[106:107], v[106:107], s[6:7], v[120:121] op_sel_hi:[1,0,0]
	s_waitcnt vmcnt(0)
	v_lshlrev_b32_e32 v102, 16, v102
	v_mul_f32_e32 v103, 0xbfb8aa3b, v102
	v_exp_f32_e32 v103, v103
	v_mul_f32_e32 v108, 0x4b800000, v107
	v_cmp_gt_f32_e64 s[50:51], s96, v107
	v_cmp_gt_f32_e64 s[48:49], s96, v106
	v_add_f32_e32 v103, 1.0, v103
	v_cndmask_b32_e64 v107, v107, v108, s[50:51]
	v_rsq_f32_e32 v107, v107
	v_rcp_f32_e32 v103, v103
	v_mul_f32_e32 v108, 0x45800000, v107
	v_cndmask_b32_e64 v107, v107, v108, s[50:51]
	v_mul_f32_e32 v100, v100, v107
	v_mul_f32_e32 v111, v103, v102
	v_mul_f32_e32 v100, v149, v100
	v_mul_f32_e32 v100, v111, v100
	v_lshl_add_u64 v[102:103], v[88:89], 0, v[210:211]
	v_cvt_pk_bf16_f32 v100, v100, s0
	global_store_short v[102:103], v100, off offset:1024
	global_load_ushort v100, v[98:99], off offset:1920
	v_mul_f32_e32 v94, v94, v107
	v_mul_f32_e32 v94, v148, v94
	v_mul_f32_e32 v90, v90, v107
	v_mul_f32_e32 v90, v146, v90
	v_lshl_add_u64 v[88:89], v[88:89], 0, v[118:119]
	v_cvt_pk_bf16_f32 v111, v82, v83
	s_waitcnt vmcnt(0)
; template <bool GLA>
; __device__ __forceinline__ void chunk_pass_c(const ChunkIn& ci, const float* wgl, int unit, unsigned char* wl, int lane, const float* Sb, const float* ng, bf16_t* omix) {
;     ...
;     for (int it = 0; it < 4; ++it) {
;         f32x4 st[4];
; #pragma unroll
;         for (int jt = 0; jt < 4; ++jt) {
;             const f32x4 z = {0.f, 0.f, 0.f, 0.f};
;             if (jt < it) st[jt] = __builtin_amdgcn_mfma_f32_16x16x32_bf16(kf[jt], qf[it], z, 0, 0, 0);
;             else if (jt > it) st[jt] = __builtin_amdgcn_mfma_f32_16x16x32_bf16(kb[jt], qb[it], z, 0, 0, 0);
;             else {
;                 const f32x4 lo = __builtin_amdgcn_mfma_f32_16x16x32_bf16(kf[jt], qf[it], z, 0, 0, 0), up = __builtin_amdgcn_mfma_f32_16x16x32_bf16(kb[jt], qb[it], z, 0, 0, 0);
; #pragma unroll
;                 for (int r = 0; r < 4; ++r) st[jt][r] = (4 * kq + r <= row) ? lo[r] : up[r];
;             }
;         }
;         bf16x8 af[2];
; #pragma unroll
;         for (int p = 0; p < 2; ++p)
;             af[p] = __builtin_bit_cast(bf16x8, (u32x4){cvtpk(st[2 * p][0], st[2 * p][1]), cvtpk(st[2 * p][2], st[2 * p][3]), cvtpk(st[2 * p + 1][0], st[2 * p + 1][1]), cvtpk(st[2 * p + 1][2], st[2 * p + 1][3])});
;         f32x4 o[4]; float ss[4] = {0.f, 0.f, 0.f, 0.f};
; #pragma unroll
;         for (int et = 0; et < 4; ++et) {
;             f32x4 acc = {0.f, 0.f, 0.f, 0.f};
;             acc = __builtin_amdgcn_mfma_f32_16x16x32_bf16(af[0], vfr[et][0], acc, 0, 0, 0);
;             acc = __builtin_amdgcn_mfma_f32_16x16x32_bf16(af[1], vfr[et][1], acc, 0, 0, 0);
;             acc = __builtin_amdgcn_mfma_f32_16x16x32_bf16(qf[it], sfr[et], acc, 0, 0, 0);
;             o[et] = acc;
; #pragma unroll
;             for (int r = 0; r < 4; ++r) ss[r] += acc[r] * acc[r];
;         }
; #pragma unroll
;         for (int r = 0; r < 4; ++r) {
;             ss[r] += swz_xor<1>(ss[r]); ss[r] += swz_xor<2>(ss[r]); ss[r] += swz_xor<4>(ss[r]); ss[r] += swz_xor<8>(ss[r]);
;             const float rs = rsqrtf(ss[r] * (1.0f / 64.0f) + EPS);
;             const int t = t0 + 16 * it + 4 * kq + r;
; #pragma unroll
;             for (int et = 0; et < 4; ++et) {
;                 const int e = 16 * et + row;
;                 const float gt = __uint_as_float((unsigned)ci.proj[(size_t)t * DINP + gcol + e] << 16);
;                 const float val = o[et][r] * rs * gn[et] * pg8::silu_f(gt);
	v_lshlrev_b32_e32 v100, 16, v100
	v_mul_f32_e32 v108, 0xbfb8aa3b, v100
	v_exp_f32_e32 v108, v108
	s_nop 0
	v_add_f32_e32 v108, 1.0, v108
	v_rcp_f32_e32 v108, v108
	s_nop 0
	v_mul_f32_e32 v100, v108, v100
	v_mul_f32_e32 v94, v94, v100
	v_cvt_pk_bf16_f32 v94, v94, s0
	global_store_short v[102:103], v94, off offset:1056
	global_load_ushort v94, v[98:99], off offset:1952
	v_mul_f32_e32 v98, v104, v107
	v_mul_f32_e32 v98, v147, v98
	s_waitcnt vmcnt(0)
	v_lshlrev_b32_e32 v94, 16, v94
	v_mul_f32_e32 v99, 0xbfb8aa3b, v94
	v_exp_f32_e32 v99, v99
	s_nop 0
	v_add_f32_e32 v99, 1.0, v99
	v_rcp_f32_e32 v99, v99
	s_nop 0
	v_mul_f32_e32 v94, v99, v94
	v_mul_f32_e32 v94, v98, v94
	v_cvt_pk_bf16_f32 v94, v94, s0
	global_store_short v[102:103], v94, off offset:1088
	global_load_ushort v92, v[92:93], off offset:1888
	s_waitcnt vmcnt(0)
	v_lshlrev_b32_e32 v92, 16, v92
	v_mul_f32_e32 v93, 0xbfb8aa3b, v92
	v_exp_f32_e32 v93, v93
	s_nop 0
	v_add_f32_e32 v93, 1.0, v93
	v_rcp_f32_e32 v93, v93
	s_nop 0
	v_mul_f32_e32 v92, v93, v92
	v_mul_f32_e32 v90, v90, v92
	v_cvt_pk_bf16_f32 v90, v90, s0
	global_store_short v[88:89], v90, off offset:1024
	v_mul_f32_e32 v88, 0x4b800000, v106
	v_cndmask_b32_e64 v88, v106, v88, s[48:49]
	v_rsq_f32_e32 v88, v88
	s_nop 0
	v_mul_f32_e32 v89, 0x45800000, v88
	v_cndmask_b32_e64 v90, v88, v89, s[48:49]
	v_or_b32_e32 v88, 3, v110
	v_ashrrev_i32_e32 v89, 31, v88
	v_lshlrev_b64 v[92:93], 12, v[88:89]
	v_lshl_add_u64 v[92:93], s[58:59], 0, v[92:93]
	v_lshl_add_u64 v[98:99], v[92:93], 0, v[210:211]
	global_load_ushort v94, v[98:99], off offset:1888
	v_mul_f32_e32 v100, v101, v90
	v_lshlrev_b64 v[88:89], 11, v[88:89]
	v_mul_f32_e32 v100, v149, v100
	v_lshl_add_u64 v[88:89], s[60:61], 0, v[88:89]
	v_mul_f32_e32 v95, v95, v90
	v_mul_f32_e32 v95, v148, v95
	v_lshl_add_u64 v[92:93], v[92:93], 0, v[118:119]
	v_cvt_pk_bf16_f32 v110, v80, v81
	s_waitcnt vmcnt(0)
	v_lshlrev_b32_e32 v94, 16, v94
	v_mul_f32_e32 v101, 0xbfb8aa3b, v94
	v_exp_f32_e32 v101, v101
	s_nop 0
	v_add_f32_e32 v101, 1.0, v101
	v_rcp_f32_e32 v101, v101
	s_nop 0
	v_mul_f32_e32 v94, v101, v94
	v_mul_f32_e32 v94, v94, v100
	v_cvt_pk_bf16_f32 v94, v94, s0
	v_lshl_add_u64 v[100:101], v[88:89], 0, v[210:211]
	global_store_short v[100:101], v94, off offset:1024
	global_load_ushort v94, v[98:99], off offset:1920
	v_lshl_add_u64 v[88:89], v[88:89], 0, v[118:119]
	s_waitcnt vmcnt(0)
	v_lshlrev_b32_e32 v94, 16, v94
	v_mul_f32_e32 v102, 0xbfb8aa3b, v94
	v_exp_f32_e32 v102, v102
	s_nop 0
	v_add_f32_e32 v102, 1.0, v102
	v_rcp_f32_e32 v102, v102
	s_nop 0
	v_mul_f32_e32 v94, v102, v94
	v_mul_f32_e32 v94, v95, v94
	v_cvt_pk_bf16_f32 v94, v94, s0
	global_store_short v[100:101], v94, off offset:1056
	global_load_ushort v94, v[98:99], off offset:1952
	v_mul_f32_e32 v95, v105, v90
	v_mul_f32_e32 v95, v147, v95
	v_mul_f32_e32 v90, v91, v90
	v_mul_f32_e32 v90, v146, v90
	s_waitcnt vmcnt(0)
	v_lshlrev_b32_e32 v94, 16, v94
	v_mul_f32_e32 v98, 0xbfb8aa3b, v94
	v_exp_f32_e32 v98, v98
	s_nop 0
	v_add_f32_e32 v98, 1.0, v98
	v_rcp_f32_e32 v98, v98
	s_nop 0
	v_mul_f32_e32 v94, v98, v94
	v_mul_f32_e32 v94, v95, v94
	v_cvt_pk_bf16_f32 v94, v94, s0
	global_store_short v[100:101], v94, off offset:1088
	global_load_ushort v92, v[92:93], off offset:1888
	v_mfma_f32_16x16x32_bf16 v[98:101], v[4:7], v[76:79], 0
	s_waitcnt vmcnt(0)
	v_lshlrev_b32_e32 v92, 16, v92
	v_mul_f32_e32 v91, 0xbfb8aa3b, v92
	v_exp_f32_e32 v91, v91
	s_nop 3
	v_cndmask_b32_e64 v86, v100, v86, s[44:45]
	v_cndmask_b32_e64 v87, v101, v87, s[46:47]
	v_cndmask_b32_e32 v84, v98, v84, vcc
	v_add_f32_e32 v91, 1.0, v91
	v_rcp_f32_e32 v91, v91
	v_cndmask_b32_e64 v85, v85, v99, s[42:43]
	v_cvt_pk_bf16_f32 v108, v84, v85
	v_cvt_pk_bf16_f32 v109, v86, v87
	v_mul_f32_e32 v91, v91, v92
	v_mul_f32_e32 v90, v90, v91
	v_cvt_pk_bf16_f32 v90, v90, s0
	global_store_short v[88:89], v90, off offset:1024
	v_mfma_f32_16x16x32_bf16 v[88:91], v[0:3], v[76:79], 0
	v_mfma_f32_16x16x32_bf16 v[92:95], v[8:11], v[76:79], 0
	v_mfma_f32_16x16x32_bf16 v[0:3], v[0:3], v[12:15], 0
	s_nop 5
	v_cvt_pk_bf16_f32 v100, v88, v89
	v_cvt_pk_bf16_f32 v101, v90, v91
	v_cvt_pk_bf16_f32 v102, v92, v93
	v_cvt_pk_bf16_f32 v103, v94, v95
	v_mfma_f32_16x16x32_bf16 v[8:11], v[8:11], v[12:15], 0
	v_cvt_pk_bf16_f32 v52, v0, v1
	v_cvt_pk_bf16_f32 v53, v2, v3
	v_mfma_f32_16x16x32_bf16 v[80:83], v[100:103], v[64:67], 0
	v_mfma_f32_16x16x32_bf16 v[80:83], v[108:111], v[60:63], v[80:83]
	s_nop 3
	v_cvt_pk_bf16_f32 v54, v8, v9
	v_cvt_pk_bf16_f32 v55, v10, v11
	v_mfma_f32_16x16x32_bf16 v[84:87], v[76:79], v[68:71], v[80:83]
	v_mfma_f32_16x16x32_bf16 v[80:83], v[100:103], v[48:51], 0
	v_mfma_f32_16x16x32_bf16 v[80:83], v[108:111], v[44:47], v[80:83]
	s_nop 5
	v_mov_b32_e32 v88, v84
	v_mfma_f32_16x16x32_bf16 v[80:83], v[76:79], v[40:43], v[80:83]
	v_mfma_f32_16x16x32_bf16 v[4:7], v[4:7], v[12:15], 0
	v_mfma_f32_16x16x32_bf16 v[0:3], v[52:55], v[64:67], 0
	s_nop 5
	v_mov_b32_e32 v89, v80
	v_pk_mul_f32 v[104:105], v[88:89], v[88:89]
	v_mov_b32_e32 v88, v85
	v_mov_b32_e32 v89, v81
	v_pk_mul_f32 v[106:107], v[88:89], v[88:89]
	v_mov_b32_e32 v88, v86
	v_mov_b32_e32 v89, v82
	v_pk_mul_f32 v[92:93], v[88:89], v[88:89]
	v_mov_b32_e32 v88, v87
	v_mov_b32_e32 v89, v83
	v_pk_mul_f32 v[98:99], v[88:89], v[88:89]
	v_mfma_f32_16x16x32_bf16 v[88:91], v[100:103], v[36:39], 0
	v_cvt_pk_bf16_f32 v4, v4, v5
	v_cvt_pk_bf16_f32 v5, v6, v7
	v_cvt_pk_bf16_f32 v6, v56, v57
	v_mfma_f32_16x16x32_bf16 v[100:103], v[100:103], v[24:27], 0
	v_cvt_pk_bf16_f32 v7, v58, v59
	v_mfma_f32_16x16x32_bf16 v[88:91], v[108:111], v[32:35], v[88:91]
	v_mfma_f32_16x16x32_bf16 v[100:103], v[108:111], v[20:23], v[100:103]
	v_mfma_f32_16x16x32_bf16 v[88:91], v[76:79], v[28:31], v[88:91]
	v_mfma_f32_16x16x32_bf16 v[76:79], v[76:79], v[16:19], v[100:103]
	v_mfma_f32_16x16x32_bf16 v[0:3], v[4:7], v[60:63], v[0:3]
	s_nop 5
	v_mov_b32_e32 v94, v88
	v_mov_b32_e32 v95, v76
	v_pk_mul_f32 v[108:109], v[94:95], v[94:95]
	v_mov_b32_e32 v94, v89
	v_mov_b32_e32 v95, v77
	v_pk_mul_f32 v[110:111], v[94:95], v[94:95]
	v_mov_b32_e32 v94, v90
	v_mov_b32_e32 v95, v78
	v_pk_mul_f32 v[100:101], v[94:95], v[94:95]
	v_mov_b32_e32 v94, v91
	v_mov_b32_e32 v95, v79
	v_pk_mul_f32 v[102:103], v[94:95], v[94:95]
	v_or_b32_e32 v94, s65, v97
	v_ashrrev_i32_e32 v95, 31, v94
	v_lshlrev_b64 v[112:113], 12, v[94:95]
	v_lshl_add_u64 v[114:115], s[58:59], 0, v[112:113]
	v_lshlrev_b64 v[112:113], 11, v[94:95]
	v_lshl_add_u64 v[116:117], s[60:61], 0, v[112:113]
	v_lshl_add_u64 v[112:113], v[114:115], 0, v[210:211]
	global_load_ushort v95, v[112:113], off offset:1888
	v_lshl_add_u64 v[124:125], v[114:115], 0, v[118:119]
	v_lshl_add_u64 v[114:115], v[116:117], 0, v[118:119]
	v_mfma_f32_16x16x32_bf16 v[8:11], v[12:15], v[68:71], v[0:3]
	s_waitcnt vmcnt(0)
; __device__ __forceinline__ unsigned cvtpk(float lo, float hi) { f32x2_t v = {lo, hi}; bf16x2_t b = __builtin_convertvector(v, bf16x2_t); return __builtin_bit_cast(unsigned, b); }
; template <int X> __device__ __forceinline__ float swz_xor(float v) { return __int_as_float(__builtin_amdgcn_ds_swizzle(__float_as_int(v), (X << 10) | 0x1F)); }
; __device__ __forceinline__ float silu_f(float g) { return g * __builtin_amdgcn_rcpf(1.0f + __expf(-g)); }
; template <bool GLA>
; __device__ __forceinline__ void chunk_pass_c(const ChunkIn& ci, const float* wgl, int unit, unsigned char* wl, int lane, const float* Sb, const float* ng, bf16_t* omix) {
;     ...
;         f32x4 o[4]; float ss[4] = {0.f, 0.f, 0.f, 0.f};
; #pragma unroll
;         for (int et = 0; et < 4; ++et) {
;             f32x4 acc = {0.f, 0.f, 0.f, 0.f};
;             acc = __builtin_amdgcn_mfma_f32_16x16x32_bf16(af[0], vfr[et][0], acc, 0, 0, 0);
;             acc = __builtin_amdgcn_mfma_f32_16x16x32_bf16(af[1], vfr[et][1], acc, 0, 0, 0);
;             acc = __builtin_amdgcn_mfma_f32_16x16x32_bf16(qf[it], sfr[et], acc, 0, 0, 0);
;             o[et] = acc;
; #pragma unroll
;             for (int r = 0; r < 4; ++r) ss[r] += acc[r] * acc[r];
;         }
; #pragma unroll
;         for (int r = 0; r < 4; ++r) {
;             ss[r] += swz_xor<1>(ss[r]); ss[r] += swz_xor<2>(ss[r]); ss[r] += swz_xor<4>(ss[r]); ss[r] += swz_xor<8>(ss[r]);
;             const float rs = rsqrtf(ss[r] * (1.0f / 64.0f) + EPS);
;             const int t = t0 + 16 * it + 4 * kq + r;
; #pragma unroll
;             for (int et = 0; et < 4; ++et) {
;                 const int e = 16 * et + row;
;                 const float gt = __uint_as_float((unsigned)ci.proj[(size_t)t * DINP + gcol + e] << 16);
;                 const float val = o[et][r] * rs * gn[et] * pg8::silu_f(gt);
;                 omix[(size_t)t * 1024 + ocol + e] = (bf16_t)(cvtpk(val, 0.f) & 0xffffu);
;             }
	v_lshlrev_b32_e32 v95, 16, v95
	v_mul_f32_e32 v122, 0xbfb8aa3b, v95
	v_exp_f32_e32 v122, v122
	v_mfma_f32_16x16x32_bf16 v[0:3], v[52:55], v[48:51], 0
	v_add_f32_e32 v122, 1.0, v122
	v_rcp_f32_e32 v122, v122
	v_mfma_f32_16x16x32_bf16 v[36:39], v[52:55], v[36:39], 0
	v_mul_f32_e32 v95, v122, v95
	v_lshl_add_u64 v[122:123], v[116:117], 0, v[210:211]
	v_mov_b32_e32 v116, v106
	v_mov_b32_e32 v117, v104
	v_mov_b32_e32 v104, v107
	v_pk_add_f32 v[104:105], v[116:117], v[104:105]
	v_mov_b32_e32 v106, v110
	v_mov_b32_e32 v107, v108
	v_pk_add_f32 v[104:105], v[104:105], v[106:107]
	v_mov_b32_e32 v108, v111
	v_pk_add_f32 v[104:105], v[104:105], v[108:109]
	ds_swizzle_b32 v107, v105 offset:swizzle(SWAP,1)
	ds_swizzle_b32 v106, v104 offset:swizzle(SWAP,1)
	v_mfma_f32_16x16x32_bf16 v[24:27], v[52:55], v[24:27], 0
	s_waitcnt lgkmcnt(0)
	v_pk_add_f32 v[104:105], v[104:105], v[106:107]
	ds_swizzle_b32 v107, v105 offset:swizzle(SWAP,2)
	ds_swizzle_b32 v106, v104 offset:swizzle(SWAP,2)
	v_mfma_f32_16x16x32_bf16 v[0:3], v[4:7], v[44:47], v[0:3]
	s_waitcnt lgkmcnt(0)
	v_pk_add_f32 v[104:105], v[104:105], v[106:107]
	ds_swizzle_b32 v107, v105 offset:swizzle(SWAP,4)
	ds_swizzle_b32 v106, v104 offset:swizzle(SWAP,4)
	v_mfma_f32_16x16x32_bf16 v[32:35], v[4:7], v[32:35], v[36:39]
	s_waitcnt lgkmcnt(0)
	v_pk_add_f32 v[104:105], v[104:105], v[106:107]
	ds_swizzle_b32 v107, v105 offset:swizzle(SWAP,8)
	ds_swizzle_b32 v106, v104 offset:swizzle(SWAP,8)
	v_mfma_f32_16x16x32_bf16 v[4:7], v[4:7], v[20:23], v[24:27]
	s_waitcnt lgkmcnt(0)
	v_pk_add_f32 v[104:105], v[104:105], v[106:107]
	s_nop 0
	v_pk_fma_f32 v[104:105], v[104:105], s[6:7], v[120:121] op_sel_hi:[1,0,0]
	v_mfma_f32_16x16x32_bf16 v[28:31], v[12:15], v[28:31], v[32:35]
	v_mul_f32_e32 v106, 0x4b800000, v105
	v_cmp_gt_f32_e64 s[50:51], s96, v105
	v_cmp_gt_f32_e64 s[48:49], s96, v104
	v_mfma_f32_16x16x32_bf16 v[4:7], v[12:15], v[16:19], v[4:7]
	v_cndmask_b32_e64 v105, v105, v106, s[50:51]
	v_rsq_f32_e32 v105, v105
	v_mfma_f32_16x16x32_bf16 v[0:3], v[12:15], v[40:43], v[0:3]
	s_nop 0
	v_mov_b32_e32 v12, v28
	v_mul_f32_e32 v106, 0x45800000, v105
	v_cndmask_b32_e64 v105, v105, v106, s[50:51]
	v_mul_f32_e32 v84, v84, v105
	v_mul_f32_e32 v84, v149, v84
	v_mul_f32_e32 v84, v95, v84
	v_cvt_pk_bf16_f32 v84, v84, s0
	global_store_short v[122:123], v84, off offset:1024
	global_load_ushort v84, v[112:113], off offset:1920
	v_mul_f32_e32 v80, v80, v105
	v_mul_f32_e32 v80, v148, v80
	v_mul_f32_e32 v76, v76, v105
	v_mul_f32_e32 v76, v146, v76
	v_mov_b32_e32 v13, v4
	v_pk_mul_f32 v[18:19], v[12:13], v[12:13]
	v_mov_b32_e32 v12, v29
	v_mov_b32_e32 v13, v5
	v_pk_mul_f32 v[20:21], v[12:13], v[12:13]
	v_mov_b32_e32 v12, v30
	v_mov_b32_e32 v13, v6
	v_pk_mul_f32 v[14:15], v[12:13], v[12:13]
	v_mov_b32_e32 v12, v31
	v_mov_b32_e32 v13, v7
	v_pk_mul_f32 v[16:17], v[12:13], v[12:13]
	v_or_b32_e32 v12, s27, v97
	v_ashrrev_i32_e32 v13, 31, v12
	v_lshlrev_b64 v[22:23], 12, v[12:13]
	v_lshl_add_u64 v[24:25], s[58:59], 0, v[22:23]
	v_lshlrev_b64 v[22:23], 11, v[12:13]
	v_lshl_add_u64 v[26:27], s[60:61], 0, v[22:23]
	v_lshl_add_u64 v[22:23], v[24:25], 0, v[210:211]
	v_mov_b32_e32 v40, v8
	v_mov_b32_e32 v41, v0
	v_pk_mul_f32 v[44:45], v[40:41], v[40:41]
	v_mov_b32_e32 v40, v9
	v_mov_b32_e32 v41, v1
	v_pk_mul_f32 v[46:47], v[40:41], v[40:41]
	v_lshl_add_u64 v[34:35], v[24:25], 0, v[118:119]
	v_lshl_add_u64 v[24:25], v[26:27], 0, v[118:119]
	v_mov_b32_e32 v36, v20
	v_mov_b32_e32 v37, v18
	v_mov_b32_e32 v18, v21
	v_mov_b32_e32 v40, v10
	v_mov_b32_e32 v41, v2
	v_mov_b32_e32 v42, v11
	v_mov_b32_e32 v43, v3
	v_pk_mul_f32 v[40:41], v[40:41], v[40:41]
	v_pk_mul_f32 v[42:43], v[42:43], v[42:43]
	s_waitcnt vmcnt(0)
	v_lshlrev_b32_e32 v84, 16, v84
	v_mul_f32_e32 v95, 0xbfb8aa3b, v84
	v_exp_f32_e32 v95, v95
	s_nop 0
	v_add_f32_e32 v95, 1.0, v95
	v_rcp_f32_e32 v95, v95
	s_nop 0
	v_mul_f32_e32 v84, v95, v84
	v_mul_f32_e32 v80, v84, v80
	v_cvt_pk_bf16_f32 v80, v80, s0
	global_store_short v[122:123], v80, off offset:1056
	global_load_ushort v80, v[112:113], off offset:1952
	v_mul_f32_e32 v84, v88, v105
	v_mul_f32_e32 v84, v147, v84
	s_waitcnt vmcnt(0)
	v_lshlrev_b32_e32 v80, 16, v80
	v_mul_f32_e32 v88, 0xbfb8aa3b, v80
	v_exp_f32_e32 v88, v88
	s_nop 0
	v_add_f32_e32 v88, 1.0, v88
	v_rcp_f32_e32 v88, v88
	s_nop 0
	v_mul_f32_e32 v80, v88, v80
	v_mul_f32_e32 v80, v84, v80
	v_cvt_pk_bf16_f32 v80, v80, s0
	global_store_short v[122:123], v80, off offset:1088
	global_load_ushort v80, v[124:125], off offset:1888
	s_waitcnt vmcnt(0)
	v_lshlrev_b32_e32 v80, 16, v80
	v_mul_f32_e32 v84, 0xbfb8aa3b, v80
	v_exp_f32_e32 v84, v84
	s_nop 0
	v_add_f32_e32 v84, 1.0, v84
	v_rcp_f32_e32 v84, v84
	s_nop 0
	v_mul_f32_e32 v80, v84, v80
	v_mul_f32_e32 v76, v76, v80
	v_cvt_pk_bf16_f32 v76, v76, s0
	global_store_short v[114:115], v76, off offset:1024
	v_mul_f32_e32 v76, 0x4b800000, v104
	v_cndmask_b32_e64 v76, v104, v76, s[48:49]
	v_rsq_f32_e32 v76, v76
	v_or_b32_e32 v104, 1, v94
	v_ashrrev_i32_e32 v105, 31, v104
	v_lshlrev_b64 v[106:107], 12, v[104:105]
	v_lshl_add_u64 v[106:107], s[58:59], 0, v[106:107]
	v_mul_f32_e32 v80, 0x45800000, v76
	v_lshl_add_u64 v[108:109], v[106:107], 0, v[210:211]
	v_cndmask_b32_e64 v76, v76, v80, s[48:49]
	global_load_ushort v80, v[108:109], off offset:1888
	v_mul_f32_e32 v84, v85, v76
	v_lshlrev_b64 v[104:105], 11, v[104:105]
	v_mul_f32_e32 v84, v149, v84
	v_lshl_add_u64 v[104:105], s[60:61], 0, v[104:105]
	v_mul_f32_e32 v81, v81, v76
	v_mul_f32_e32 v81, v148, v81
	s_waitcnt vmcnt(0)
; __device__ __forceinline__ unsigned cvtpk(float lo, float hi) { f32x2_t v = {lo, hi}; bf16x2_t b = __builtin_convertvector(v, bf16x2_t); return __builtin_bit_cast(unsigned, b); }
; template <int X> __device__ __forceinline__ float swz_xor(float v) { return __int_as_float(__builtin_amdgcn_ds_swizzle(__float_as_int(v), (X << 10) | 0x1F)); }
; __device__ __forceinline__ float silu_f(float g) { return g * __builtin_amdgcn_rcpf(1.0f + __expf(-g)); }
; template <bool GLA>
; __device__ __forceinline__ void chunk_pass_c(const ChunkIn& ci, const float* wgl, int unit, unsigned char* wl, int lane, const float* Sb, const float* ng, bf16_t* omix) {
;     ...
; #pragma unroll
;         for (int r = 0; r < 4; ++r) {
;             ss[r] += swz_xor<1>(ss[r]); ss[r] += swz_xor<2>(ss[r]); ss[r] += swz_xor<4>(ss[r]); ss[r] += swz_xor<8>(ss[r]);
;             const float rs = rsqrtf(ss[r] * (1.0f / 64.0f) + EPS);
;             const int t = t0 + 16 * it + 4 * kq + r;
; #pragma unroll
;             for (int et = 0; et < 4; ++et) {
;                 const int e = 16 * et + row;
;                 const float gt = __uint_as_float((unsigned)ci.proj[(size_t)t * DINP + gcol + e] << 16);
;                 const float val = o[et][r] * rs * gn[et] * pg8::silu_f(gt);
;                 omix[(size_t)t * 1024 + ocol + e] = (bf16_t)(cvtpk(val, 0.f) & 0xffffu);
;             }
	v_lshlrev_b32_e32 v80, 16, v80
	v_mul_f32_e32 v85, 0xbfb8aa3b, v80
	v_exp_f32_e32 v85, v85
	s_nop 0
	v_add_f32_e32 v85, 1.0, v85
	v_rcp_f32_e32 v85, v85
	s_nop 0
	v_mul_f32_e32 v80, v85, v80
	v_mul_f32_e32 v80, v80, v84
	v_cvt_pk_bf16_f32 v80, v80, s0
	v_lshl_add_u64 v[84:85], v[104:105], 0, v[210:211]
	global_store_short v[84:85], v80, off offset:1024
	global_load_ushort v80, v[108:109], off offset:1920
	s_waitcnt vmcnt(0)
	v_lshlrev_b32_e32 v80, 16, v80
	v_mul_f32_e32 v88, 0xbfb8aa3b, v80
	v_exp_f32_e32 v88, v88
	s_nop 0
	v_add_f32_e32 v88, 1.0, v88
	v_rcp_f32_e32 v88, v88
	s_nop 0
	v_mul_f32_e32 v80, v88, v80
	v_mul_f32_e32 v80, v81, v80
	v_cvt_pk_bf16_f32 v80, v80, s0
	global_store_short v[84:85], v80, off offset:1056
	global_load_ushort v80, v[108:109], off offset:1952
	v_mul_f32_e32 v81, v89, v76
	v_mul_f32_e32 v81, v147, v81
	v_mul_f32_e32 v76, v77, v76
	v_mul_f32_e32 v76, v146, v76
	s_waitcnt vmcnt(0)
	v_lshlrev_b32_e32 v80, 16, v80
	v_mul_f32_e32 v88, 0xbfb8aa3b, v80
	v_exp_f32_e32 v88, v88
	s_nop 0
	v_add_f32_e32 v88, 1.0, v88
	v_rcp_f32_e32 v88, v88
	s_nop 0
	v_mul_f32_e32 v80, v88, v80
	v_mul_f32_e32 v80, v81, v80
	v_cvt_pk_bf16_f32 v80, v80, s0
	global_store_short v[84:85], v80, off offset:1088
	v_lshl_add_u64 v[80:81], v[106:107], 0, v[118:119]
	global_load_ushort v80, v[80:81], off offset:1888
	s_waitcnt vmcnt(0)
	v_lshlrev_b32_e32 v80, 16, v80
	v_mul_f32_e32 v77, 0xbfb8aa3b, v80
	v_exp_f32_e32 v77, v77
	s_nop 0
	v_add_f32_e32 v77, 1.0, v77
	v_rcp_f32_e32 v77, v77
	s_nop 0
	v_mul_f32_e32 v77, v77, v80
	v_mul_f32_e32 v76, v76, v77
	v_cvt_pk_bf16_f32 v80, v76, s0
	v_lshl_add_u64 v[76:77], v[104:105], 0, v[118:119]
	global_store_short v[76:77], v80, off offset:1024
	v_or_b32_e32 v76, 2, v94
	v_ashrrev_i32_e32 v77, 31, v76
	v_lshlrev_b64 v[80:81], 12, v[76:77]
	v_lshl_add_u64 v[80:81], s[58:59], 0, v[80:81]
	v_lshl_add_u64 v[84:85], v[80:81], 0, v[210:211]
	global_load_ushort v88, v[84:85], off offset:1888
	v_mov_b32_e32 v104, v98
	v_mov_b32_e32 v105, v92
	v_mov_b32_e32 v92, v99
	v_pk_add_f32 v[92:93], v[104:105], v[92:93]
	v_mov_b32_e32 v98, v102
	v_mov_b32_e32 v99, v100
	v_pk_add_f32 v[92:93], v[92:93], v[98:99]
	v_mov_b32_e32 v100, v103
	v_pk_add_f32 v[92:93], v[92:93], v[100:101]
	ds_swizzle_b32 v99, v93 offset:swizzle(SWAP,1)
	ds_swizzle_b32 v98, v92 offset:swizzle(SWAP,1)
	v_lshlrev_b64 v[76:77], 11, v[76:77]
	v_lshl_add_u64 v[76:77], s[60:61], 0, v[76:77]
	v_lshl_add_u64 v[80:81], v[80:81], 0, v[118:119]
	s_waitcnt lgkmcnt(0)
	v_pk_add_f32 v[92:93], v[92:93], v[98:99]
	ds_swizzle_b32 v99, v93 offset:swizzle(SWAP,2)
	ds_swizzle_b32 v98, v92 offset:swizzle(SWAP,2)
	s_waitcnt lgkmcnt(0)
	v_pk_add_f32 v[92:93], v[92:93], v[98:99]
	ds_swizzle_b32 v99, v93 offset:swizzle(SWAP,4)
	ds_swizzle_b32 v98, v92 offset:swizzle(SWAP,4)
	s_waitcnt lgkmcnt(0)
	v_pk_add_f32 v[92:93], v[92:93], v[98:99]
	ds_swizzle_b32 v99, v93 offset:swizzle(SWAP,8)
	ds_swizzle_b32 v98, v92 offset:swizzle(SWAP,8)
	s_waitcnt lgkmcnt(0)
	v_pk_add_f32 v[92:93], v[92:93], v[98:99]
	s_nop 0
	v_pk_fma_f32 v[92:93], v[92:93], s[6:7], v[120:121] op_sel_hi:[1,0,0]
	s_waitcnt vmcnt(0)
	v_lshlrev_b32_e32 v88, 16, v88
	v_mul_f32_e32 v89, 0xbfb8aa3b, v88
	v_exp_f32_e32 v89, v89
	v_mul_f32_e32 v98, 0x4b800000, v93
	v_cmp_gt_f32_e64 s[50:51], s96, v93
	v_cmp_gt_f32_e64 s[48:49], s96, v92
	v_add_f32_e32 v89, 1.0, v89
	v_cndmask_b32_e64 v93, v93, v98, s[50:51]
	v_rsq_f32_e32 v93, v93
	v_rcp_f32_e32 v89, v89
	v_mul_f32_e32 v98, 0x45800000, v93
	v_cndmask_b32_e64 v93, v93, v98, s[50:51]
	v_mul_f32_e32 v86, v86, v93
	v_mul_f32_e32 v95, v89, v88
	v_mul_f32_e32 v86, v149, v86
	v_mul_f32_e32 v86, v95, v86
	v_lshl_add_u64 v[88:89], v[76:77], 0, v[210:211]
	v_cvt_pk_bf16_f32 v86, v86, s0
	global_store_short v[88:89], v86, off offset:1024
	global_load_ushort v86, v[84:85], off offset:1920
	v_mul_f32_e32 v82, v82, v93
	v_mul_f32_e32 v82, v148, v82
	v_mul_f32_e32 v78, v78, v93
	v_mul_f32_e32 v78, v146, v78
	v_lshl_add_u64 v[76:77], v[76:77], 0, v[118:119]
	s_waitcnt vmcnt(0)
	v_lshlrev_b32_e32 v86, 16, v86
	v_mul_f32_e32 v95, 0xbfb8aa3b, v86
	v_exp_f32_e32 v95, v95
	s_nop 0
	v_add_f32_e32 v95, 1.0, v95
	v_rcp_f32_e32 v95, v95
	s_nop 0
	v_mul_f32_e32 v86, v95, v86
	v_mul_f32_e32 v82, v82, v86
	v_cvt_pk_bf16_f32 v82, v82, s0
	global_store_short v[88:89], v82, off offset:1056
	global_load_ushort v82, v[84:85], off offset:1952
	v_mul_f32_e32 v84, v90, v93
	v_mul_f32_e32 v84, v147, v84
	s_waitcnt vmcnt(0)
	v_lshlrev_b32_e32 v82, 16, v82
	v_mul_f32_e32 v85, 0xbfb8aa3b, v82
	v_exp_f32_e32 v85, v85
	s_nop 0
	v_add_f32_e32 v85, 1.0, v85
	v_rcp_f32_e32 v85, v85
	s_nop 0
	v_mul_f32_e32 v82, v85, v82
	v_mul_f32_e32 v82, v84, v82
	v_cvt_pk_bf16_f32 v82, v82, s0
	global_store_short v[88:89], v82, off offset:1088
	global_load_ushort v80, v[80:81], off offset:1888
	s_waitcnt vmcnt(0)
	v_lshlrev_b32_e32 v80, 16, v80
	v_mul_f32_e32 v81, 0xbfb8aa3b, v80
	v_exp_f32_e32 v81, v81
	s_nop 0
	v_add_f32_e32 v81, 1.0, v81
	v_rcp_f32_e32 v81, v81
	s_nop 0
	v_mul_f32_e32 v80, v81, v80
	v_mul_f32_e32 v78, v78, v80
	v_cvt_pk_bf16_f32 v78, v78, s0
	global_store_short v[76:77], v78, off offset:1024
	v_mul_f32_e32 v76, 0x4b800000, v92
	v_cndmask_b32_e64 v76, v92, v76, s[48:49]
	v_rsq_f32_e32 v76, v76
	s_nop 0
	v_mul_f32_e32 v77, 0x45800000, v76
	v_cndmask_b32_e64 v78, v76, v77, s[48:49]
	v_or_b32_e32 v76, 3, v94
	v_ashrrev_i32_e32 v77, 31, v76
	v_lshlrev_b64 v[80:81], 12, v[76:77]
	v_lshl_add_u64 v[80:81], s[58:59], 0, v[80:81]
	v_lshl_add_u64 v[84:85], v[80:81], 0, v[210:211]
	global_load_ushort v82, v[84:85], off offset:1888
	v_mul_f32_e32 v86, v87, v78
	v_lshlrev_b64 v[76:77], 11, v[76:77]
	v_mul_f32_e32 v86, v149, v86
	v_lshl_add_u64 v[76:77], s[60:61], 0, v[76:77]
	v_mul_f32_e32 v83, v83, v78
	v_mul_f32_e32 v83, v148, v83
	v_lshl_add_u64 v[80:81], v[80:81], 0, v[118:119]
	s_waitcnt vmcnt(0)
; __device__ __forceinline__ unsigned cvtpk(float lo, float hi) { f32x2_t v = {lo, hi}; bf16x2_t b = __builtin_convertvector(v, bf16x2_t); return __builtin_bit_cast(unsigned, b); }
; template <int X> __device__ __forceinline__ float swz_xor(float v) { return __int_as_float(__builtin_amdgcn_ds_swizzle(__float_as_int(v), (X << 10) | 0x1F)); }
; __device__ __forceinline__ float silu_f(float g) { return g * __builtin_amdgcn_rcpf(1.0f + __expf(-g)); }
; template <bool GLA>
; __device__ __forceinline__ void chunk_pass_c(const ChunkIn& ci, const float* wgl, int unit, unsigned char* wl, int lane, const float* Sb, const float* ng, bf16_t* omix) {
;     ...
; #pragma unroll
;         for (int r = 0; r < 4; ++r) {
;             ss[r] += swz_xor<1>(ss[r]); ss[r] += swz_xor<2>(ss[r]); ss[r] += swz_xor<4>(ss[r]); ss[r] += swz_xor<8>(ss[r]);
;             const float rs = rsqrtf(ss[r] * (1.0f / 64.0f) + EPS);
;             const int t = t0 + 16 * it + 4 * kq + r;
; #pragma unroll
;             for (int et = 0; et < 4; ++et) {
;                 const int e = 16 * et + row;
;                 const float gt = __uint_as_float((unsigned)ci.proj[(size_t)t * DINP + gcol + e] << 16);
;                 const float val = o[et][r] * rs * gn[et] * pg8::silu_f(gt);
;                 omix[(size_t)t * 1024 + ocol + e] = (bf16_t)(cvtpk(val, 0.f) & 0xffffu);
;             }
	v_lshlrev_b32_e32 v82, 16, v82
	v_mul_f32_e32 v87, 0xbfb8aa3b, v82
	v_exp_f32_e32 v87, v87
	s_nop 0
	v_add_f32_e32 v87, 1.0, v87
	v_rcp_f32_e32 v87, v87
	s_nop 0
	v_mul_f32_e32 v82, v87, v82
	v_mul_f32_e32 v82, v82, v86
	v_cvt_pk_bf16_f32 v82, v82, s0
	v_lshl_add_u64 v[86:87], v[76:77], 0, v[210:211]
	global_store_short v[86:87], v82, off offset:1024
	global_load_ushort v82, v[84:85], off offset:1920
	v_lshl_add_u64 v[76:77], v[76:77], 0, v[118:119]
	s_waitcnt vmcnt(0)
	v_lshlrev_b32_e32 v82, 16, v82
	v_mul_f32_e32 v88, 0xbfb8aa3b, v82
	v_exp_f32_e32 v88, v88
	s_nop 0
	v_add_f32_e32 v88, 1.0, v88
	v_rcp_f32_e32 v88, v88
	s_nop 0
	v_mul_f32_e32 v82, v88, v82
	v_mul_f32_e32 v82, v83, v82
	v_cvt_pk_bf16_f32 v82, v82, s0
	global_store_short v[86:87], v82, off offset:1056
	global_load_ushort v82, v[84:85], off offset:1952
	v_mul_f32_e32 v83, v91, v78
	v_mul_f32_e32 v83, v147, v83
	v_mul_f32_e32 v78, v79, v78
	v_mul_f32_e32 v78, v146, v78
	s_waitcnt vmcnt(0)
	v_lshlrev_b32_e32 v82, 16, v82
	v_mul_f32_e32 v84, 0xbfb8aa3b, v82
	v_exp_f32_e32 v84, v84
	s_nop 0
	v_add_f32_e32 v84, 1.0, v84
	v_rcp_f32_e32 v84, v84
	s_nop 0
	v_mul_f32_e32 v82, v84, v82
	v_mul_f32_e32 v82, v83, v82
	v_cvt_pk_bf16_f32 v82, v82, s0
	global_store_short v[86:87], v82, off offset:1088
	global_load_ushort v80, v[80:81], off offset:1888
	s_waitcnt vmcnt(0)
	v_lshlrev_b32_e32 v80, 16, v80
	v_mul_f32_e32 v79, 0xbfb8aa3b, v80
	v_exp_f32_e32 v79, v79
	s_nop 0
	v_add_f32_e32 v79, 1.0, v79
	v_rcp_f32_e32 v79, v79
	s_nop 0
	v_mul_f32_e32 v79, v79, v80
	v_mul_f32_e32 v78, v78, v79
	v_cvt_pk_bf16_f32 v78, v78, s0
	global_store_short v[76:77], v78, off offset:1024
	global_load_ushort v13, v[22:23], off offset:1888
	s_waitcnt vmcnt(0)
	v_lshlrev_b32_e32 v13, 16, v13
	v_mul_f32_e32 v32, 0xbfb8aa3b, v13
	v_exp_f32_e32 v32, v32
	s_nop 0
	v_add_f32_e32 v32, 1.0, v32
	v_rcp_f32_e32 v32, v32
	s_nop 0
	v_mul_f32_e32 v13, v32, v13
	v_lshl_add_u64 v[32:33], v[26:27], 0, v[210:211]
	v_mov_b32_e32 v26, v46
	v_mov_b32_e32 v27, v44
	v_mov_b32_e32 v44, v47
	v_pk_add_f32 v[26:27], v[26:27], v[44:45]
	s_nop 0
	v_pk_add_f32 v[26:27], v[26:27], v[36:37]
	s_nop 0
	v_pk_add_f32 v[18:19], v[26:27], v[18:19]
	ds_swizzle_b32 v21, v19 offset:swizzle(SWAP,1)
	ds_swizzle_b32 v20, v18 offset:swizzle(SWAP,1)
	s_waitcnt lgkmcnt(0)
	v_pk_add_f32 v[18:19], v[18:19], v[20:21]
	ds_swizzle_b32 v21, v19 offset:swizzle(SWAP,2)
	ds_swizzle_b32 v20, v18 offset:swizzle(SWAP,2)
	s_waitcnt lgkmcnt(0)
	v_pk_add_f32 v[18:19], v[18:19], v[20:21]
	ds_swizzle_b32 v21, v19 offset:swizzle(SWAP,4)
	ds_swizzle_b32 v20, v18 offset:swizzle(SWAP,4)
	s_waitcnt lgkmcnt(0)
	v_pk_add_f32 v[18:19], v[18:19], v[20:21]
	ds_swizzle_b32 v21, v19 offset:swizzle(SWAP,8)
	ds_swizzle_b32 v20, v18 offset:swizzle(SWAP,8)
	s_waitcnt lgkmcnt(0)
	v_pk_add_f32 v[18:19], v[18:19], v[20:21]
	s_nop 0
	v_pk_fma_f32 v[18:19], v[18:19], s[6:7], v[120:121] op_sel_hi:[1,0,0]
	s_nop 0
	v_mul_f32_e32 v20, 0x4b800000, v19
	v_cmp_gt_f32_e64 s[42:43], s96, v19
	v_cmp_gt_f32_e32 vcc, s96, v18
	s_nop 0
	v_cndmask_b32_e64 v19, v19, v20, s[42:43]
	v_rsq_f32_e32 v19, v19
	s_nop 0
	v_mul_f32_e32 v20, 0x45800000, v19
	v_cndmask_b32_e64 v19, v19, v20, s[42:43]
	v_mul_f32_e32 v8, v8, v19
	v_mul_f32_e32 v8, v149, v8
	v_mul_f32_e32 v8, v13, v8
	v_cvt_pk_bf16_f32 v8, v8, s0
	global_store_short v[32:33], v8, off offset:1024
	global_load_ushort v8, v[22:23], off offset:1920
	v_mul_f32_e32 v0, v0, v19
	v_mul_f32_e32 v0, v148, v0
	v_mul_f32_e32 v4, v4, v19
	v_mul_f32_e32 v4, v146, v4
	s_waitcnt vmcnt(0)
	v_lshlrev_b32_e32 v8, 16, v8
	v_mul_f32_e32 v13, 0xbfb8aa3b, v8
	v_exp_f32_e32 v13, v13
	s_nop 0
	v_add_f32_e32 v13, 1.0, v13
	v_rcp_f32_e32 v13, v13
	s_nop 0
	v_mul_f32_e32 v8, v13, v8
	v_mul_f32_e32 v0, v8, v0
	v_cvt_pk_bf16_f32 v0, v0, s0
	global_store_short v[32:33], v0, off offset:1056
	global_load_ushort v0, v[22:23], off offset:1952
	v_mul_f32_e32 v8, v28, v19
	v_mul_f32_e32 v8, v147, v8
	s_waitcnt vmcnt(0)
	v_lshlrev_b32_e32 v0, 16, v0
	v_mul_f32_e32 v13, 0xbfb8aa3b, v0
	v_exp_f32_e32 v13, v13
	s_nop 0
	v_add_f32_e32 v13, 1.0, v13
	v_rcp_f32_e32 v13, v13
	s_nop 0
	v_mul_f32_e32 v0, v13, v0
	v_mul_f32_e32 v0, v8, v0
	v_cvt_pk_bf16_f32 v0, v0, s0
	global_store_short v[32:33], v0, off offset:1088
	global_load_ushort v0, v[34:35], off offset:1888
	s_waitcnt vmcnt(0)
	v_lshlrev_b32_e32 v0, 16, v0
	v_mul_f32_e32 v8, 0xbfb8aa3b, v0
	v_exp_f32_e32 v8, v8
	s_nop 0
	v_add_f32_e32 v8, 1.0, v8
	v_rcp_f32_e32 v8, v8
	s_nop 0
	v_mul_f32_e32 v0, v8, v0
	v_mul_f32_e32 v0, v4, v0
	v_cvt_pk_bf16_f32 v0, v0, s0
	global_store_short v[24:25], v0, off offset:1024
	v_mul_f32_e32 v0, 0x4b800000, v18
	v_cndmask_b32_e32 v0, v18, v0, vcc
	v_rsq_f32_e32 v0, v0
	v_or_b32_e32 v18, 1, v12
	v_ashrrev_i32_e32 v19, 31, v18
	v_lshlrev_b64 v[20:21], 12, v[18:19]
	v_lshl_add_u64 v[20:21], s[58:59], 0, v[20:21]
	v_mul_f32_e32 v4, 0x45800000, v0
	v_lshl_add_u64 v[22:23], v[20:21], 0, v[210:211]
	v_cndmask_b32_e32 v4, v0, v4, vcc
	global_load_ushort v0, v[22:23], off offset:1888
	v_mul_f32_e32 v8, v9, v4
	v_lshlrev_b64 v[18:19], 11, v[18:19]
	v_mul_f32_e32 v8, v149, v8
	v_lshl_add_u64 v[18:19], s[60:61], 0, v[18:19]
	v_mul_f32_e32 v1, v1, v4
	v_mul_f32_e32 v1, v148, v1
	s_waitcnt vmcnt(0)
	v_lshlrev_b32_e32 v0, 16, v0
	v_mul_f32_e32 v9, 0xbfb8aa3b, v0
	v_exp_f32_e32 v9, v9
	s_nop 0
	v_add_f32_e32 v9, 1.0, v9
	v_rcp_f32_e32 v9, v9
	s_nop 0
	v_mul_f32_e32 v0, v9, v0
	v_mul_f32_e32 v0, v0, v8
	v_cvt_pk_bf16_f32 v0, v0, s0
	v_lshl_add_u64 v[8:9], v[18:19], 0, v[210:211]
	global_store_short v[8:9], v0, off offset:1024
	global_load_ushort v0, v[22:23], off offset:1920
	s_waitcnt vmcnt(0)
; __device__ __forceinline__ unsigned cvtpk(float lo, float hi) { f32x2_t v = {lo, hi}; bf16x2_t b = __builtin_convertvector(v, bf16x2_t); return __builtin_bit_cast(unsigned, b); }
; template <int X> __device__ __forceinline__ float swz_xor(float v) { return __int_as_float(__builtin_amdgcn_ds_swizzle(__float_as_int(v), (X << 10) | 0x1F)); }
; __device__ __forceinline__ float silu_f(float g) { return g * __builtin_amdgcn_rcpf(1.0f + __expf(-g)); }
; template <bool GLA>
; __device__ __forceinline__ void chunk_pass_c(const ChunkIn& ci, const float* wgl, int unit, unsigned char* wl, int lane, const float* Sb, const float* ng, bf16_t* omix) {
;     ...
; #pragma unroll
;         for (int r = 0; r < 4; ++r) {
;             ss[r] += swz_xor<1>(ss[r]); ss[r] += swz_xor<2>(ss[r]); ss[r] += swz_xor<4>(ss[r]); ss[r] += swz_xor<8>(ss[r]);
;             const float rs = rsqrtf(ss[r] * (1.0f / 64.0f) + EPS);
;             const int t = t0 + 16 * it + 4 * kq + r;
; #pragma unroll
;             for (int et = 0; et < 4; ++et) {
;                 const int e = 16 * et + row;
;                 const float gt = __uint_as_float((unsigned)ci.proj[(size_t)t * DINP + gcol + e] << 16);
;                 const float val = o[et][r] * rs * gn[et] * pg8::silu_f(gt);
;                 omix[(size_t)t * 1024 + ocol + e] = (bf16_t)(cvtpk(val, 0.f) & 0xffffu);
;             }
;         }
;     }
;     __builtin_amdgcn_s_waitcnt(0); asm volatile("" ::: "memory");
	v_lshlrev_b32_e32 v0, 16, v0
	v_mul_f32_e32 v13, 0xbfb8aa3b, v0
	v_exp_f32_e32 v13, v13
	s_nop 0
	v_add_f32_e32 v13, 1.0, v13
	v_rcp_f32_e32 v13, v13
	s_nop 0
	v_mul_f32_e32 v0, v13, v0
	v_mul_f32_e32 v0, v1, v0
	v_cvt_pk_bf16_f32 v0, v0, s0
	global_store_short v[8:9], v0, off offset:1056
	global_load_ushort v0, v[22:23], off offset:1952
	v_mul_f32_e32 v1, v29, v4
	v_mul_f32_e32 v1, v147, v1
	v_mov_b32_e32 v22, v16
	v_mov_b32_e32 v23, v14
	v_mov_b32_e32 v14, v17
	s_waitcnt vmcnt(0)
	v_lshlrev_b32_e32 v0, 16, v0
	v_mul_f32_e32 v13, 0xbfb8aa3b, v0
	v_exp_f32_e32 v13, v13
	s_nop 0
	v_add_f32_e32 v13, 1.0, v13
	v_rcp_f32_e32 v13, v13
	s_nop 0
	v_mul_f32_e32 v0, v13, v0
	v_mul_f32_e32 v0, v1, v0
	v_cvt_pk_bf16_f32 v0, v0, s0
	global_store_short v[8:9], v0, off offset:1088
	v_lshl_add_u64 v[0:1], v[20:21], 0, v[118:119]
	global_load_ushort v0, v[0:1], off offset:1888
	v_mul_f32_e32 v1, v5, v4
	v_mul_f32_e32 v1, v146, v1
	v_mov_b32_e32 v20, v42
	v_mov_b32_e32 v21, v40
	v_mov_b32_e32 v40, v43
	v_pk_add_f32 v[20:21], v[20:21], v[40:41]
	s_waitcnt vmcnt(0)
	v_lshlrev_b32_e32 v0, 16, v0
	v_mul_f32_e32 v4, 0xbfb8aa3b, v0
	v_exp_f32_e32 v4, v4
	v_pk_add_f32 v[20:21], v[20:21], v[22:23]
	v_add_f32_e32 v4, 1.0, v4
	v_rcp_f32_e32 v4, v4
	v_pk_add_f32 v[14:15], v[20:21], v[14:15]
	ds_swizzle_b32 v17, v15 offset:swizzle(SWAP,1)
	ds_swizzle_b32 v16, v14 offset:swizzle(SWAP,1)
	v_mul_f32_e32 v0, v4, v0
	v_mul_f32_e32 v0, v1, v0
	v_cvt_pk_bf16_f32 v4, v0, s0
	v_lshl_add_u64 v[0:1], v[18:19], 0, v[118:119]
	global_store_short v[0:1], v4, off offset:1024
	v_or_b32_e32 v0, 2, v12
	v_ashrrev_i32_e32 v1, 31, v0
	v_lshlrev_b64 v[4:5], 12, v[0:1]
	v_lshl_add_u64 v[4:5], s[58:59], 0, v[4:5]
	v_lshl_add_u64 v[8:9], v[4:5], 0, v[210:211]
	global_load_ushort v13, v[8:9], off offset:1888
	s_waitcnt lgkmcnt(0)
	v_pk_add_f32 v[14:15], v[14:15], v[16:17]
	ds_swizzle_b32 v17, v15 offset:swizzle(SWAP,2)
	ds_swizzle_b32 v16, v14 offset:swizzle(SWAP,2)
	v_lshlrev_b64 v[0:1], 11, v[0:1]
	v_lshl_add_u64 v[0:1], s[60:61], 0, v[0:1]
	v_lshl_add_u64 v[4:5], v[4:5], 0, v[118:119]
	s_waitcnt lgkmcnt(0)
	v_pk_add_f32 v[14:15], v[14:15], v[16:17]
	ds_swizzle_b32 v17, v15 offset:swizzle(SWAP,4)
	ds_swizzle_b32 v16, v14 offset:swizzle(SWAP,4)
	s_waitcnt lgkmcnt(0)
	v_pk_add_f32 v[14:15], v[14:15], v[16:17]
	ds_swizzle_b32 v17, v15 offset:swizzle(SWAP,8)
	ds_swizzle_b32 v16, v14 offset:swizzle(SWAP,8)
	s_waitcnt lgkmcnt(0)
	v_pk_add_f32 v[14:15], v[14:15], v[16:17]
	s_nop 0
	v_pk_fma_f32 v[14:15], v[14:15], s[6:7], v[120:121] op_sel_hi:[1,0,0]
	s_waitcnt vmcnt(0)
	v_lshlrev_b32_e32 v13, 16, v13
	v_mul_f32_e32 v18, 0xbfb8aa3b, v13
	v_exp_f32_e32 v18, v18
	v_mul_f32_e32 v16, 0x4b800000, v15
	v_cmp_gt_f32_e64 s[42:43], s96, v15
	v_cmp_gt_f32_e32 vcc, s96, v14
	v_add_f32_e32 v18, 1.0, v18
	v_cndmask_b32_e64 v15, v15, v16, s[42:43]
	v_rsq_f32_e32 v15, v15
	v_rcp_f32_e32 v18, v18
	v_mul_f32_e32 v16, 0x45800000, v15
	v_cndmask_b32_e64 v15, v15, v16, s[42:43]
	v_mul_f32_e32 v10, v10, v15
	v_mul_f32_e32 v13, v18, v13
	v_mul_f32_e32 v10, v149, v10
	v_mul_f32_e32 v10, v13, v10
	v_lshl_add_u64 v[18:19], v[0:1], 0, v[210:211]
	v_cvt_pk_bf16_f32 v10, v10, s0
	global_store_short v[18:19], v10, off offset:1024
	global_load_ushort v10, v[8:9], off offset:1920
	v_mul_f32_e32 v2, v2, v15
	v_mul_f32_e32 v2, v148, v2
	v_lshl_add_u64 v[0:1], v[0:1], 0, v[118:119]
	s_waitcnt vmcnt(0)
	v_lshlrev_b32_e32 v10, 16, v10
	v_mul_f32_e32 v13, 0xbfb8aa3b, v10
	v_exp_f32_e32 v13, v13
	s_nop 0
	v_add_f32_e32 v13, 1.0, v13
	v_rcp_f32_e32 v13, v13
	s_nop 0
	v_mul_f32_e32 v10, v13, v10
	v_mul_f32_e32 v2, v2, v10
	v_cvt_pk_bf16_f32 v2, v2, s0
	global_store_short v[18:19], v2, off offset:1056
	global_load_ushort v2, v[8:9], off offset:1952
	v_mul_f32_e32 v8, v30, v15
	v_mul_f32_e32 v8, v147, v8
	s_waitcnt vmcnt(0)
	v_lshlrev_b32_e32 v2, 16, v2
	v_mul_f32_e32 v9, 0xbfb8aa3b, v2
	v_exp_f32_e32 v9, v9
	s_nop 0
	v_add_f32_e32 v9, 1.0, v9
	v_rcp_f32_e32 v9, v9
	s_nop 0
	v_mul_f32_e32 v2, v9, v2
	v_mul_f32_e32 v2, v8, v2
	v_cvt_pk_bf16_f32 v2, v2, s0
	global_store_short v[18:19], v2, off offset:1088
	global_load_ushort v2, v[4:5], off offset:1888
	v_mul_f32_e32 v4, v6, v15
	v_mul_f32_e32 v4, v146, v4
	s_waitcnt vmcnt(0)
	v_lshlrev_b32_e32 v2, 16, v2
	v_mul_f32_e32 v5, 0xbfb8aa3b, v2
	v_exp_f32_e32 v5, v5
	s_nop 0
	v_add_f32_e32 v5, 1.0, v5
	v_rcp_f32_e32 v5, v5
	s_nop 0
	v_mul_f32_e32 v2, v5, v2
	v_mul_f32_e32 v2, v4, v2
	v_cvt_pk_bf16_f32 v2, v2, s0
	global_store_short v[0:1], v2, off offset:1024
	v_mul_f32_e32 v0, 0x4b800000, v14
	v_cndmask_b32_e32 v0, v14, v0, vcc
	v_rsq_f32_e32 v0, v0
	s_nop 0
	v_mul_f32_e32 v1, 0x45800000, v0
	v_cndmask_b32_e32 v6, v0, v1, vcc
	v_or_b32_e32 v0, 3, v12
	v_ashrrev_i32_e32 v1, 31, v0
	v_lshlrev_b64 v[4:5], 12, v[0:1]
	v_lshl_add_u64 v[4:5], s[58:59], 0, v[4:5]
	v_lshl_add_u64 v[8:9], v[4:5], 0, v[210:211]
	global_load_ushort v2, v[8:9], off offset:1888
	v_mul_f32_e32 v10, v11, v6
	v_lshlrev_b64 v[0:1], 11, v[0:1]
	v_mul_f32_e32 v10, v149, v10
	v_lshl_add_u64 v[0:1], s[60:61], 0, v[0:1]
	v_mul_f32_e32 v3, v3, v6
	v_mul_f32_e32 v3, v148, v3
	s_waitcnt vmcnt(0)
	v_lshlrev_b32_e32 v2, 16, v2
	v_mul_f32_e32 v11, 0xbfb8aa3b, v2
	v_exp_f32_e32 v11, v11
	s_nop 0
	v_add_f32_e32 v11, 1.0, v11
	v_rcp_f32_e32 v11, v11
	s_nop 0
	v_mul_f32_e32 v2, v11, v2
	v_mul_f32_e32 v2, v2, v10
	v_cvt_pk_bf16_f32 v2, v2, s0
	v_lshl_add_u64 v[10:11], v[0:1], 0, v[210:211]
	global_store_short v[10:11], v2, off offset:1024
	global_load_ushort v2, v[8:9], off offset:1920
	v_lshl_add_u64 v[0:1], v[0:1], 0, v[118:119]
	s_waitcnt vmcnt(0)
	v_lshlrev_b32_e32 v2, 16, v2
	v_mul_f32_e32 v12, 0xbfb8aa3b, v2
	v_exp_f32_e32 v12, v12
	s_nop 0
	v_add_f32_e32 v12, 1.0, v12
	v_rcp_f32_e32 v12, v12
	s_nop 0
	v_mul_f32_e32 v2, v12, v2
	v_mul_f32_e32 v2, v3, v2
	v_cvt_pk_bf16_f32 v2, v2, s0
	global_store_short v[10:11], v2, off offset:1056
	global_load_ushort v2, v[8:9], off offset:1952
	v_mul_f32_e32 v3, v31, v6
	v_mul_f32_e32 v3, v147, v3
	s_waitcnt vmcnt(0)
	v_lshlrev_b32_e32 v2, 16, v2
	v_mul_f32_e32 v8, 0xbfb8aa3b, v2
	v_exp_f32_e32 v8, v8
	s_nop 0
	v_add_f32_e32 v8, 1.0, v8
	v_rcp_f32_e32 v8, v8
	s_nop 0
	v_mul_f32_e32 v2, v8, v2
	v_mul_f32_e32 v2, v3, v2
	v_cvt_pk_bf16_f32 v2, v2, s0
	global_store_short v[10:11], v2, off offset:1088
	v_lshl_add_u64 v[2:3], v[4:5], 0, v[118:119]
	global_load_ushort v2, v[2:3], off offset:1888
	v_mul_f32_e32 v3, v7, v6
	v_mul_f32_e32 v3, v146, v3
	s_waitcnt vmcnt(0)
	v_lshlrev_b32_e32 v2, 16, v2
	v_mul_f32_e32 v4, 0xbfb8aa3b, v2
	v_exp_f32_e32 v4, v4
	s_nop 0
	v_add_f32_e32 v4, 1.0, v4
	v_rcp_f32_e32 v4, v4
	s_nop 0
	v_mul_f32_e32 v2, v4, v2
	v_mul_f32_e32 v2, v3, v2
	v_cvt_pk_bf16_f32 v2, v2, s0
	global_store_short v[0:1], v2, off offset:1024
	s_waitcnt lgkmcnt(0)

; __device__ __forceinline__ void chunk_load_vt(const bf16_t* proj, int t0, int vcol, unsigned char* wl, int lane) {
;     const bf16_t* vp = proj + (size_t)(t0 + lane) * DINP + vcol;
; #pragma unroll
;     for (int cidx = 0; cidx < 8; ++cidx) {
;         const u32x4 v = *(const u32x4*)(vp + cidx * 8);
;         const unsigned w4[4] = {v.x, v.y, v.z, v.w};
; #pragma unroll
;         for (int j = 0; j < 4; ++j) {
;             *(bf16_t*)(wl + (cidx * 8 + 2 * j) * GP + lane * 2) = (bf16_t)(w4[j] & 0xffffu);
;             *(bf16_t*)(wl + (cidx * 8 + 2 * j + 1) * GP + lane * 2) = (bf16_t)(w4[j] >> 16);
;         }
;     }
; }
; template <bool GLA>
; __device__ __forceinline__ void chunk_pass_c(const ChunkIn& ci, const float* wgl, int unit, unsigned char* wl, int lane, const float* Sb, const float* ng, bf16_t* omix) {
;     const int h = unit & 3, bn = unit >> 2, t0 = bn * 64;
;     const int row = lane & 15, kq = lane >> 4;
;     chunk_load_vt(ci.proj, t0, (GLA ? C_GV : C_RV) + h * 64, wl, lane);
;     unsigned char* sst = wl + 64 * GP;
;     { const float* sp = Sb + (size_t)unit * 2048 + lane;
;       float sv[32];
; #pragma unroll
;       for (int d = 0; d < 32; ++d) sv[d] = sp[d * 64];
.LBB0_215:
	v_mov_b32_e32 v0, v211
	v_readlane_b32 s3, v254, 60
	v_mbcnt_lo_u32_b32 v0, -1, v0
	s_waitcnt vmcnt(35)
	v_mbcnt_hi_u32_b32 v133, -1, v0
	v_and_b32_e32 v147, 63, v133
	v_lshrrev_b32_e32 v119, 4, v147
	s_mov_b64 s[6:7], -1
	s_cmpk_gt_i32 s25, 0x7ff
	v_and_b32_e32 v156, 15, v133
	v_lshlrev_b32_e32 v210, 2, v147
	v_lshl_add_u32 v158, v147, 1, s3
	v_lshl_add_u32 v157, v147, 6, s3
	v_lshlrev_b32_e32 v97, 2, v119
	v_lshlrev_b32_e32 v114, 3, v119
	s_cbranch_scc0 .LBB0_217
	s_load_dwordx2 s[4:5], s[0:1], 0x88
	s_mov_b32 s65, s17
	v_mov_b32_e32 v115, v211
	v_cmp_lt_u32_e64 s[42:43], v97, v156
	v_lshlrev_b32_e32 v110, 1, v156
	s_waitcnt lgkmcnt(0)
	s_add_u32 s48, s4, s56
	s_addc_u32 s49, s5, s57
	s_add_i32 s3, s90, 0xffff8000
	s_and_b32 s4, s3, 0x7fc0
	v_or_b32_e32 v0, s4, v147
	s_lshl_b64 s[4:5], s[64:65], 2
	s_add_u32 s4, s37, s4
	v_lshlrev_b32_e32 v28, 12, v0
	s_addc_u32 s5, s70, s5
	global_load_dwordx4 v[0:3], v28, s[58:59] offset:2912
	global_load_dwordx4 v[4:7], v28, s[58:59] offset:2928
	global_load_dwordx4 v[8:11], v28, s[58:59] offset:2944
	global_load_dwordx4 v[12:15], v28, s[58:59] offset:2960
	global_load_dwordx4 v[16:19], v28, s[58:59] offset:2976
	global_load_dwordx4 v[20:23], v28, s[58:59] offset:2992
	global_load_dwordx4 v[24:27], v28, s[58:59] offset:3008
	s_nop 0
	global_load_dwordx4 v[28:31], v28, s[58:59] offset:3024
	v_lshl_add_u64 v[32:33], s[4:5], 0, v[210:211]
	v_add_co_u32_e32 v32, vcc, s10, v32
	global_load_dword v34, v210, s[4:5]
	global_load_dword v35, v210, s[4:5] offset:256
	global_load_dword v36, v210, s[4:5] offset:512
	global_load_dword v37, v210, s[4:5] offset:768
	global_load_dword v38, v210, s[4:5] offset:1024
	global_load_dword v39, v210, s[4:5] offset:1280
	global_load_dword v40, v210, s[4:5] offset:1536
	global_load_dword v41, v210, s[4:5] offset:1792
	global_load_dword v42, v210, s[4:5] offset:2048
	global_load_dword v43, v210, s[4:5] offset:2304
	global_load_dword v44, v210, s[4:5] offset:2560
	global_load_dword v45, v210, s[4:5] offset:2816
	global_load_dword v46, v210, s[4:5] offset:3072
	global_load_dword v47, v210, s[4:5] offset:3328
	global_load_dword v48, v210, s[4:5] offset:3584
	global_load_dword v49, v210, s[4:5] offset:3840
	v_addc_co_u32_e32 v33, vcc, 0, v33, vcc
	global_load_dword v50, v[32:33], off
	global_load_dword v51, v[32:33], off offset:256
	global_load_dword v52, v[32:33], off offset:512
	global_load_dword v53, v[32:33], off offset:768
	global_load_dword v54, v[32:33], off offset:1024
	global_load_dword v55, v[32:33], off offset:1280
	global_load_dword v56, v[32:33], off offset:1536
	global_load_dword v57, v[32:33], off offset:1792
	global_load_dword v58, v[32:33], off offset:2048
	global_load_dword v59, v[32:33], off offset:2304
	global_load_dword v60, v[32:33], off offset:2560
	global_load_dword v61, v[32:33], off offset:2816
	global_load_dword v62, v[32:33], off offset:3072
	global_load_dword v63, v[32:33], off offset:3328
	global_load_dword v64, v[32:33], off offset:3584
	s_nop 0
	global_load_dword v32, v[32:33], off offset:3840
	s_and_b32 s6, s90, 0x7fc0
	v_readlane_b32 s4, v255, 14
	s_or_b32 s5, s6, 16
	s_or_b32 s3, s3, 48
	v_or_b32_e32 v165, s6, v97
	v_mov_b32_e32 v111, v211
	v_lshlrev_b32_e32 v159, 2, v156
	v_or_b32_e32 v177, 48, v147
	s_waitcnt vmcnt(39)
	ds_write_b16 v158, v0
	ds_write_b16_d16_hi v158, v0 offset:144
	ds_write_b16 v158, v1 offset:288
	ds_write_b16_d16_hi v158, v1 offset:432
	ds_write_b16 v158, v2 offset:576
	ds_write_b16_d16_hi v158, v2 offset:720
	ds_write_b16 v158, v3 offset:864
	ds_write_b16_d16_hi v158, v3 offset:1008
	s_waitcnt vmcnt(38)
	ds_write_b16 v158, v4 offset:1152
	ds_write_b16_d16_hi v158, v4 offset:1296
	ds_write_b16 v158, v5 offset:1440
	ds_write_b16_d16_hi v158, v5 offset:1584
	ds_write_b16 v158, v6 offset:1728
	ds_write_b16_d16_hi v158, v6 offset:1872
	ds_write_b16 v158, v7 offset:2016
	ds_write_b16_d16_hi v158, v7 offset:2160
	s_waitcnt vmcnt(37)
	ds_write_b16 v158, v8 offset:2304
	ds_write_b16_d16_hi v158, v8 offset:2448
	ds_write_b16 v158, v9 offset:2592
	ds_write_b16_d16_hi v158, v9 offset:2736
	ds_write_b16 v158, v10 offset:2880
	ds_write_b16_d16_hi v158, v10 offset:3024
	ds_write_b16 v158, v11 offset:3168
	ds_write_b16_d16_hi v158, v11 offset:3312
	s_waitcnt vmcnt(36)
	ds_write_b16 v158, v12 offset:3456
	ds_write_b16_d16_hi v158, v12 offset:3600
	ds_write_b16 v158, v13 offset:3744
	ds_write_b16_d16_hi v158, v13 offset:3888
	ds_write_b16 v158, v14 offset:4032
	ds_write_b16_d16_hi v158, v14 offset:4176
	ds_write_b16 v158, v15 offset:4320
	ds_write_b16_d16_hi v158, v15 offset:4464
	s_waitcnt vmcnt(35)
	ds_write_b16 v158, v16 offset:4608
	ds_write_b16_d16_hi v158, v16 offset:4752
	ds_write_b16 v158, v17 offset:4896
	ds_write_b16_d16_hi v158, v17 offset:5040
	ds_write_b16 v158, v18 offset:5184
	ds_write_b16_d16_hi v158, v18 offset:5328
	ds_write_b16 v158, v19 offset:5472
	ds_write_b16_d16_hi v158, v19 offset:5616
	s_waitcnt vmcnt(34)
	ds_write_b16 v158, v20 offset:5760
	ds_write_b16_d16_hi v158, v20 offset:5904
	ds_write_b16 v158, v21 offset:6048
	ds_write_b16_d16_hi v158, v21 offset:6192
	ds_write_b16 v158, v22 offset:6336
	ds_write_b16_d16_hi v158, v22 offset:6480
	ds_write_b16 v158, v23 offset:6624
	ds_write_b16_d16_hi v158, v23 offset:6768
	s_waitcnt vmcnt(33)
	ds_write_b16 v158, v24 offset:6912
	ds_write_b16_d16_hi v158, v24 offset:7056
	ds_write_b16 v158, v25 offset:7200
	ds_write_b16_d16_hi v158, v25 offset:7344
	ds_write_b16 v158, v26 offset:7488
	ds_write_b16_d16_hi v158, v26 offset:7632
	ds_write_b16 v158, v27 offset:7776
	ds_write_b16_d16_hi v158, v27 offset:7920
	s_waitcnt vmcnt(32)
; __device__ __forceinline__ unsigned cvtpk(float lo, float hi) { f32x2_t v = {lo, hi}; bf16x2_t b = __builtin_convertvector(v, bf16x2_t); return __builtin_bit_cast(unsigned, b); }
; template <bool GLA>
; __device__ __forceinline__ void chunk_load(const ChunkIn& ci, int t, int h, int kq, ChunkRaw& r) {
;     const bf16_t* pr = ci.proj + (size_t)t * DINP;
;     const int cq = GLA ? C_GQ : C_RQ, ck = GLA ? C_GK : C_RK;
;     r.qa = *(const u32x2*)(pr + cq + h * 32 + 4 * kq); r.qb = *(const u32x2*)(pr + cq + h * 32 + 16 + 4 * kq);
;     r.ka = *(const u32x2*)(pr + ck + h * 32 + 4 * kq); r.kb = *(const u32x2*)(pr + ck + h * 32 + 16 + 4 * kq);
;     if (GLA) { r.g0 = *(const u32x4*)(pr + C_GG); r.g1 = *(const u32x4*)(pr + C_GG + 8); }
;     ...
; }
; __device__ __forceinline__ void chunk_load_vt(const bf16_t* proj, int t0, int vcol, unsigned char* wl, int lane) {
;     ...
;             *(bf16_t*)(wl + (cidx * 8 + 2 * j) * GP + lane * 2) = (bf16_t)(w4[j] & 0xffffu);
;             *(bf16_t*)(wl + (cidx * 8 + 2 * j + 1) * GP + lane * 2) = (bf16_t)(w4[j] >> 16);
;         }
;     }
; }
; template <bool GLA>
; __device__ __forceinline__ void chunk_pass_a(const ChunkIn& ci, const float* wgl, int unit, unsigned char* wl, int lane, float* dS, float* dec) {
;     ...
;     const float lg = GLA ? 0.f : __logf(1.0f - __builtin_amdgcn_exp2f(-5.0f - hf));
; template <bool GLA>
; __device__ __forceinline__ void chunk_pass_c(const ChunkIn& ci, const float* wgl, int unit, unsigned char* wl, int lane, const float* Sb, const float* ng, bf16_t* omix) {
;     ...
;       for (int q4 = 0; q4 < 4; ++q4) {
;           u32x4 w; w.x = cvtpk(sv[4 * q4 + 0], sv[4 * q4 + 1]); w.y = cvtpk(sv[4 * q4 + 2], sv[4 * q4 + 3]); w.z = cvtpk(sv[16 + 4 * q4 + 0], sv[16 + 4 * q4 + 1]); w.w = cvtpk(sv[16 + 4 * q4 + 2], sv[16 + 4 * q4 + 3]);
;           *(u32x4*)(sst + lane * 64 + q4 * 16) = w;
;       } }
	ds_write_b16 v158, v28 offset:8064
	ds_write_b16_d16_hi v158, v28 offset:8208
	ds_write_b16 v158, v29 offset:8352
	ds_write_b16_d16_hi v158, v29 offset:8496
	ds_write_b16 v158, v30 offset:8640
	ds_write_b16_d16_hi v158, v30 offset:8784
	ds_write_b16 v158, v31 offset:8928
	ds_write_b16_d16_hi v158, v31 offset:9072
	s_waitcnt vmcnt(30)
	v_cvt_pk_bf16_f32 v0, v34, v35
	s_waitcnt vmcnt(28)
	v_cvt_pk_bf16_f32 v1, v36, v37
	s_waitcnt vmcnt(14)
	v_cvt_pk_bf16_f32 v2, v50, v51
	s_waitcnt vmcnt(12)
	v_cvt_pk_bf16_f32 v3, v52, v53
	ds_write_b128 v157, v[0:3] offset:9216
	v_cvt_pk_bf16_f32 v0, v38, v39
	v_cvt_pk_bf16_f32 v1, v40, v41
	s_waitcnt vmcnt(10)
	v_cvt_pk_bf16_f32 v2, v54, v55
	s_waitcnt vmcnt(8)
	v_cvt_pk_bf16_f32 v3, v56, v57
	ds_write_b128 v157, v[0:3] offset:9232
	v_cvt_pk_bf16_f32 v0, v42, v43
	v_cvt_pk_bf16_f32 v1, v44, v45
	s_waitcnt vmcnt(6)
	v_cvt_pk_bf16_f32 v2, v58, v59
	s_waitcnt vmcnt(4)
	v_cvt_pk_bf16_f32 v3, v60, v61
	ds_write_b128 v157, v[0:3] offset:9248
	v_cvt_pk_bf16_f32 v0, v46, v47
	v_cvt_pk_bf16_f32 v1, v48, v49
	s_waitcnt vmcnt(2)
	v_cvt_pk_bf16_f32 v2, v62, v63
	s_waitcnt vmcnt(0)
	v_cvt_pk_bf16_f32 v3, v64, v32
	v_or_b32_e32 v6, s6, v156
	ds_write_b128 v157, v[0:3] offset:9264
	v_and_b32_e32 v0, 48, v147
	v_mov_b32_e32 v1, v211
	v_lshlrev_b32_e32 v4, 12, v6
	v_mov_b32_e32 v5, v211
	v_lshl_add_u64 v[2:3], s[22:23], 0, v[0:1]
	v_lshl_add_u64 v[4:5], s[62:63], 0, v[4:5]
	v_lshlrev_b32_e32 v6, 6, v6
	v_mov_b32_e32 v7, v211
	v_lshl_add_u64 v[0:1], s[20:21], 0, v[0:1]
	v_lshl_add_u64 v[4:5], v[4:5], 0, v[114:115]
	v_lshl_add_u64 v[8:9], v[2:3], 0, v[6:7]
	global_load_dwordx2 v[24:25], v[4:5], off offset:2400
	global_load_dwordx2 v[26:27], v[4:5], off offset:2432
	v_lshl_add_u64 v[6:7], v[0:1], 0, v[6:7]
	global_load_dwordx4 v[8:11], v[8:9], off
	s_nop 0
	global_load_dwordx4 v[16:19], v[6:7], off
	global_load_dwordx2 v[32:33], v[4:5], off offset:2656
	global_load_dwordx2 v[34:35], v[4:5], off offset:2688
	v_cvt_f32_i32_e32 v12, s4
	v_mov_b32_e32 v5, v211
	s_or_b32 s4, s6, 32
	s_mov_b32 s6, 0x358637bd
	v_sub_f32_e32 v6, 0xc0a00000, v12
	v_exp_f32_e32 v6, v6
	s_waitcnt vmcnt(5)
	v_lshlrev_b32_e32 v40, 16, v24
	v_sub_f32_e32 v36, 1.0, v6
	v_or_b32_e32 v6, s5, v156
	v_lshlrev_b32_e32 v4, 12, v6
	v_lshl_add_u64 v[4:5], s[62:63], 0, v[4:5]
	v_lshl_add_u64 v[4:5], v[4:5], 0, v[114:115]
	global_load_dwordx2 v[144:145], v[4:5], off offset:2400
	global_load_dwordx2 v[142:143], v[4:5], off offset:2432
	global_load_dwordx2 v[30:31], v[4:5], off offset:2656
	global_load_dwordx2 v[28:29], v[4:5], off offset:2688
	v_lshlrev_b32_e32 v4, 6, v6
	v_mov_b32_e32 v5, v211
	v_lshl_add_u64 v[6:7], v[2:3], 0, v[4:5]
	v_lshl_add_u64 v[4:5], v[0:1], 0, v[4:5]
	global_load_dwordx4 v[76:79], v[6:7], off
	global_load_dwordx4 v[80:83], v[4:5], off
	v_or_b32_e32 v6, s4, v156
	v_lshlrev_b32_e32 v4, 12, v6
	v_mov_b32_e32 v5, v211
	v_lshl_add_u64 v[4:5], s[62:63], 0, v[4:5]
	v_lshl_add_u64 v[4:5], v[4:5], 0, v[114:115]
	global_load_dwordx2 v[130:131], v[4:5], off offset:2400
	global_load_dwordx2 v[128:129], v[4:5], off offset:2432
	global_load_dwordx2 v[22:23], v[4:5], off offset:2656
	global_load_dwordx2 v[20:21], v[4:5], off offset:2688
	v_lshlrev_b32_e32 v4, 6, v6
	v_mov_b32_e32 v5, v211
	v_lshl_add_u64 v[6:7], v[2:3], 0, v[4:5]
	v_lshl_add_u64 v[4:5], v[0:1], 0, v[4:5]
	global_load_dwordx4 v[64:67], v[6:7], off
	global_load_dwordx4 v[68:71], v[4:5], off
	v_or_b32_e32 v4, s3, v156
	v_mov_b32_e32 v5, v211
	v_lshlrev_b64 v[6:7], 12, v[4:5]
	v_lshl_add_u64 v[6:7], s[62:63], 0, v[6:7]
	v_cmp_gt_f32_e32 vcc, s96, v36
	v_lshl_add_u64 v[6:7], v[6:7], 0, v[114:115]
	s_and_b64 s[8:9], vcc, exec
	global_load_dwordx2 v[108:109], v[6:7], off offset:2400
	global_load_dwordx2 v[106:107], v[6:7], off offset:2432
	global_load_dwordx2 v[14:15], v[6:7], off offset:2656
	global_load_dwordx2 v[12:13], v[6:7], off offset:2688
	v_lshlrev_b64 v[4:5], 6, v[4:5]
	s_cselect_b32 s7, 32, 0
	v_lshl_add_u64 v[2:3], v[2:3], 0, v[4:5]
	v_ldexp_f32 v6, v36, s7
	v_lshl_add_u64 v[4:5], v[0:1], 0, v[4:5]
	v_log_f32_e32 v36, v6
	global_load_dwordx4 v[0:3], v[2:3], off
	s_nop 0
	global_load_dwordx4 v[4:7], v[4:5], off
	s_mov_b32 s7, 0x3f317217
	v_cndmask_b32_e32 v37, 0, v237, vcc
	v_mul_f32_e32 v38, 0x3f317217, v36
	v_fma_f32 v38, v36, s7, -v38
	v_fmac_f32_e32 v38, 0x3377d1cf, v36
	s_mov_b32 s7, 0x7f800000
	v_fmac_f32_e32 v38, 0x3f317217, v36
	v_cmp_lt_f32_e64 vcc, |v36|, s7
	v_and_b32_e32 v41, 0xffff0000, v24
	s_waitcnt vmcnt(18)
; __device__ __forceinline__ unsigned cvtpk(float lo, float hi) { f32x2_t v = {lo, hi}; bf16x2_t b = __builtin_convertvector(v, bf16x2_t); return __builtin_bit_cast(unsigned, b); }
; template <bool GLA>
; __device__ __forceinline__ void chunk_tile(const ChunkRaw& raw, const bf16x8 (&wfr)[2], const f32x4 (&bfr)[2], int h, int it, int row, int kq, float lg, float (&carry)[8], float (&bq)[8], float (&qv)[8], float (&kv)[8]) {
;     ...
; #pragma unroll
;         for (int j = 0; j < 4; ++j) {
;             qv[j] = (q[j] * cc[j] - q[4 + j] * ss[j]) * qs; qv[4 + j] = (q[j] * ss[j] + q[4 + j] * cc[j]) * qs;
;             kv[j] = k[j] * cc[j] - k[4 + j] * ss[j];        kv[4 + j] = k[j] * ss[j] + k[4 + j] * cc[j];
;         }
; #pragma unroll
;         for (int j = 0; j < 8; ++j) { bq[j] = (float)(16 * it + row + 1) * lg; carry[j] = 64.0f * lg; }
; template <bool GLA>
; __device__ __forceinline__ void chunk_pass_c(const ChunkIn& ci, const float* wgl, int unit, unsigned char* wl, int lane, const float* Sb, const float* ng, bf16_t* omix) {
;     ...
;         float a[8], bneg[8], cpos[8], dneg[8];
; #pragma unroll
;         for (int j = 0; j < 8; ++j) { const float eb = __expf(bq[j]), enb = __expf(-bq[j]); a[j] = qv[j] * eb; bneg[j] = kv[j] * enb; cpos[j] = qv[j] * enb; dneg[j] = kv[j] * eb; }
;         qf[it] = __builtin_bit_cast(bf16x8, (u32x4){cvtpk(a[0], a[1]), cvtpk(a[2], a[3]), cvtpk(a[4], a[5]), cvtpk(a[6], a[7])});
;         kf[it] = __builtin_bit_cast(bf16x8, (u32x4){cvtpk(bneg[0], bneg[1]), cvtpk(bneg[2], bneg[3]), cvtpk(bneg[4], bneg[5]), cvtpk(bneg[6], bneg[7])});
;         qb[it] = __builtin_bit_cast(bf16x8, (u32x4){cvtpk(cpos[0], cpos[1]), cvtpk(cpos[2], cpos[3]), cvtpk(cpos[4], cpos[5]), cvtpk(cpos[6], cpos[7])});
;         kb[it] = __builtin_bit_cast(bf16x8, (u32x4){cvtpk(dneg[0], dneg[1]), cvtpk(dneg[2], dneg[3]), cvtpk(dneg[4], dneg[5]), cvtpk(dneg[6], dneg[7])});
	v_lshlrev_b32_e32 v50, 16, v34
	v_cndmask_b32_e32 v36, v36, v38, vcc
	v_sub_f32_e32 v39, v36, v37
	v_add_u32_e32 v36, 1, v156
	v_cvt_f32_ubyte0_e32 v36, v36
	v_mul_f32_e32 v37, v39, v36
	v_mul_f32_e32 v36, 0x3fb8aa3b, v37
	v_mul_f32_e32 v37, 0xbfb8aa3b, v37
	v_exp_f32_e32 v36, v36
	v_exp_f32_e32 v38, v37
	v_and_b32_e32 v51, 0xffff0000, v34
	v_lshlrev_b32_e32 v42, 16, v26
	v_and_b32_e32 v43, 0xffff0000, v26
	v_pk_mul_f32 v[44:45], v[16:17], v[40:41]
	v_lshlrev_b32_e32 v48, 16, v32
	v_and_b32_e32 v49, 0xffff0000, v32
	v_pk_mul_f32 v[52:53], v[8:9], v[50:51]
	v_pk_fma_f32 v[44:45], v[8:9], v[42:43], v[44:45]
	v_pk_mul_f32 v[42:43], v[16:17], v[42:43]
	v_pk_fma_f32 v[52:53], v[16:17], v[48:49], v[52:53]
	v_pk_mul_f32 v[16:17], v[16:17], v[50:51]
	v_pk_fma_f32 v[40:41], v[8:9], v[40:41], v[42:43] neg_lo:[0,0,1] neg_hi:[0,0,1]
	v_pk_fma_f32 v[8:9], v[8:9], v[48:49], v[16:17] neg_lo:[0,0,1] neg_hi:[0,0,1]
	v_lshlrev_b32_e32 v24, 16, v27
	v_pk_mul_f32 v[16:17], v[38:39], v[8:9] op_sel_hi:[0,1]
	v_pk_mul_f32 v[48:49], v[36:37], v[8:9] op_sel_hi:[0,1]
	v_lshlrev_b32_e32 v8, 16, v25
	v_and_b32_e32 v9, 0xffff0000, v25
	v_and_b32_e32 v25, 0xffff0000, v27
	v_pk_mul_f32 v[26:27], v[18:19], v[8:9]
	v_lshlrev_b32_e32 v34, 16, v35
	v_and_b32_e32 v35, 0xffff0000, v35
	v_pk_fma_f32 v[26:27], v[10:11], v[24:25], v[26:27]
	v_pk_mul_f32 v[24:25], v[18:19], v[24:25]
	v_lshlrev_b32_e32 v32, 16, v33
	v_and_b32_e32 v33, 0xffff0000, v33
	v_pk_mul_f32 v[56:57], v[10:11], v[34:35]
	s_mov_b32 s8, 0x3e3504f3
	v_pk_fma_f32 v[8:9], v[10:11], v[8:9], v[24:25] neg_lo:[0,0,1] neg_hi:[0,0,1]
	v_pk_fma_f32 v[56:57], v[18:19], v[32:33], v[56:57]
	v_pk_mul_f32 v[18:19], v[18:19], v[34:35]
	v_pk_mul_f32 v[8:9], v[8:9], s[8:9] op_sel_hi:[1,0]
	v_pk_fma_f32 v[10:11], v[10:11], v[32:33], v[18:19] neg_lo:[0,0,1] neg_hi:[0,0,1]
	v_pk_mul_f32 v[24:25], v[36:37], v[8:9] op_sel_hi:[0,1]
	v_pk_mul_f32 v[32:33], v[36:37], v[10:11] op_sel_hi:[0,1]
	v_cvt_pk_bf16_f32 v89, v24, v25
	v_cvt_pk_bf16_f32 v25, v32, v33
	v_add_u32_e32 v32, 17, v156
	v_cvt_f32_ubyte0_e32 v32, v32
	v_mul_f32_e32 v164, v39, v32
	v_pk_mul_f32 v[44:45], v[44:45], s[8:9] op_sel_hi:[1,0]
	v_pk_mul_f32 v[40:41], v[40:41], s[8:9] op_sel_hi:[1,0]
	v_pk_mul_f32 v[26:27], v[26:27], s[8:9] op_sel_hi:[1,0]
	v_pk_mul_f32 v[34:35], v[38:39], v[56:57] op_sel_hi:[0,1]
	v_mul_f32_e32 v32, 0x3fb8aa3b, v164
	v_pk_mul_f32 v[42:43], v[36:37], v[40:41] op_sel_hi:[0,1]
	v_pk_mul_f32 v[46:47], v[36:37], v[44:45] op_sel_hi:[0,1]
	v_pk_mul_f32 v[50:51], v[38:39], v[52:53] op_sel_hi:[0,1]
	v_pk_mul_f32 v[52:53], v[36:37], v[52:53] op_sel_hi:[0,1]
	v_pk_mul_f32 v[54:55], v[38:39], v[8:9] op_sel_hi:[0,1]
	v_pk_mul_f32 v[8:9], v[36:37], v[26:27] op_sel_hi:[0,1]
	v_pk_mul_f32 v[26:27], v[38:39], v[26:27] op_sel_hi:[0,1]
	v_pk_mul_f32 v[18:19], v[38:39], v[10:11] op_sel_hi:[0,1]
	v_pk_mul_f32 v[36:37], v[36:37], v[56:57] op_sel_hi:[0,1]
	v_cvt_pk_bf16_f32 v11, v34, v35
	v_exp_f32_e32 v146, v32
	s_waitcnt vmcnt(14)
	v_lshlrev_b32_e32 v34, 16, v28
	v_and_b32_e32 v35, 0xffff0000, v28
	v_cvt_pk_bf16_f32 v91, v8, v9
	v_cvt_pk_bf16_f32 v9, v18, v19
	v_cvt_pk_bf16_f32 v19, v26, v27
	v_cvt_pk_bf16_f32 v27, v36, v37
	v_lshlrev_b32_e32 v32, 16, v30
	v_and_b32_e32 v33, 0xffff0000, v30
	s_waitcnt vmcnt(13)
	v_pk_mul_f32 v[36:37], v[76:77], v[34:35]
	v_lshlrev_b32_e32 v28, 16, v29
	v_and_b32_e32 v29, 0xffff0000, v29
	s_waitcnt vmcnt(12)
	v_pk_fma_f32 v[148:149], v[80:81], v[32:33], v[36:37]
	v_lshlrev_b32_e32 v30, 16, v31
	v_and_b32_e32 v31, 0xffff0000, v31
	v_pk_mul_f32 v[36:37], v[78:79], v[28:29]
	v_pk_mul_f32 v[28:29], v[82:83], v[28:29]
	v_pk_mul_f32 v[34:35], v[80:81], v[34:35]
	v_pk_fma_f32 v[154:155], v[78:79], v[30:31], v[28:29] neg_lo:[0,0,1] neg_hi:[0,0,1]
	v_pk_fma_f32 v[152:153], v[82:83], v[30:31], v[36:37]
	v_pk_mul_f32 v[28:29], v[146:147], v[154:155] op_sel_hi:[0,1]
	v_cvt_pk_bf16_f32 v85, v28, v29
	v_add_u32_e32 v28, 33, v156
	v_cvt_f32_ubyte0_e32 v28, v28
	v_mul_f32_e32 v163, v39, v28
	v_pk_fma_f32 v[150:151], v[76:77], v[32:33], v[34:35] neg_lo:[0,0,1] neg_hi:[0,0,1]
	v_pk_mul_f32 v[30:31], v[146:147], v[152:153] op_sel_hi:[0,1]
	v_mul_f32_e32 v28, 0x3fb8aa3b, v163
	v_pk_mul_f32 v[32:33], v[146:147], v[150:151] op_sel_hi:[0,1]
	v_cvt_pk_bf16_f32 v87, v30, v31
	v_exp_f32_e32 v132, v28
	s_waitcnt vmcnt(8)
	v_lshlrev_b32_e32 v30, 16, v20
	v_and_b32_e32 v31, 0xffff0000, v20
	v_cvt_pk_bf16_f32 v84, v32, v33
	v_lshlrev_b32_e32 v28, 16, v22
	v_and_b32_e32 v29, 0xffff0000, v22
	s_waitcnt vmcnt(7)
	v_pk_mul_f32 v[32:33], v[64:65], v[30:31]
	v_lshlrev_b32_e32 v20, 16, v21
	v_and_b32_e32 v21, 0xffff0000, v21
	s_waitcnt vmcnt(6)
	v_pk_fma_f32 v[134:135], v[68:69], v[28:29], v[32:33]
	v_lshlrev_b32_e32 v22, 16, v23
	v_and_b32_e32 v23, 0xffff0000, v23
	v_pk_mul_f32 v[32:33], v[66:67], v[20:21]
	v_pk_mul_f32 v[20:21], v[70:71], v[20:21]
	v_cvt_pk_bf16_f32 v8, v16, v17
	v_pk_fma_f32 v[140:141], v[66:67], v[22:23], v[20:21] neg_lo:[0,0,1] neg_hi:[0,0,1]
	v_cvt_pk_bf16_f32 v10, v50, v51
	v_pk_mul_f32 v[20:21], v[132:133], v[140:141] op_sel_hi:[0,1]
	v_cvt_pk_bf16_f32 v73, v20, v21
	v_add_u32_e32 v20, 49, v156
	v_cvt_pk_bf16_f32 v24, v48, v49
	v_cvt_pk_bf16_f32 v26, v52, v53
	v_cvt_f32_ubyte0_e32 v20, v20
	v_pk_mul_f32 v[30:31], v[68:69], v[30:31]
	v_pk_fma_f32 v[138:139], v[70:71], v[22:23], v[32:33]
	v_mul_f32_e32 v162, v39, v20
	v_pk_fma_f32 v[136:137], v[64:65], v[28:29], v[30:31] neg_lo:[0,0,1] neg_hi:[0,0,1]
	v_pk_mul_f32 v[22:23], v[132:133], v[138:139] op_sel_hi:[0,1]
	v_mul_f32_e32 v20, 0x3fb8aa3b, v162
	v_pk_mul_f32 v[40:41], v[38:39], v[40:41] op_sel_hi:[0,1]
	v_pk_mul_f32 v[44:45], v[38:39], v[44:45] op_sel_hi:[0,1]
	v_pk_mul_f32 v[34:35], v[146:147], v[148:149] op_sel_hi:[0,1]
	v_pk_mul_f32 v[28:29], v[132:133], v[136:137] op_sel_hi:[0,1]
	v_cvt_pk_bf16_f32 v75, v22, v23
	v_exp_f32_e32 v118, v20
	s_waitcnt vmcnt(2)
; template <bool GLA>
; __device__ __forceinline__ void chunk_pass_c(const ChunkIn& ci, const float* wgl, int unit, unsigned char* wl, int lane, const float* Sb, const float* ng, bf16_t* omix) {
;     ...
;     __builtin_amdgcn_s_waitcnt(0); asm volatile("" ::: "memory");
;     bf16x8 vfr[4][2], sfr[4];
; #pragma unroll
;     for (int et = 0; et < 4; ++et) {
; #pragma unroll
;         for (int p = 0; p < 2; ++p) {
;             const u32x2 lo = *(const u32x2*)(wl + (16 * et + row) * GP + (32 * p + 4 * kq) * 2), hh = *(const u32x2*)(wl + (16 * et + row) * GP + (32 * p + 16 + 4 * kq) * 2);
;             vfr[et][p] = __builtin_bit_cast(bf16x8, (u32x4){lo.x, lo.y, hh.x, hh.y});
;         }
;         sfr[et] = *(const bf16x8*)(sst + (16 * et + row) * 64 + kq * 16);
;     }
;     const int gcol = (GLA ? C_GR : C_RG) + h * 64, ocol = (GLA ? 512 : 768) + h * 64;
;     float gn[4];
; #pragma unroll
;     for (int et = 0; et < 4; ++et) gn[et] = ng[16 * et + row];
; #pragma unroll
;     for (int it = 0; it < 4; ++it) {
;         f32x4 st[4];
; #pragma unroll
;         for (int jt = 0; jt < 4; ++jt) {
;             const f32x4 z = {0.f, 0.f, 0.f, 0.f};
;             if (jt < it) st[jt] = __builtin_amdgcn_mfma_f32_16x16x32_bf16(kf[jt], qf[it], z, 0, 0, 0);
;             else if (jt > it) st[jt] = __builtin_amdgcn_mfma_f32_16x16x32_bf16(kb[jt], qb[it], z, 0, 0, 0);
;             else {
;                 const f32x4 lo = __builtin_amdgcn_mfma_f32_16x16x32_bf16(kf[jt], qf[it], z, 0, 0, 0), up = __builtin_amdgcn_mfma_f32_16x16x32_bf16(kb[jt], qb[it], z, 0, 0, 0);
; #pragma unroll
;                 for (int r = 0; r < 4; ++r) st[jt][r] = (4 * kq + r <= row) ? lo[r] : up[r];
;             }
;         }
;         bf16x8 af[2];
; #pragma unroll
;         for (int p = 0; p < 2; ++p)
;             af[p] = __builtin_bit_cast(bf16x8, (u32x4){cvtpk(st[2 * p][0], st[2 * p][1]), cvtpk(st[2 * p][2], st[2 * p][3]), cvtpk(st[2 * p + 1][0], st[2 * p + 1][1]), cvtpk(st[2 * p + 1][2], st[2 * p + 1][3])});
;         f32x4 o[4]; float ss[4] = {0.f, 0.f, 0.f, 0.f};
; #pragma unroll
;         for (int et = 0; et < 4; ++et) {
;             f32x4 acc = {0.f, 0.f, 0.f, 0.f};
;             acc = __builtin_amdgcn_mfma_f32_16x16x32_bf16(af[0], vfr[et][0], acc, 0, 0, 0);
;             acc = __builtin_amdgcn_mfma_f32_16x16x32_bf16(af[1], vfr[et][1], acc, 0, 0, 0);
	v_lshlrev_b32_e32 v22, 16, v12
	v_and_b32_e32 v23, 0xffff0000, v12
	v_cvt_pk_bf16_f32 v88, v42, v43
	v_cvt_pk_bf16_f32 v90, v46, v47
	v_cvt_pk_bf16_f32 v16, v40, v41
	v_cvt_pk_bf16_f32 v17, v54, v55
	v_cvt_pk_bf16_f32 v18, v44, v45
	v_cvt_pk_bf16_f32 v86, v34, v35
	v_cvt_pk_bf16_f32 v72, v28, v29
	v_lshlrev_b32_e32 v20, 16, v14
	v_and_b32_e32 v21, 0xffff0000, v14
	s_waitcnt vmcnt(1)
	v_pk_mul_f32 v[28:29], v[0:1], v[22:23]
	v_lshlrev_b32_e32 v12, 16, v13
	v_and_b32_e32 v13, 0xffff0000, v13
	s_waitcnt vmcnt(0)
	v_pk_fma_f32 v[120:121], v[4:5], v[20:21], v[28:29]
	v_pk_mul_f32 v[22:23], v[4:5], v[22:23]
	v_lshlrev_b32_e32 v14, 16, v15
	v_and_b32_e32 v15, 0xffff0000, v15
	v_pk_mul_f32 v[28:29], v[2:3], v[12:13]
	v_pk_mul_f32 v[12:13], v[6:7], v[12:13]
	v_mfma_f32_16x16x32_bf16 v[32:35], v[8:11], v[88:91], 0
	v_fma_f32 v122, v0, v20, -v22
	v_fma_f32 v123, v1, v21, -v23
	v_pk_fma_f32 v[124:125], v[6:7], v[14:15], v[28:29]
	v_pk_fma_f32 v[126:127], v[2:3], v[14:15], v[12:13] neg_lo:[0,0,1] neg_hi:[0,0,1]
	v_mfma_f32_16x16x32_bf16 v[24:27], v[24:27], v[16:19], 0
	v_mul_f32_e64 v30, v132, v134
	v_mul_f32_e64 v31, v132, v135
	v_pk_mul_f32 v[20:21], v[118:119], v[122:123] op_sel_hi:[0,1]
	v_pk_mul_f32 v[22:23], v[118:119], v[120:121] op_sel_hi:[0,1]
	v_pk_mul_f32 v[14:15], v[118:119], v[126:127] op_sel_hi:[0,1]
	v_pk_mul_f32 v[28:29], v[118:119], v[124:125] op_sel_hi:[0,1]
	v_cvt_pk_bf16_f32 v74, v30, v31
	v_cvt_pk_bf16_f32 v12, v20, v21
	v_cvt_pk_bf16_f32 v13, v14, v15
	v_cvt_pk_bf16_f32 v14, v22, v23
	v_cvt_pk_bf16_f32 v15, v28, v29
	v_cmp_gt_u32_e32 vcc, v97, v156
	v_mfma_f32_16x16x32_bf16 v[36:39], v[84:87], v[16:19], 0
	v_mul_u32_u24_e32 v20, 0x90, v156
	v_cndmask_b32_e32 v24, v32, v24, vcc
	v_or_b32_e32 v32, 2, v97
	v_cmp_gt_u32_e64 s[44:45], v32, v156
	v_or_b32_e32 v32, 3, v97
	v_cmp_gt_u32_e64 s[46:47], v32, v156
	v_readlane_b32 s7, v254, 60
	v_cndmask_b32_e64 v25, v25, v33, s[42:43]
	v_cndmask_b32_e64 v26, v34, v26, s[44:45]
	v_cndmask_b32_e64 v27, v35, v27, s[46:47]
	s_waitcnt vmcnt(0) expcnt(0) lgkmcnt(0)
	v_add3_u32 v48, s7, v20, v114
	v_mfma_f32_16x16x32_bf16 v[40:43], v[72:75], v[16:19], 0
	v_cvt_pk_bf16_f32 v166, v24, v25
	v_cvt_pk_bf16_f32 v167, v26, v27
	v_cvt_pk_bf16_f32 v168, v36, v37
	v_mfma_f32_16x16x32_bf16 v[16:19], v[12:15], v[16:19], 0
	v_cvt_pk_bf16_f32 v169, v38, v39
	ds_read2_b64 v[28:31], v48 offset1:4
	ds_read2_b64 v[20:23], v48 offset0:8 offset1:12
	s_nop 0
	v_cvt_pk_bf16_f32 v170, v40, v41
	v_cvt_pk_bf16_f32 v171, v42, v43
	s_nop 1
	v_cvt_pk_bf16_f32 v172, v16, v17
	v_cvt_pk_bf16_f32 v173, v18, v19
	s_waitcnt lgkmcnt(1)
	v_mfma_f32_16x16x32_bf16 v[16:19], v[166:169], v[28:31], 0
	v_lshlrev_b32_e32 v24, 6, v156
	v_and_b32_e32 v25, 48, v133
	v_add3_u32 v60, s7, v25, v24
	ds_read_b128 v[24:27], v60 offset:9216
	s_waitcnt lgkmcnt(1)
	v_mfma_f32_16x16x32_bf16 v[32:35], v[170:173], v[20:23], v[16:19]
	v_add_u32_e32 v40, 0x800, v48
	ds_read2_b64 v[44:47], v40 offset0:32 offset1:36
	v_mov_b32_e32 v41, v211
	ds_read_b128 v[16:19], v60 offset:10240
	s_waitcnt lgkmcnt(2)
	v_mfma_f32_16x16x32_bf16 v[92:95], v[88:91], v[24:27], v[32:35]
	s_nop 2
	ds_read2_b64 v[32:35], v40 offset0:40 offset1:44
	v_lshlrev_b32_e32 v40, 12, v165
	v_lshl_add_u64 v[174:175], s[58:59], 0, v[40:41]
	v_lshl_add_u64 v[112:113], v[174:175], 0, v[110:111]
	global_load_ushort v176, v[112:113], off offset:3424
	s_waitcnt lgkmcnt(2)
	v_mfma_f32_16x16x32_bf16 v[36:39], v[166:169], v[44:47], 0
	v_add_u32_e32 v40, 0x1000, v48
	v_mov_b32_e32 v160, v93
	s_waitcnt lgkmcnt(0)
	v_mfma_f32_16x16x32_bf16 v[36:39], v[170:173], v[32:35], v[36:39]
	v_mfma_f32_16x16x32_bf16 v[102:105], v[88:91], v[16:19], v[36:39]
	ds_read2_b64 v[56:59], v40 offset0:64 offset1:68
	ds_read2_b64 v[52:55], v40 offset0:72 offset1:76
	s_nop 4
	ds_read_b128 v[36:39], v60 offset:11264
	global_load_dword v115, v159, s[48:49]
	v_mov_b32_e32 v117, v102
	s_waitcnt lgkmcnt(2)
	v_mfma_f32_16x16x32_bf16 v[40:43], v[166:169], v[56:59], 0
	v_mov_b32_e32 v161, v103
	v_pk_mul_f32 v[160:161], v[160:161], v[160:161]
	s_waitcnt lgkmcnt(1)
	v_mfma_f32_16x16x32_bf16 v[48:51], v[170:173], v[52:55], v[40:43]
	s_waitcnt lgkmcnt(0)
	v_mfma_f32_16x16x32_bf16 v[98:101], v[88:91], v[36:39], v[48:51]
	s_nop 1
	v_mul_u32_u24_e32 v40, 0x90, v177
	v_add3_u32 v116, s7, v40, v114
	ds_read_b128 v[40:43], v60 offset:12288
	ds_read2_b64 v[60:63], v116 offset1:4
	ds_read2_b64 v[48:51], v116 offset0:8 offset1:12
	s_waitcnt lgkmcnt(1)
	v_mfma_f32_16x16x32_bf16 v[166:169], v[166:169], v[60:63], 0
	v_mov_b32_e32 v116, v92
	v_pk_mul_f32 v[116:117], v[116:117], v[116:117]
	s_waitcnt lgkmcnt(0)
	v_mfma_f32_16x16x32_bf16 v[166:169], v[170:173], v[48:51], v[166:169]
	v_mov_b32_e32 v170, v160
	v_mov_b32_e32 v171, v116
	v_mov_b32_e32 v116, v161
	v_mfma_f32_16x16x32_bf16 v[88:91], v[88:91], v[40:43], v[166:169]
	v_add_f32_e64 v116, v170, v116
	v_add_f32_e64 v117, v171, v117
	s_waitcnt vmcnt(1)
	v_lshlrev_b32_e32 v170, 16, v176
	v_mov_b32_e32 v166, v98
	s_nop 2
	v_mov_b32_e32 v167, v88
	v_mov_b32_e32 v168, v99
	v_mov_b32_e32 v169, v89
	v_pk_mul_f32 v[166:167], v[166:167], v[166:167]
	v_pk_mul_f32 v[168:169], v[168:169], v[168:169]
	v_mov_b32_e32 v161, v166
	v_mov_b32_e32 v160, v168
	v_pk_add_f32 v[116:117], v[116:117], v[160:161]
	v_mov_b32_e32 v166, v169
	v_pk_add_f32 v[116:117], v[116:117], v[166:167]
	ds_swizzle_b32 v161, v117 offset:swizzle(SWAP,1)
	ds_swizzle_b32 v160, v116 offset:swizzle(SWAP,1)
	v_lshlrev_b32_e32 v168, 2, v177
	v_mov_b32_e32 v169, v211
	s_waitcnt lgkmcnt(0)
	v_pk_add_f32 v[116:117], v[116:117], v[160:161]
	ds_swizzle_b32 v161, v117 offset:swizzle(SWAP,2)
	ds_swizzle_b32 v160, v116 offset:swizzle(SWAP,2)
	s_waitcnt lgkmcnt(0)
; __device__ __forceinline__ unsigned cvtpk(float lo, float hi) { f32x2_t v = {lo, hi}; bf16x2_t b = __builtin_convertvector(v, bf16x2_t); return __builtin_bit_cast(unsigned, b); }
; template <int X> __device__ __forceinline__ float swz_xor(float v) { return __int_as_float(__builtin_amdgcn_ds_swizzle(__float_as_int(v), (X << 10) | 0x1F)); }
; __device__ __forceinline__ float silu_f(float g) { return g * __builtin_amdgcn_rcpf(1.0f + __expf(-g)); }
; template <bool GLA>
; __device__ __forceinline__ void chunk_pass_c(const ChunkIn& ci, const float* wgl, int unit, unsigned char* wl, int lane, const float* Sb, const float* ng, bf16_t* omix) {
;     ...
; #pragma unroll
;         for (int r = 0; r < 4; ++r) {
;             ss[r] += swz_xor<1>(ss[r]); ss[r] += swz_xor<2>(ss[r]); ss[r] += swz_xor<4>(ss[r]); ss[r] += swz_xor<8>(ss[r]);
;             const float rs = rsqrtf(ss[r] * (1.0f / 64.0f) + EPS);
;             const int t = t0 + 16 * it + 4 * kq + r;
; #pragma unroll
;             for (int et = 0; et < 4; ++et) {
;                 const int e = 16 * et + row;
;                 const float gt = __uint_as_float((unsigned)ci.proj[(size_t)t * DINP + gcol + e] << 16);
;                 const float val = o[et][r] * rs * gn[et] * pg8::silu_f(gt);
;                 omix[(size_t)t * 1024 + ocol + e] = (bf16_t)(cvtpk(val, 0.f) & 0xffffu);
;             }
;         }
	v_pk_add_f32 v[116:117], v[116:117], v[160:161]
	ds_swizzle_b32 v167, v117 offset:swizzle(SWAP,4)
	ds_swizzle_b32 v166, v116 offset:swizzle(SWAP,4)
	global_load_dword v161, v159, s[48:49] offset:64
	global_load_dword v160, v159, s[48:49] offset:128
	s_nop 0
	global_load_dword v159, v168, s[48:49]
	v_mul_f32_e32 v168, 0xbfb8aa3b, v170
	v_exp_f32_e32 v171, v168
	v_lshlrev_b32_e32 v168, 11, v165
	s_waitcnt lgkmcnt(0)
	v_pk_add_f32 v[116:117], v[116:117], v[166:167]
	ds_swizzle_b32 v167, v117 offset:swizzle(SWAP,8)
	ds_swizzle_b32 v166, v116 offset:swizzle(SWAP,8)
	v_add_f32_e32 v171, 1.0, v171
	v_rcp_f32_e32 v171, v171
	v_lshl_add_u64 v[168:169], s[60:61], 0, v[168:169]
	s_waitcnt lgkmcnt(0)
	v_pk_add_f32 v[166:167], v[116:117], v[166:167]
	v_mov_b64_e32 v[116:117], s[6:7]
	s_mov_b32 s6, 0x3c800000
	v_pk_fma_f32 v[166:167], v[166:167], s[6:7], v[116:117] op_sel_hi:[1,0,0]
	s_nop 0
	v_mul_f32_e32 v172, 0x4b800000, v167
	v_cmp_gt_f32_e64 s[48:49], s96, v167
	s_nop 1
	v_cndmask_b32_e64 v167, v167, v172, s[48:49]
	v_rsq_f32_e32 v167, v167
	v_mul_f32_e32 v172, v171, v170
	v_lshl_add_u64 v[170:171], v[168:169], 0, v[110:111]
	v_mul_f32_e32 v173, 0x45800000, v167
	v_cndmask_b32_e64 v167, v167, v173, s[48:49]
	v_mul_f32_e32 v92, v92, v167
	s_waitcnt vmcnt(3)
	v_mul_f32_e32 v92, v115, v92
	v_mul_f32_e32 v92, v172, v92
	v_cvt_pk_bf16_f32 v92, v92, s0
	global_store_short v[170:171], v92, off offset:1536
	global_load_ushort v92, v[112:113], off offset:3456
	v_mul_f32_e32 v102, v102, v167
	v_mul_f32_e32 v98, v98, v167
	v_mul_f32_e32 v88, v88, v167
	v_cmp_gt_f32_e64 s[48:49], s96, v166
	s_waitcnt vmcnt(4)
	v_mul_f32_e32 v102, v161, v102
	s_waitcnt vmcnt(3)
	v_mul_f32_e32 v98, v160, v98
	s_waitcnt vmcnt(2)
	v_mul_f32_e32 v88, v159, v88
	s_waitcnt vmcnt(0)
	v_lshlrev_b32_e32 v92, 16, v92
	v_mul_f32_e32 v172, 0xbfb8aa3b, v92
	v_exp_f32_e32 v172, v172
	s_nop 0
	v_add_f32_e32 v172, 1.0, v172
	v_rcp_f32_e32 v172, v172
	s_nop 0
	v_mul_f32_e32 v92, v172, v92
	v_mul_f32_e32 v92, v92, v102
	v_cvt_pk_bf16_f32 v92, v92, s0
	global_store_short v[170:171], v92, off offset:1568
	global_load_ushort v92, v[112:113], off offset:3488
	v_lshlrev_b32_e32 v112, 1, v177
	v_mov_b32_e32 v113, v211
	v_lshl_add_u64 v[172:173], v[174:175], 0, v[112:113]
	v_lshl_add_u64 v[168:169], v[168:169], 0, v[112:113]
	s_waitcnt vmcnt(0)
	v_lshlrev_b32_e32 v92, 16, v92
	v_mul_f32_e32 v102, 0xbfb8aa3b, v92
	v_exp_f32_e32 v102, v102
	s_nop 0
	v_add_f32_e32 v102, 1.0, v102
	v_rcp_f32_e32 v102, v102
	s_nop 0
	v_mul_f32_e32 v92, v102, v92
	v_mul_f32_e32 v92, v98, v92
	v_cvt_pk_bf16_f32 v92, v92, s0
	global_store_short v[170:171], v92, off offset:1600
	global_load_ushort v92, v[172:173], off offset:3424
	v_mov_b32_e32 v173, v211
	s_waitcnt vmcnt(0)
	v_lshlrev_b32_e32 v92, 16, v92
	v_mul_f32_e32 v98, 0xbfb8aa3b, v92
	v_exp_f32_e32 v98, v98
	s_nop 0
	v_add_f32_e32 v98, 1.0, v98
	v_rcp_f32_e32 v98, v98
	s_nop 0
	v_mul_f32_e32 v92, v98, v92
	v_mul_f32_e32 v88, v88, v92
	v_cvt_pk_bf16_f32 v88, v88, s0
	global_store_short v[168:169], v88, off offset:1536
	v_or_b32_e32 v88, 1, v165
	v_lshlrev_b32_e32 v168, 12, v88
	v_mov_b32_e32 v169, v211
	v_lshl_add_u64 v[168:169], s[58:59], 0, v[168:169]
	v_lshl_add_u64 v[170:171], v[168:169], 0, v[110:111]
	global_load_ushort v92, v[170:171], off offset:3424
	v_lshlrev_b32_e32 v172, 11, v88
	v_mul_f32_e32 v88, 0x4b800000, v166
	v_cndmask_b32_e64 v88, v166, v88, s[48:49]
	v_rsq_f32_e32 v88, v88
	v_lshl_add_u64 v[166:167], s[60:61], 0, v[172:173]
	v_lshl_add_u64 v[172:173], v[166:167], 0, v[110:111]
	v_mul_f32_e32 v102, 0x45800000, v88
	v_cndmask_b32_e64 v88, v88, v102, s[48:49]
	v_mul_f32_e32 v93, v93, v88
	v_mul_f32_e32 v93, v115, v93
	v_mul_f32_e32 v99, v99, v88
	v_mul_f32_e32 v99, v160, v99
	s_waitcnt vmcnt(0)
	v_lshlrev_b32_e32 v92, 16, v92
	v_mul_f32_e32 v98, 0xbfb8aa3b, v92
	v_exp_f32_e32 v98, v98
	s_nop 0
	v_add_f32_e32 v98, 1.0, v98
	v_rcp_f32_e32 v98, v98
	s_nop 0
	v_mul_f32_e32 v92, v98, v92
	v_mul_f32_e32 v92, v92, v93
	v_cvt_pk_bf16_f32 v92, v92, s0
	global_store_short v[172:173], v92, off offset:1536
	global_load_ushort v92, v[170:171], off offset:3456
	v_mul_f32_e32 v98, v103, v88
	v_mul_f32_e32 v98, v161, v98
	v_mul_f32_e32 v88, v89, v88
	v_mul_f32_e32 v88, v159, v88
	s_waitcnt vmcnt(0)
	v_lshlrev_b32_e32 v92, 16, v92
	v_mul_f32_e32 v93, 0xbfb8aa3b, v92
	v_exp_f32_e32 v93, v93
	s_nop 0
	v_add_f32_e32 v93, 1.0, v93
	v_rcp_f32_e32 v93, v93
	s_nop 0
	v_mul_f32_e32 v92, v93, v92
	v_mul_f32_e32 v92, v98, v92
	v_cvt_pk_bf16_f32 v92, v92, s0
	global_store_short v[172:173], v92, off offset:1568
	global_load_ushort v92, v[170:171], off offset:3488
	s_waitcnt vmcnt(0)
	v_lshlrev_b32_e32 v98, 16, v92
	v_mul_f32_e32 v92, 0xbfb8aa3b, v98
	v_exp_f32_e32 v92, v92
	s_nop 0
	v_add_f32_e32 v92, 1.0, v92
	v_rcp_f32_e32 v102, v92
	v_lshl_add_u64 v[92:93], v[168:169], 0, v[112:113]
	v_mov_b32_e32 v169, v91
	v_mul_f32_e32 v98, v102, v98
	v_mul_f32_e32 v98, v99, v98
	v_cvt_pk_bf16_f32 v98, v98, s0
	global_store_short v[172:173], v98, off offset:1600
	global_load_ushort v92, v[92:93], off offset:3424
	v_lshl_add_u64 v[98:99], v[166:167], 0, v[112:113]
	v_or_b32_e32 v172, 2, v165
	v_mov_b32_e32 v93, v211
	v_mov_b32_e32 v167, v90
	s_waitcnt vmcnt(0)
; template <bool GLA>
; __device__ __forceinline__ void chunk_pass_c(const ChunkIn& ci, const float* wgl, int unit, unsigned char* wl, int lane, const float* Sb, const float* ng, bf16_t* omix) {
;     ...
;     for (int it = 0; it < 4; ++it) {
;         f32x4 st[4];
; #pragma unroll
;         for (int jt = 0; jt < 4; ++jt) {
;             const f32x4 z = {0.f, 0.f, 0.f, 0.f};
;             if (jt < it) st[jt] = __builtin_amdgcn_mfma_f32_16x16x32_bf16(kf[jt], qf[it], z, 0, 0, 0);
;             else if (jt > it) st[jt] = __builtin_amdgcn_mfma_f32_16x16x32_bf16(kb[jt], qb[it], z, 0, 0, 0);
;             else {
;                 const f32x4 lo = __builtin_amdgcn_mfma_f32_16x16x32_bf16(kf[jt], qf[it], z, 0, 0, 0), up = __builtin_amdgcn_mfma_f32_16x16x32_bf16(kb[jt], qb[it], z, 0, 0, 0);
; #pragma unroll
;                 for (int r = 0; r < 4; ++r) st[jt][r] = (4 * kq + r <= row) ? lo[r] : up[r];
;             }
;         }
;         bf16x8 af[2];
; #pragma unroll
;         for (int p = 0; p < 2; ++p)
;             af[p] = __builtin_bit_cast(bf16x8, (u32x4){cvtpk(st[2 * p][0], st[2 * p][1]), cvtpk(st[2 * p][2], st[2 * p][3]), cvtpk(st[2 * p + 1][0], st[2 * p + 1][1]), cvtpk(st[2 * p + 1][2], st[2 * p + 1][3])});
;         f32x4 o[4]; float ss[4] = {0.f, 0.f, 0.f, 0.f};
; #pragma unroll
;         for (int et = 0; et < 4; ++et) {
;             f32x4 acc = {0.f, 0.f, 0.f, 0.f};
;             acc = __builtin_amdgcn_mfma_f32_16x16x32_bf16(af[0], vfr[et][0], acc, 0, 0, 0);
;             acc = __builtin_amdgcn_mfma_f32_16x16x32_bf16(af[1], vfr[et][1], acc, 0, 0, 0);
;             acc = __builtin_amdgcn_mfma_f32_16x16x32_bf16(qf[it], sfr[et], acc, 0, 0, 0);
;     ...
; #pragma unroll
;         for (int r = 0; r < 4; ++r) {
;             ss[r] += swz_xor<1>(ss[r]); ss[r] += swz_xor<2>(ss[r]); ss[r] += swz_xor<4>(ss[r]); ss[r] += swz_xor<8>(ss[r]);
;             const float rs = rsqrtf(ss[r] * (1.0f / 64.0f) + EPS);
;             const int t = t0 + 16 * it + 4 * kq + r;
; #pragma unroll
;             for (int et = 0; et < 4; ++et) {
;                 const int e = 16 * et + row;
;                 const float gt = __uint_as_float((unsigned)ci.proj[(size_t)t * DINP + gcol + e] << 16);
;                 const float val = o[et][r] * rs * gn[et] * pg8::silu_f(gt);
;                 omix[(size_t)t * 1024 + ocol + e] = (bf16_t)(cvtpk(val, 0.f) & 0xffffu);
;             }
;         }
	v_lshlrev_b32_e32 v168, 16, v92
	v_mul_f32_e32 v92, 0xbfb8aa3b, v168
	v_exp_f32_e32 v102, v92
	v_lshlrev_b32_e32 v92, 12, v172
	v_lshl_add_u64 v[92:93], s[58:59], 0, v[92:93]
	v_add_f32_e32 v102, 1.0, v102
	v_rcp_f32_e32 v166, v102
	v_lshl_add_u64 v[102:103], v[92:93], 0, v[110:111]
	v_lshl_add_u64 v[92:93], v[92:93], 0, v[112:113]
	v_mul_f32_e32 v89, v166, v168
	v_mul_f32_e32 v88, v88, v89
	v_cvt_pk_bf16_f32 v88, v88, s0
	global_store_short v[98:99], v88, off offset:1536
	global_load_ushort v173, v[102:103], off offset:3424
	v_mov_b32_e32 v88, v94
	v_mov_b32_e32 v89, v104
	v_mov_b32_e32 v98, v95
	v_mov_b32_e32 v99, v105
	v_mov_b32_e32 v166, v100
	v_mov_b32_e32 v168, v101
	v_pk_mul_f32 v[88:89], v[88:89], v[88:89]
	v_pk_mul_f32 v[98:99], v[98:99], v[98:99]
	v_pk_mul_f32 v[166:167], v[166:167], v[166:167]
	v_pk_mul_f32 v[168:169], v[168:169], v[168:169]
	v_mov_b32_e32 v170, v98
	v_mov_b32_e32 v171, v88
	v_mov_b32_e32 v88, v99
	v_mov_b32_e32 v98, v168
	v_mov_b32_e32 v99, v166
	v_pk_add_f32 v[88:89], v[170:171], v[88:89]
	v_mov_b32_e32 v166, v169
	v_pk_add_f32 v[88:89], v[88:89], v[98:99]
	s_waitcnt vmcnt(0)
	v_lshlrev_b32_e32 v168, 16, v173
	v_pk_add_f32 v[88:89], v[88:89], v[166:167]
	ds_swizzle_b32 v99, v89 offset:swizzle(SWAP,1)
	ds_swizzle_b32 v98, v88 offset:swizzle(SWAP,1)
	v_mov_b32_e32 v167, v211
	v_lshlrev_b32_e32 v166, 11, v172
	s_waitcnt lgkmcnt(0)
	v_pk_add_f32 v[88:89], v[88:89], v[98:99]
	ds_swizzle_b32 v99, v89 offset:swizzle(SWAP,2)
	ds_swizzle_b32 v98, v88 offset:swizzle(SWAP,2)
	s_waitcnt lgkmcnt(0)
	v_pk_add_f32 v[88:89], v[88:89], v[98:99]
	ds_swizzle_b32 v99, v89 offset:swizzle(SWAP,4)
	ds_swizzle_b32 v98, v88 offset:swizzle(SWAP,4)
	s_waitcnt lgkmcnt(0)
	v_pk_add_f32 v[88:89], v[88:89], v[98:99]
	ds_swizzle_b32 v99, v89 offset:swizzle(SWAP,8)
	ds_swizzle_b32 v98, v88 offset:swizzle(SWAP,8)
	s_waitcnt lgkmcnt(0)
	v_pk_add_f32 v[88:89], v[88:89], v[98:99]
	s_nop 0
	v_pk_fma_f32 v[88:89], v[88:89], s[6:7], v[116:117] op_sel_hi:[1,0,0]
	s_nop 0
	v_mul_f32_e32 v98, 0x4b800000, v89
	v_cmp_gt_f32_e64 s[48:49], s96, v89
	s_nop 1
	v_cndmask_b32_e64 v89, v89, v98, s[48:49]
	v_mul_f32_e32 v98, 0xbfb8aa3b, v168
	v_exp_f32_e32 v169, v98
	v_rsq_f32_e32 v89, v89
	v_lshl_add_u64 v[98:99], s[60:61], 0, v[166:167]
	v_lshl_add_u64 v[166:167], v[98:99], 0, v[110:111]
	v_add_f32_e32 v169, 1.0, v169
	v_rcp_f32_e32 v169, v169
	v_mul_f32_e32 v170, 0x45800000, v89
	v_cndmask_b32_e64 v89, v89, v170, s[48:49]
	v_mul_f32_e32 v94, v94, v89
	v_mul_f32_e32 v94, v115, v94
	v_mul_f32_e32 v168, v169, v168
	v_mul_f32_e32 v94, v168, v94
	v_cvt_pk_bf16_f32 v94, v94, s0
	global_store_short v[166:167], v94, off offset:1536
	global_load_ushort v94, v[102:103], off offset:3456
	v_mul_f32_e32 v104, v104, v89
	v_mul_f32_e32 v104, v161, v104
	v_mul_f32_e32 v100, v100, v89
	v_mul_f32_e32 v100, v160, v100
	v_mul_f32_e32 v89, v90, v89
	v_mul_f32_e32 v89, v159, v89
	v_cmp_gt_f32_e64 s[48:49], s96, v88
	s_waitcnt vmcnt(0)
	v_lshlrev_b32_e32 v94, 16, v94
	v_mul_f32_e32 v168, 0xbfb8aa3b, v94
	v_exp_f32_e32 v168, v168
	s_nop 0
	v_add_f32_e32 v168, 1.0, v168
	v_rcp_f32_e32 v168, v168
	s_nop 0
	v_mul_f32_e32 v94, v168, v94
	v_mul_f32_e32 v94, v104, v94
	v_cvt_pk_bf16_f32 v94, v94, s0
	global_store_short v[166:167], v94, off offset:1568
	global_load_ushort v94, v[102:103], off offset:3488
	v_and_b32_e32 v103, 0xffff0000, v142
	s_waitcnt vmcnt(0)
	v_lshlrev_b32_e32 v94, 16, v94
	v_mul_f32_e32 v102, 0xbfb8aa3b, v94
	v_exp_f32_e32 v102, v102
	s_nop 0
	v_add_f32_e32 v102, 1.0, v102
	v_rcp_f32_e32 v102, v102
	s_nop 0
	v_mul_f32_e32 v94, v102, v94
	v_mul_f32_e32 v94, v100, v94
	v_cvt_pk_bf16_f32 v94, v94, s0
	global_store_short v[166:167], v94, off offset:1600
	global_load_ushort v92, v[92:93], off offset:3424
	v_or_b32_e32 v94, 3, v165
	v_mov_b32_e32 v93, v211
	s_waitcnt vmcnt(0)
	v_lshlrev_b32_e32 v100, 16, v92
	v_mul_f32_e32 v92, 0xbfb8aa3b, v100
	v_exp_f32_e32 v102, v92
	v_lshlrev_b32_e32 v92, 12, v94
	v_lshl_add_u64 v[168:169], s[58:59], 0, v[92:93]
	v_lshl_add_u64 v[92:93], v[98:99], 0, v[112:113]
	v_add_f32_e32 v98, 1.0, v102
	v_rcp_f32_e32 v102, v98
	v_lshl_add_u64 v[98:99], v[168:169], 0, v[110:111]
	v_mul_f32_e32 v90, v102, v100
	v_mul_f32_e32 v89, v89, v90
	v_cvt_pk_bf16_f32 v89, v89, s0
	global_store_short v[92:93], v89, off offset:1536
	global_load_ushort v89, v[98:99], off offset:3424
	v_mul_f32_e32 v90, 0xbfb8aa3b, v164
	v_mov_b32_e32 v93, v211
	v_lshlrev_b32_e32 v92, 11, v94
	v_exp_f32_e32 v90, v90
	v_lshl_add_u64 v[170:171], s[60:61], 0, v[92:93]
	v_lshlrev_b32_e32 v92, 16, v144
	v_and_b32_e32 v93, 0xffff0000, v144
	v_lshlrev_b32_e32 v102, 16, v142
	v_lshlrev_b32_e32 v144, 16, v145
	v_and_b32_e32 v145, 0xffff0000, v145
	v_lshlrev_b32_e32 v142, 16, v143
	v_and_b32_e32 v143, 0xffff0000, v143
	v_pk_mul_f32 v[164:165], v[80:81], v[92:93]
	v_pk_mul_f32 v[80:81], v[80:81], v[102:103]
	v_pk_mul_f32 v[166:167], v[82:83], v[144:145]
	v_pk_mul_f32 v[82:83], v[82:83], v[142:143]
	v_pk_fma_f32 v[102:103], v[76:77], v[102:103], v[164:165]
	v_pk_fma_f32 v[76:77], v[76:77], v[92:93], v[80:81] neg_lo:[0,0,1] neg_hi:[0,0,1]
	v_pk_fma_f32 v[80:81], v[78:79], v[142:143], v[166:167]
	v_pk_fma_f32 v[78:79], v[78:79], v[144:145], v[82:83] neg_lo:[0,0,1] neg_hi:[0,0,1]
	v_pk_mul_f32 v[82:83], v[102:103], s[8:9] op_sel_hi:[1,0]
	v_pk_mul_f32 v[76:77], v[76:77], s[8:9] op_sel_hi:[1,0]
	v_pk_mul_f32 v[92:93], v[90:91], v[150:151] op_sel_hi:[0,1]
	v_pk_mul_f32 v[102:103], v[90:91], v[148:149] op_sel_hi:[0,1]
	v_pk_mul_f32 v[148:149], v[80:81], s[8:9] op_sel_hi:[1,0]
	v_pk_mul_f32 v[150:151], v[78:79], s[8:9] op_sel_hi:[1,0]
	v_pk_mul_f32 v[78:79], v[90:91], v[154:155] op_sel_hi:[0,1]
	v_pk_mul_f32 v[80:81], v[90:91], v[152:153] op_sel_hi:[0,1]
	v_pk_mul_f32 v[142:143], v[146:147], v[76:77] op_sel_hi:[0,1]
	v_pk_mul_f32 v[152:153], v[90:91], v[76:77] op_sel_hi:[0,1]
	v_pk_mul_f32 v[164:165], v[90:91], v[82:83] op_sel_hi:[0,1]
	v_cvt_pk_bf16_f32 v76, v92, v93
	v_cvt_pk_bf16_f32 v77, v78, v79
	v_cvt_pk_bf16_f32 v78, v102, v103
	v_pk_mul_f32 v[92:93], v[90:91], v[150:151] op_sel_hi:[0,1]
	v_pk_mul_f32 v[102:103], v[90:91], v[148:149] op_sel_hi:[0,1]
	v_mul_f32_e32 v90, 0x4b800000, v88
	v_pk_mul_f32 v[154:155], v[146:147], v[148:149] op_sel_hi:[0,1]
	v_cvt_pk_bf16_f32 v149, v92, v93
	v_cndmask_b32_e64 v88, v88, v90, s[48:49]
	v_rsq_f32_e32 v90, v88
	v_cvt_pk_bf16_f32 v79, v80, v81
	v_pk_mul_f32 v[144:145], v[146:147], v[82:83] op_sel_hi:[0,1]
	v_pk_mul_f32 v[82:83], v[146:147], v[150:151] op_sel_hi:[0,1]
	v_mul_f32_e32 v94, 0x45800000, v90
	v_cndmask_b32_e64 v90, v90, v94, s[48:49]
	v_mul_f32_e32 v94, v95, v90
	v_mul_f32_e32 v94, v115, v94
	v_cvt_pk_bf16_f32 v80, v142, v143
	v_cvt_pk_bf16_f32 v81, v82, v83
	v_cvt_pk_bf16_f32 v82, v144, v145
	v_cvt_pk_bf16_f32 v83, v154, v155
	v_cvt_pk_bf16_f32 v148, v152, v153
	v_cvt_pk_bf16_f32 v150, v164, v165
	v_cvt_pk_bf16_f32 v151, v102, v103
	v_mfma_f32_16x16x32_bf16 v[152:155], v[76:79], v[80:83], 0
	v_mul_f32_e32 v101, v101, v90
	v_mul_f32_e32 v101, v160, v101
	s_waitcnt vmcnt(0)
; template <bool GLA>
; __device__ __forceinline__ void chunk_pass_c(const ChunkIn& ci, const float* wgl, int unit, unsigned char* wl, int lane, const float* Sb, const float* ng, bf16_t* omix) {
;     ...
;     for (int it = 0; it < 4; ++it) {
;         f32x4 st[4];
; #pragma unroll
;         for (int jt = 0; jt < 4; ++jt) {
;             const f32x4 z = {0.f, 0.f, 0.f, 0.f};
;             if (jt < it) st[jt] = __builtin_amdgcn_mfma_f32_16x16x32_bf16(kf[jt], qf[it], z, 0, 0, 0);
;             else if (jt > it) st[jt] = __builtin_amdgcn_mfma_f32_16x16x32_bf16(kb[jt], qb[it], z, 0, 0, 0);
;             else {
;                 const f32x4 lo = __builtin_amdgcn_mfma_f32_16x16x32_bf16(kf[jt], qf[it], z, 0, 0, 0), up = __builtin_amdgcn_mfma_f32_16x16x32_bf16(kb[jt], qb[it], z, 0, 0, 0);
; #pragma unroll
;                 for (int r = 0; r < 4; ++r) st[jt][r] = (4 * kq + r <= row) ? lo[r] : up[r];
;             }
;         }
;         bf16x8 af[2];
; #pragma unroll
;         for (int p = 0; p < 2; ++p)
;             af[p] = __builtin_bit_cast(bf16x8, (u32x4){cvtpk(st[2 * p][0], st[2 * p][1]), cvtpk(st[2 * p][2], st[2 * p][3]), cvtpk(st[2 * p + 1][0], st[2 * p + 1][1]), cvtpk(st[2 * p + 1][2], st[2 * p + 1][3])});
;         f32x4 o[4]; float ss[4] = {0.f, 0.f, 0.f, 0.f};
; #pragma unroll
;         for (int et = 0; et < 4; ++et) {
;             f32x4 acc = {0.f, 0.f, 0.f, 0.f};
;             acc = __builtin_amdgcn_mfma_f32_16x16x32_bf16(af[0], vfr[et][0], acc, 0, 0, 0);
;             acc = __builtin_amdgcn_mfma_f32_16x16x32_bf16(af[1], vfr[et][1], acc, 0, 0, 0);
;             acc = __builtin_amdgcn_mfma_f32_16x16x32_bf16(qf[it], sfr[et], acc, 0, 0, 0);
;             o[et] = acc;
; #pragma unroll
;             for (int r = 0; r < 4; ++r) ss[r] += acc[r] * acc[r];
;         }
; #pragma unroll
;         for (int r = 0; r < 4; ++r) {
;             ss[r] += swz_xor<1>(ss[r]); ss[r] += swz_xor<2>(ss[r]); ss[r] += swz_xor<4>(ss[r]); ss[r] += swz_xor<8>(ss[r]);
;             const float rs = rsqrtf(ss[r] * (1.0f / 64.0f) + EPS);
;             const int t = t0 + 16 * it + 4 * kq + r;
; #pragma unroll
;             for (int et = 0; et < 4; ++et) {
;                 const int e = 16 * et + row;
;                 const float gt = __uint_as_float((unsigned)ci.proj[(size_t)t * DINP + gcol + e] << 16);
;                 const float val = o[et][r] * rs * gn[et] * pg8::silu_f(gt);
	v_lshlrev_b32_e32 v92, 16, v89
	v_mul_f32_e32 v88, 0xbfb8aa3b, v92
	v_exp_f32_e32 v93, v88
	v_lshl_add_u64 v[88:89], v[170:171], 0, v[110:111]
	v_mfma_f32_16x16x32_bf16 v[84:87], v[84:87], v[148:151], 0
	v_add_f32_e32 v93, 1.0, v93
	v_rcp_f32_e32 v93, v93
	v_mfma_f32_16x16x32_bf16 v[142:145], v[8:11], v[80:83], 0
	v_mul_f32_e32 v92, v93, v92
	v_mul_f32_e32 v92, v92, v94
	v_cvt_pk_bf16_f32 v92, v92, s0
	global_store_short v[88:89], v92, off offset:1536
	global_load_ushort v100, v[98:99], off offset:3456
	v_cndmask_b32_e32 v102, v152, v84, vcc
	v_cndmask_b32_e64 v103, v85, v153, s[42:43]
	v_cndmask_b32_e64 v104, v154, v86, s[44:45]
	v_cvt_pk_bf16_f32 v86, v102, v103
	v_mul_f32_e32 v103, v105, v90
	v_mul_f32_e32 v103, v161, v103
	v_cndmask_b32_e64 v87, v155, v87, s[46:47]
	v_mfma_f32_16x16x32_bf16 v[164:167], v[72:75], v[148:151], 0
	v_cvt_pk_bf16_f32 v84, v142, v143
	v_cvt_pk_bf16_f32 v85, v144, v145
	v_cvt_pk_bf16_f32 v87, v104, v87
	v_mfma_f32_16x16x32_bf16 v[92:95], v[12:15], v[148:151], 0
	v_mul_f32_e32 v90, v91, v90
	s_nop 2
	v_cvt_pk_bf16_f32 v152, v164, v165
	v_cvt_pk_bf16_f32 v153, v166, v167
	v_mfma_f32_16x16x32_bf16 v[142:145], v[84:87], v[28:31], 0
	v_mul_f32_e32 v90, v159, v90
	v_cvt_pk_bf16_f32 v154, v92, v93
	v_cvt_pk_bf16_f32 v155, v94, v95
	v_mfma_f32_16x16x32_bf16 v[148:151], v[84:87], v[44:47], 0
	s_waitcnt vmcnt(0)
	v_lshlrev_b32_e32 v100, 16, v100
	v_mul_f32_e32 v102, 0xbfb8aa3b, v100
	v_exp_f32_e32 v102, v102
	v_mfma_f32_16x16x32_bf16 v[92:95], v[152:155], v[20:23], v[142:145]
	v_add_f32_e32 v102, 1.0, v102
	v_rcp_f32_e32 v102, v102
	v_mfma_f32_16x16x32_bf16 v[142:145], v[152:155], v[32:35], v[148:151]
	v_mul_f32_e32 v100, v102, v100
	v_mul_f32_e32 v100, v103, v100
	v_cvt_pk_bf16_f32 v100, v100, s0
	global_store_short v[88:89], v100, off offset:1568
	global_load_ushort v98, v[98:99], off offset:3488
	v_mfma_f32_16x16x32_bf16 v[102:105], v[84:87], v[56:59], 0
	s_waitcnt vmcnt(0)
	v_lshlrev_b32_e32 v100, 16, v98
	v_mul_f32_e32 v98, 0xbfb8aa3b, v100
	v_exp_f32_e32 v146, v98
	v_lshl_add_u64 v[98:99], v[168:169], 0, v[112:113]
	v_mfma_f32_16x16x32_bf16 v[84:87], v[84:87], v[60:63], 0
	v_add_f32_e32 v146, 1.0, v146
	v_rcp_f32_e32 v146, v146
	v_mfma_f32_16x16x32_bf16 v[148:151], v[152:155], v[48:51], v[84:87]
	v_mul_f32_e32 v100, v146, v100
	v_mul_f32_e32 v100, v101, v100
	v_cvt_pk_bf16_f32 v100, v100, s0
	global_store_short v[88:89], v100, off offset:1600
	global_load_ushort v146, v[98:99], off offset:3424
	v_mfma_f32_16x16x32_bf16 v[98:101], v[80:83], v[24:27], v[92:95]
	v_mov_b32_e32 v89, v211
	s_waitcnt vmcnt(0)
	v_lshlrev_b32_e32 v146, 16, v146
	v_mul_f32_e32 v84, 0xbfb8aa3b, v146
	v_exp_f32_e32 v84, v84
	v_mfma_f32_16x16x32_bf16 v[92:95], v[80:83], v[16:19], v[142:145]
	v_add_f32_e32 v84, 1.0, v84
	s_nop 1
	v_rcp_f32_e32 v144, v84
	v_mfma_f32_16x16x32_bf16 v[102:105], v[152:155], v[52:55], v[102:105]
	v_or_b32_e32 v154, s5, v97
	v_lshlrev_b32_e32 v88, 12, v154
	v_mul_f32_e32 v91, v144, v146
	v_mul_f32_e32 v90, v90, v91
	v_lshl_add_u64 v[88:89], s[58:59], 0, v[88:89]
	v_lshl_add_u64 v[152:153], v[170:171], 0, v[112:113]
	v_cvt_pk_bf16_f32 v90, v90, s0
	v_lshl_add_u64 v[142:143], v[88:89], 0, v[110:111]
	global_store_short v[152:153], v90, off offset:1536
	global_load_ushort v146, v[142:143], off offset:3424
	v_mfma_f32_16x16x32_bf16 v[84:87], v[80:83], v[36:39], v[102:105]
	v_mov_b32_e32 v90, v98
	v_mov_b32_e32 v91, v92
	v_pk_mul_f32 v[90:91], v[90:91], v[90:91]
	v_mfma_f32_16x16x32_bf16 v[80:83], v[80:83], v[40:43], v[148:151]
	v_mov_b32_e32 v102, v99
	v_mov_b32_e32 v103, v93
	s_nop 1
	v_mov_b32_e32 v104, v84
	v_mov_b32_e32 v144, v85
	v_pk_mul_f32 v[102:103], v[102:103], v[102:103]
	s_nop 0
	v_mov_b32_e32 v105, v80
	v_mov_b32_e32 v145, v81
	v_pk_mul_f32 v[104:105], v[104:105], v[104:105]
	v_pk_mul_f32 v[144:145], v[144:145], v[144:145]
	v_mov_b32_e32 v148, v102
	v_mov_b32_e32 v149, v90
	v_mov_b32_e32 v90, v103
	v_mov_b32_e32 v102, v144
	v_mov_b32_e32 v103, v104
	v_pk_add_f32 v[90:91], v[148:149], v[90:91]
	v_mov_b32_e32 v104, v145
	v_pk_add_f32 v[90:91], v[90:91], v[102:103]
	v_lshl_add_u64 v[88:89], v[88:89], 0, v[112:113]
	v_pk_add_f32 v[90:91], v[90:91], v[104:105]
	ds_swizzle_b32 v103, v91 offset:swizzle(SWAP,1)
	ds_swizzle_b32 v102, v90 offset:swizzle(SWAP,1)
	v_mov_b32_e32 v105, v211
	v_lshlrev_b32_e32 v104, 11, v154
	s_waitcnt lgkmcnt(0)
	v_pk_add_f32 v[90:91], v[90:91], v[102:103]
	ds_swizzle_b32 v103, v91 offset:swizzle(SWAP,2)
	ds_swizzle_b32 v102, v90 offset:swizzle(SWAP,2)
	s_waitcnt lgkmcnt(0)
	v_pk_add_f32 v[90:91], v[90:91], v[102:103]
	ds_swizzle_b32 v103, v91 offset:swizzle(SWAP,4)
	ds_swizzle_b32 v102, v90 offset:swizzle(SWAP,4)
	s_waitcnt lgkmcnt(0)
	v_pk_add_f32 v[90:91], v[90:91], v[102:103]
	ds_swizzle_b32 v103, v91 offset:swizzle(SWAP,8)
	ds_swizzle_b32 v102, v90 offset:swizzle(SWAP,8)
	s_waitcnt lgkmcnt(0)
	v_pk_add_f32 v[90:91], v[90:91], v[102:103]
	s_nop 0
	v_pk_fma_f32 v[90:91], v[90:91], s[6:7], v[116:117] op_sel_hi:[1,0,0]
	s_waitcnt vmcnt(0)
	v_lshlrev_b32_e32 v144, 16, v146
	v_mul_f32_e32 v102, 0x4b800000, v91
	v_cmp_gt_f32_e64 s[48:49], s96, v91
	s_nop 1
	v_cndmask_b32_e64 v91, v91, v102, s[48:49]
	v_mul_f32_e32 v102, 0xbfb8aa3b, v144
	v_exp_f32_e32 v145, v102
	v_rsq_f32_e32 v91, v91
	v_lshl_add_u64 v[102:103], s[60:61], 0, v[104:105]
	v_lshl_add_u64 v[104:105], v[102:103], 0, v[110:111]
	v_add_f32_e32 v145, 1.0, v145
	v_rcp_f32_e32 v145, v145
	v_mul_f32_e32 v146, 0x45800000, v91
	v_cndmask_b32_e64 v91, v91, v146, s[48:49]
	v_mul_f32_e32 v98, v98, v91
	v_mul_f32_e32 v98, v115, v98
	v_mul_f32_e32 v144, v145, v144
	v_mul_f32_e32 v98, v144, v98
	v_cvt_pk_bf16_f32 v98, v98, s0
	global_store_short v[104:105], v98, off offset:1536
	global_load_ushort v98, v[142:143], off offset:3456
	v_mul_f32_e32 v92, v92, v91
	v_mul_f32_e32 v92, v161, v92
	v_mul_f32_e32 v84, v84, v91
	v_mul_f32_e32 v84, v160, v84
	v_mul_f32_e32 v80, v80, v91
	v_mul_f32_e32 v80, v159, v80
	v_lshl_add_u64 v[102:103], v[102:103], 0, v[112:113]
	v_cmp_gt_f32_e64 s[48:49], s96, v90
	s_waitcnt vmcnt(0)
; __device__ __forceinline__ unsigned cvtpk(float lo, float hi) { f32x2_t v = {lo, hi}; bf16x2_t b = __builtin_convertvector(v, bf16x2_t); return __builtin_bit_cast(unsigned, b); }
; template <int X> __device__ __forceinline__ float swz_xor(float v) { return __int_as_float(__builtin_amdgcn_ds_swizzle(__float_as_int(v), (X << 10) | 0x1F)); }
; __device__ __forceinline__ float silu_f(float g) { return g * __builtin_amdgcn_rcpf(1.0f + __expf(-g)); }
; template <bool GLA>
; __device__ __forceinline__ void chunk_pass_c(const ChunkIn& ci, const float* wgl, int unit, unsigned char* wl, int lane, const float* Sb, const float* ng, bf16_t* omix) {
;     ...
; #pragma unroll
;         for (int r = 0; r < 4; ++r) {
;             ss[r] += swz_xor<1>(ss[r]); ss[r] += swz_xor<2>(ss[r]); ss[r] += swz_xor<4>(ss[r]); ss[r] += swz_xor<8>(ss[r]);
;             const float rs = rsqrtf(ss[r] * (1.0f / 64.0f) + EPS);
;             const int t = t0 + 16 * it + 4 * kq + r;
; #pragma unroll
;             for (int et = 0; et < 4; ++et) {
;                 const int e = 16 * et + row;
;                 const float gt = __uint_as_float((unsigned)ci.proj[(size_t)t * DINP + gcol + e] << 16);
;                 const float val = o[et][r] * rs * gn[et] * pg8::silu_f(gt);
;                 omix[(size_t)t * 1024 + ocol + e] = (bf16_t)(cvtpk(val, 0.f) & 0xffffu);
;             }
;         }
	v_lshlrev_b32_e32 v98, 16, v98
	v_mul_f32_e32 v144, 0xbfb8aa3b, v98
	v_exp_f32_e32 v144, v144
	s_nop 0
	v_add_f32_e32 v144, 1.0, v144
	v_rcp_f32_e32 v144, v144
	s_nop 0
	v_mul_f32_e32 v98, v144, v98
	v_mul_f32_e32 v92, v98, v92
	v_cvt_pk_bf16_f32 v92, v92, s0
	global_store_short v[104:105], v92, off offset:1568
	global_load_ushort v92, v[142:143], off offset:3488
	s_waitcnt vmcnt(0)
	v_lshlrev_b32_e32 v92, 16, v92
	v_mul_f32_e32 v98, 0xbfb8aa3b, v92
	v_exp_f32_e32 v98, v98
	s_nop 0
	v_add_f32_e32 v98, 1.0, v98
	v_rcp_f32_e32 v98, v98
	s_nop 0
	v_mul_f32_e32 v92, v98, v92
	v_mul_f32_e32 v84, v84, v92
	v_cvt_pk_bf16_f32 v84, v84, s0
	global_store_short v[104:105], v84, off offset:1600
	global_load_ushort v84, v[88:89], off offset:3424
	v_or_b32_e32 v92, 1, v154
	v_mov_b32_e32 v89, v211
	s_waitcnt vmcnt(0)
	v_lshlrev_b32_e32 v84, 16, v84
	v_mul_f32_e32 v88, 0xbfb8aa3b, v84
	v_exp_f32_e32 v98, v88
	v_lshlrev_b32_e32 v88, 12, v92
	v_lshl_add_u64 v[88:89], s[58:59], 0, v[88:89]
	v_lshl_add_u64 v[104:105], v[88:89], 0, v[110:111]
	v_add_f32_e32 v98, 1.0, v98
	v_rcp_f32_e32 v98, v98
	v_lshl_add_u64 v[88:89], v[88:89], 0, v[112:113]
	v_mul_f32_e32 v84, v98, v84
	v_mul_f32_e32 v80, v80, v84
	v_cvt_pk_bf16_f32 v80, v80, s0
	global_store_short v[102:103], v80, off offset:1536
	global_load_ushort v80, v[104:105], off offset:3424
	v_mul_f32_e32 v84, 0x4b800000, v90
	v_cndmask_b32_e64 v84, v90, v84, s[48:49]
	v_lshlrev_b32_e32 v102, 11, v92
	v_rsq_f32_e32 v84, v84
	v_mov_b32_e32 v103, v211
	v_mul_f32_e32 v98, 0x45800000, v84
	v_cndmask_b32_e64 v98, v84, v98, s[48:49]
	v_mul_f32_e32 v84, v99, v98
	v_mul_f32_e32 v84, v115, v84
	v_mul_f32_e32 v85, v85, v98
	v_mul_f32_e32 v85, v160, v85
	v_mul_f32_e32 v81, v81, v98
	v_mul_f32_e32 v81, v159, v81
	v_mov_b32_e32 v99, v83
	s_waitcnt vmcnt(0)
	v_lshlrev_b32_e32 v80, 16, v80
	v_mul_f32_e32 v90, 0xbfb8aa3b, v80
	v_exp_f32_e32 v92, v90
	v_lshl_add_u64 v[90:91], s[60:61], 0, v[102:103]
	v_lshl_add_u64 v[102:103], v[90:91], 0, v[110:111]
	v_add_f32_e32 v92, 1.0, v92
	v_rcp_f32_e32 v92, v92
	s_nop 0
	v_mul_f32_e32 v80, v92, v80
	v_mul_f32_e32 v80, v80, v84
	v_cvt_pk_bf16_f32 v80, v80, s0
	global_store_short v[102:103], v80, off offset:1536
	global_load_ushort v80, v[104:105], off offset:3456
	v_mul_f32_e32 v92, v93, v98
	v_mul_f32_e32 v92, v161, v92
	v_mov_b32_e32 v93, v82
	v_mov_b32_e32 v98, v87
	v_pk_mul_f32 v[98:99], v[98:99], v[98:99]
	s_waitcnt vmcnt(0)
	v_lshlrev_b32_e32 v80, 16, v80
	v_mul_f32_e32 v84, 0xbfb8aa3b, v80
	v_exp_f32_e32 v84, v84
	s_nop 0
	v_add_f32_e32 v84, 1.0, v84
	v_rcp_f32_e32 v84, v84
	s_nop 0
	v_mul_f32_e32 v80, v84, v80
	v_mul_f32_e32 v80, v92, v80
	v_cvt_pk_bf16_f32 v80, v80, s0
	global_store_short v[102:103], v80, off offset:1568
	global_load_ushort v80, v[104:105], off offset:3488
	v_or_b32_e32 v104, 2, v154
	s_waitcnt vmcnt(0)
	v_lshlrev_b32_e32 v80, 16, v80
	v_mul_f32_e32 v84, 0xbfb8aa3b, v80
	v_exp_f32_e32 v84, v84
	s_nop 0
	v_add_f32_e32 v84, 1.0, v84
	v_rcp_f32_e32 v84, v84
	s_nop 0
	v_mul_f32_e32 v80, v84, v80
	v_mul_f32_e32 v80, v85, v80
	v_cvt_pk_bf16_f32 v80, v80, s0
	global_store_short v[102:103], v80, off offset:1600
	global_load_ushort v80, v[88:89], off offset:3424
	v_lshl_add_u64 v[88:89], v[90:91], 0, v[112:113]
	v_mov_b32_e32 v85, v211
	s_waitcnt vmcnt(0)
	v_lshlrev_b32_e32 v80, 16, v80
	v_mul_f32_e32 v84, 0xbfb8aa3b, v80
	v_exp_f32_e32 v92, v84
	v_lshlrev_b32_e32 v84, 12, v104
	v_lshl_add_u64 v[84:85], s[58:59], 0, v[84:85]
	v_add_f32_e32 v90, 1.0, v92
	v_rcp_f32_e32 v92, v90
	v_lshl_add_u64 v[90:91], v[84:85], 0, v[110:111]
	v_lshl_add_u64 v[84:85], v[84:85], 0, v[112:113]
	v_mul_f32_e32 v80, v92, v80
	v_mul_f32_e32 v80, v81, v80
	v_cvt_pk_bf16_f32 v80, v80, s0
	global_store_short v[88:89], v80, off offset:1536
	global_load_ushort v105, v[90:91], off offset:3424
	v_mov_b32_e32 v80, v100
	v_mov_b32_e32 v81, v94
	v_mov_b32_e32 v88, v101
	v_mov_b32_e32 v89, v95
	v_mov_b32_e32 v92, v86
	v_pk_mul_f32 v[80:81], v[80:81], v[80:81]
	v_pk_mul_f32 v[88:89], v[88:89], v[88:89]
	v_pk_mul_f32 v[92:93], v[92:93], v[92:93]
	v_mov_b32_e32 v102, v88
	v_mov_b32_e32 v103, v80
	v_mov_b32_e32 v80, v89
	v_mov_b32_e32 v88, v98
	v_mov_b32_e32 v89, v92
	v_pk_add_f32 v[80:81], v[102:103], v[80:81]
	v_mov_b32_e32 v92, v99
	v_pk_add_f32 v[80:81], v[80:81], v[88:89]
	v_and_b32_e32 v103, 0xffff0000, v129
	v_pk_add_f32 v[80:81], v[80:81], v[92:93]
	ds_swizzle_b32 v89, v81 offset:swizzle(SWAP,1)
	ds_swizzle_b32 v88, v80 offset:swizzle(SWAP,1)
	v_mov_b32_e32 v93, v211
	v_lshlrev_b32_e32 v92, 11, v104
	s_waitcnt lgkmcnt(0)
	v_pk_add_f32 v[80:81], v[80:81], v[88:89]
	ds_swizzle_b32 v89, v81 offset:swizzle(SWAP,2)
	ds_swizzle_b32 v88, v80 offset:swizzle(SWAP,2)
	s_waitcnt lgkmcnt(0)
	v_pk_add_f32 v[80:81], v[80:81], v[88:89]
	ds_swizzle_b32 v89, v81 offset:swizzle(SWAP,4)
	ds_swizzle_b32 v88, v80 offset:swizzle(SWAP,4)
	s_waitcnt lgkmcnt(0)
	v_pk_add_f32 v[80:81], v[80:81], v[88:89]
	ds_swizzle_b32 v89, v81 offset:swizzle(SWAP,8)
	ds_swizzle_b32 v88, v80 offset:swizzle(SWAP,8)
	s_waitcnt lgkmcnt(0)
	v_pk_add_f32 v[80:81], v[80:81], v[88:89]
	s_nop 0
	v_pk_fma_f32 v[80:81], v[80:81], s[6:7], v[116:117] op_sel_hi:[1,0,0]
	s_waitcnt vmcnt(0)
; __device__ __forceinline__ unsigned cvtpk(float lo, float hi) { f32x2_t v = {lo, hi}; bf16x2_t b = __builtin_convertvector(v, bf16x2_t); return __builtin_bit_cast(unsigned, b); }
; template <int X> __device__ __forceinline__ float swz_xor(float v) { return __int_as_float(__builtin_amdgcn_ds_swizzle(__float_as_int(v), (X << 10) | 0x1F)); }
; template <bool GLA>
; __device__ __forceinline__ void chunk_tile(const ChunkRaw& raw, const bf16x8 (&wfr)[2], const f32x4 (&bfr)[2], int h, int it, int row, int kq, float lg, float (&carry)[8], float (&bq)[8], float (&qv)[8], float (&kv)[8]) {
;     ...
; #pragma unroll
;         for (int j = 0; j < 4; ++j) {
;             qv[j] = (q[j] * cc[j] - q[4 + j] * ss[j]) * qs; qv[4 + j] = (q[j] * ss[j] + q[4 + j] * cc[j]) * qs;
;             kv[j] = k[j] * cc[j] - k[4 + j] * ss[j];        kv[4 + j] = k[j] * ss[j] + k[4 + j] * cc[j];
;         }
; #pragma unroll
;         for (int j = 0; j < 8; ++j) { bq[j] = (float)(16 * it + row + 1) * lg; carry[j] = 64.0f * lg; }
; template <bool GLA>
; __device__ __forceinline__ void chunk_pass_c(const ChunkIn& ci, const float* wgl, int unit, unsigned char* wl, int lane, const float* Sb, const float* ng, bf16_t* omix) {
;     ...
;     for (int it = 0; it < 4; ++it) {
;         f32x4 st[4];
; #pragma unroll
;         for (int jt = 0; jt < 4; ++jt) {
;             const f32x4 z = {0.f, 0.f, 0.f, 0.f};
;             if (jt < it) st[jt] = __builtin_amdgcn_mfma_f32_16x16x32_bf16(kf[jt], qf[it], z, 0, 0, 0);
;             else if (jt > it) st[jt] = __builtin_amdgcn_mfma_f32_16x16x32_bf16(kb[jt], qb[it], z, 0, 0, 0);
;     ...
; #pragma unroll
;         for (int r = 0; r < 4; ++r) {
;             ss[r] += swz_xor<1>(ss[r]); ss[r] += swz_xor<2>(ss[r]); ss[r] += swz_xor<4>(ss[r]); ss[r] += swz_xor<8>(ss[r]);
;             const float rs = rsqrtf(ss[r] * (1.0f / 64.0f) + EPS);
;             const int t = t0 + 16 * it + 4 * kq + r;
; #pragma unroll
;             for (int et = 0; et < 4; ++et) {
;                 const int e = 16 * et + row;
;                 const float gt = __uint_as_float((unsigned)ci.proj[(size_t)t * DINP + gcol + e] << 16);
;                 const float val = o[et][r] * rs * gn[et] * pg8::silu_f(gt);
;                 omix[(size_t)t * 1024 + ocol + e] = (bf16_t)(cvtpk(val, 0.f) & 0xffffu);
;             }
;         }
	v_lshlrev_b32_e32 v98, 16, v105
	v_mul_f32_e32 v88, 0x4b800000, v81
	v_cmp_gt_f32_e64 s[48:49], s96, v81
	s_nop 1
	v_cndmask_b32_e64 v81, v81, v88, s[48:49]
	v_mul_f32_e32 v88, 0xbfb8aa3b, v98
	v_exp_f32_e32 v99, v88
	v_rsq_f32_e32 v81, v81
	v_lshl_add_u64 v[88:89], s[60:61], 0, v[92:93]
	v_lshl_add_u64 v[92:93], v[88:89], 0, v[110:111]
	v_add_f32_e32 v99, 1.0, v99
	v_rcp_f32_e32 v99, v99
	v_mul_f32_e32 v102, 0x45800000, v81
	v_cndmask_b32_e64 v81, v81, v102, s[48:49]
	v_mul_f32_e32 v100, v100, v81
	v_mul_f32_e32 v100, v115, v100
	v_mul_f32_e32 v98, v99, v98
	v_mul_f32_e32 v98, v98, v100
	v_cvt_pk_bf16_f32 v98, v98, s0
	global_store_short v[92:93], v98, off offset:1536
	global_load_ushort v98, v[90:91], off offset:3456
	v_mul_f32_e32 v94, v94, v81
	v_mul_f32_e32 v94, v161, v94
	v_mul_f32_e32 v86, v86, v81
	v_mul_f32_e32 v86, v160, v86
	v_mul_f32_e32 v81, v82, v81
	v_mul_f32_e32 v81, v159, v81
	v_lshl_add_u64 v[88:89], v[88:89], 0, v[112:113]
	v_lshlrev_b32_e32 v102, 16, v129
	v_cmp_gt_f32_e64 s[48:49], s96, v80
	s_waitcnt vmcnt(0)
	v_lshlrev_b32_e32 v98, 16, v98
	v_mul_f32_e32 v99, 0xbfb8aa3b, v98
	v_exp_f32_e32 v99, v99
	s_nop 0
	v_add_f32_e32 v99, 1.0, v99
	v_rcp_f32_e32 v99, v99
	s_nop 0
	v_mul_f32_e32 v98, v99, v98
	v_mul_f32_e32 v94, v94, v98
	v_cvt_pk_bf16_f32 v94, v94, s0
	global_store_short v[92:93], v94, off offset:1568
	global_load_ushort v90, v[90:91], off offset:3488
	v_lshlrev_b32_e32 v98, 16, v131
	v_and_b32_e32 v99, 0xffff0000, v131
	s_waitcnt vmcnt(0)
	v_lshlrev_b32_e32 v90, 16, v90
	v_mul_f32_e32 v91, 0xbfb8aa3b, v90
	v_exp_f32_e32 v91, v91
	s_nop 0
	v_add_f32_e32 v91, 1.0, v91
	v_rcp_f32_e32 v91, v91
	s_nop 0
	v_mul_f32_e32 v90, v91, v90
	v_mul_f32_e32 v86, v86, v90
	v_cvt_pk_bf16_f32 v86, v86, s0
	global_store_short v[92:93], v86, off offset:1600
	global_load_ushort v84, v[84:85], off offset:3424
	v_or_b32_e32 v86, 3, v154
	v_mov_b32_e32 v85, v211
	s_waitcnt vmcnt(0)
	v_lshlrev_b32_e32 v90, 16, v84
	v_mul_f32_e32 v84, 0xbfb8aa3b, v90
	v_exp_f32_e32 v91, v84
	v_lshlrev_b32_e32 v84, 12, v86
	v_lshl_add_u64 v[84:85], s[58:59], 0, v[84:85]
	v_lshl_add_u64 v[92:93], v[84:85], 0, v[110:111]
	v_add_f32_e32 v91, 1.0, v91
	v_rcp_f32_e32 v91, v91
	s_nop 0
	v_mul_f32_e32 v82, v91, v90
	v_mul_f32_e32 v81, v81, v82
	v_cvt_pk_bf16_f32 v81, v81, s0
	global_store_short v[88:89], v81, off offset:1536
	global_load_ushort v81, v[92:93], off offset:3424
	v_mov_b32_e32 v89, v211
	v_lshlrev_b32_e32 v88, 11, v86
	v_mul_f32_e32 v82, 0xbfb8aa3b, v163
	v_lshl_add_u64 v[142:143], s[60:61], 0, v[88:89]
	v_exp_f32_e32 v82, v82
	v_lshlrev_b32_e32 v88, 16, v130
	v_and_b32_e32 v89, 0xffff0000, v130
	v_lshlrev_b32_e32 v90, 16, v128
	v_and_b32_e32 v91, 0xffff0000, v128
	v_pk_mul_f32 v[104:105], v[68:69], v[88:89]
	v_pk_mul_f32 v[68:69], v[68:69], v[90:91]
	v_pk_mul_f32 v[128:129], v[70:71], v[98:99]
	v_pk_mul_f32 v[70:71], v[70:71], v[102:103]
	v_pk_fma_f32 v[90:91], v[64:65], v[90:91], v[104:105]
	v_pk_fma_f32 v[64:65], v[64:65], v[88:89], v[68:69] neg_lo:[0,0,1] neg_hi:[0,0,1]
	v_pk_fma_f32 v[68:69], v[66:67], v[102:103], v[128:129]
	v_pk_fma_f32 v[66:67], v[66:67], v[98:99], v[70:71] neg_lo:[0,0,1] neg_hi:[0,0,1]
	v_pk_mul_f32 v[70:71], v[90:91], s[8:9] op_sel_hi:[1,0]
	v_pk_mul_f32 v[64:65], v[64:65], s[8:9] op_sel_hi:[1,0]
	v_pk_mul_f32 v[68:69], v[68:69], s[8:9] op_sel_hi:[1,0]
	v_pk_mul_f32 v[66:67], v[66:67], s[8:9] op_sel_hi:[1,0]
	v_pk_mul_f32 v[88:89], v[82:83], v[136:137] op_sel_hi:[0,1]
	v_pk_mul_f32 v[98:99], v[82:83], v[134:135] op_sel_hi:[0,1]
	v_pk_mul_f32 v[102:103], v[82:83], v[140:141] op_sel_hi:[0,1]
	v_pk_mul_f32 v[104:105], v[82:83], v[138:139] op_sel_hi:[0,1]
	v_pk_mul_f32 v[128:129], v[82:83], v[64:65] op_sel_hi:[0,1]
	v_pk_mul_f32 v[134:135], v[82:83], v[70:71] op_sel_hi:[0,1]
	v_pk_mul_f32 v[136:137], v[82:83], v[66:67] op_sel_hi:[0,1]
	v_pk_mul_f32 v[138:139], v[82:83], v[68:69] op_sel_hi:[0,1]
	v_mul_f32_e32 v82, 0x4b800000, v80
	v_cndmask_b32_e64 v80, v80, v82, s[48:49]
	v_rsq_f32_e32 v80, v80
	v_pk_mul_f32 v[90:91], v[132:133], v[64:65] op_sel_hi:[0,1]
	v_pk_mul_f32 v[130:131], v[132:133], v[70:71] op_sel_hi:[0,1]
	v_pk_mul_f32 v[70:71], v[132:133], v[66:67] op_sel_hi:[0,1]
	v_mul_f32_e32 v86, 0x45800000, v80
	v_pk_mul_f32 v[66:67], v[132:133], v[68:69] op_sel_hi:[0,1]
	v_cndmask_b32_e64 v132, v80, v86, s[48:49]
	v_mul_f32_e32 v80, v101, v132
	v_mul_f32_e32 v80, v115, v80
	v_lshl_add_u64 v[144:145], v[142:143], 0, v[110:111]
	v_cvt_pk_bf16_f32 v64, v88, v89
	v_cvt_pk_bf16_f32 v69, v70, v71
	v_cvt_pk_bf16_f32 v71, v66, v67
	v_cvt_pk_bf16_f32 v65, v102, v103
	v_cvt_pk_bf16_f32 v66, v98, v99
	v_cvt_pk_bf16_f32 v67, v104, v105
	v_cvt_pk_bf16_f32 v68, v90, v91
	v_cvt_pk_bf16_f32 v70, v130, v131
	v_cvt_pk_bf16_f32 v128, v128, v129
	v_cvt_pk_bf16_f32 v129, v136, v137
	v_cvt_pk_bf16_f32 v130, v134, v135
	v_cvt_pk_bf16_f32 v131, v138, v139
	v_mfma_f32_16x16x32_bf16 v[134:137], v[64:67], v[68:71], 0
	v_mul_f32_e32 v83, v83, v132
	v_mul_f32_e32 v83, v159, v83
	s_waitcnt vmcnt(0)
	v_lshlrev_b32_e32 v81, 16, v81
	v_mul_f32_e32 v82, 0xbfb8aa3b, v81
	v_exp_f32_e32 v82, v82
	v_mfma_f32_16x16x32_bf16 v[72:75], v[72:75], v[128:131], 0
	v_add_f32_e32 v82, 1.0, v82
	v_rcp_f32_e32 v82, v82
	v_mfma_f32_16x16x32_bf16 v[98:101], v[12:15], v[128:131], 0
	s_nop 4
	v_cndmask_b32_e64 v86, v136, v74, s[44:45]
	v_cndmask_b32_e64 v129, v137, v75, s[46:47]
	v_mul_f32_e32 v81, v82, v81
	v_mul_f32_e32 v80, v81, v80
	v_cvt_pk_bf16_f32 v80, v80, s0
	global_store_short v[144:145], v80, off offset:1536
	global_load_ushort v80, v[92:93], off offset:3456
	v_mul_f32_e32 v82, v95, v132
	v_mul_f32_e32 v82, v161, v82
	v_cvt_pk_bf16_f32 v129, v86, v129
	v_mfma_f32_16x16x32_bf16 v[88:91], v[8:11], v[68:71], 0
	v_cvt_pk_bf16_f32 v130, v98, v99
	v_cvt_pk_bf16_f32 v131, v100, v101
	s_waitcnt vmcnt(0)
; template <bool GLA>
; __device__ __forceinline__ void chunk_pass_c(const ChunkIn& ci, const float* wgl, int unit, unsigned char* wl, int lane, const float* Sb, const float* ng, bf16_t* omix) {
;     ...
;     for (int it = 0; it < 4; ++it) {
;         f32x4 st[4];
; #pragma unroll
;         for (int jt = 0; jt < 4; ++jt) {
;             const f32x4 z = {0.f, 0.f, 0.f, 0.f};
;             if (jt < it) st[jt] = __builtin_amdgcn_mfma_f32_16x16x32_bf16(kf[jt], qf[it], z, 0, 0, 0);
;             else if (jt > it) st[jt] = __builtin_amdgcn_mfma_f32_16x16x32_bf16(kb[jt], qb[it], z, 0, 0, 0);
;             else {
;                 const f32x4 lo = __builtin_amdgcn_mfma_f32_16x16x32_bf16(kf[jt], qf[it], z, 0, 0, 0), up = __builtin_amdgcn_mfma_f32_16x16x32_bf16(kb[jt], qb[it], z, 0, 0, 0);
; #pragma unroll
;                 for (int r = 0; r < 4; ++r) st[jt][r] = (4 * kq + r <= row) ? lo[r] : up[r];
;             }
;         }
;         bf16x8 af[2];
; #pragma unroll
;         for (int p = 0; p < 2; ++p)
;             af[p] = __builtin_bit_cast(bf16x8, (u32x4){cvtpk(st[2 * p][0], st[2 * p][1]), cvtpk(st[2 * p][2], st[2 * p][3]), cvtpk(st[2 * p + 1][0], st[2 * p + 1][1]), cvtpk(st[2 * p + 1][2], st[2 * p + 1][3])});
;         f32x4 o[4]; float ss[4] = {0.f, 0.f, 0.f, 0.f};
; #pragma unroll
;         for (int et = 0; et < 4; ++et) {
;             f32x4 acc = {0.f, 0.f, 0.f, 0.f};
;             acc = __builtin_amdgcn_mfma_f32_16x16x32_bf16(af[0], vfr[et][0], acc, 0, 0, 0);
;             acc = __builtin_amdgcn_mfma_f32_16x16x32_bf16(af[1], vfr[et][1], acc, 0, 0, 0);
;             acc = __builtin_amdgcn_mfma_f32_16x16x32_bf16(qf[it], sfr[et], acc, 0, 0, 0);
;             o[et] = acc;
; #pragma unroll
;             for (int r = 0; r < 4; ++r) ss[r] += acc[r] * acc[r];
;         }
; #pragma unroll
;         for (int r = 0; r < 4; ++r) {
;             ss[r] += swz_xor<1>(ss[r]); ss[r] += swz_xor<2>(ss[r]); ss[r] += swz_xor<4>(ss[r]); ss[r] += swz_xor<8>(ss[r]);
;             const float rs = rsqrtf(ss[r] * (1.0f / 64.0f) + EPS);
;             const int t = t0 + 16 * it + 4 * kq + r;
; #pragma unroll
;             for (int et = 0; et < 4; ++et) {
;                 const int e = 16 * et + row;
;                 const float gt = __uint_as_float((unsigned)ci.proj[(size_t)t * DINP + gcol + e] << 16);
;                 const float val = o[et][r] * rs * gn[et] * pg8::silu_f(gt);
	v_lshlrev_b32_e32 v80, 16, v80
	v_mul_f32_e32 v81, 0xbfb8aa3b, v80
	v_exp_f32_e32 v81, v81
	v_mfma_f32_16x16x32_bf16 v[102:105], v[76:79], v[68:71], 0
	s_nop 0
	v_cvt_pk_bf16_f32 v88, v88, v89
	v_cvt_pk_bf16_f32 v89, v90, v91
	v_add_f32_e32 v81, 1.0, v81
	v_rcp_f32_e32 v81, v81
	s_nop 0
	v_mul_f32_e32 v80, v81, v80
	v_mul_f32_e32 v80, v82, v80
	v_cvt_pk_bf16_f32 v80, v80, s0
	global_store_short v[144:145], v80, off offset:1568
	global_load_ushort v80, v[92:93], off offset:3488
	v_cndmask_b32_e32 v81, v134, v72, vcc
	v_cndmask_b32_e64 v82, v73, v135, s[42:43]
	v_cvt_pk_bf16_f32 v128, v81, v82
	v_cvt_pk_bf16_f32 v90, v102, v103
	v_cvt_pk_bf16_f32 v91, v104, v105
	s_waitcnt vmcnt(0)
	v_lshlrev_b32_e32 v82, 16, v80
	v_mul_f32_e32 v80, 0xbfb8aa3b, v82
	v_exp_f32_e32 v86, v80
	v_lshl_add_u64 v[80:81], v[84:85], 0, v[112:113]
	v_mul_f32_e32 v85, v87, v132
	v_mul_f32_e32 v85, v160, v85
	v_add_f32_e32 v84, 1.0, v86
	v_rcp_f32_e32 v84, v84
	v_mfma_f32_16x16x32_bf16 v[102:105], v[88:91], v[28:31], 0
	v_mul_f32_e32 v82, v84, v82
	v_mul_f32_e32 v82, v85, v82
	v_cvt_pk_bf16_f32 v82, v82, s0
	global_store_short v[144:145], v82, off offset:1600
	global_load_ushort v82, v[80:81], off offset:3424
	v_mfma_f32_16x16x32_bf16 v[92:95], v[88:91], v[44:47], 0
	v_mov_b32_e32 v81, v211
	s_waitcnt vmcnt(0)
	v_lshlrev_b32_e32 v82, 16, v82
	v_mfma_f32_16x16x32_bf16 v[72:75], v[88:91], v[56:59], 0
	v_mul_f32_e32 v84, 0xbfb8aa3b, v82
	v_mfma_f32_16x16x32_bf16 v[88:91], v[88:91], v[60:63], 0
	v_mfma_f32_16x16x32_bf16 v[98:101], v[128:131], v[20:23], v[102:105]
	v_mfma_f32_16x16x32_bf16 v[92:95], v[128:131], v[32:35], v[92:95]
	v_mfma_f32_16x16x32_bf16 v[102:105], v[128:131], v[48:51], v[88:91]
	v_mfma_f32_16x16x32_bf16 v[88:91], v[68:71], v[24:27], v[98:101]
	s_nop 4
	v_exp_f32_e32 v100, v84
	v_mfma_f32_16x16x32_bf16 v[84:87], v[68:71], v[16:19], v[92:95]
	s_nop 2
	v_add_f32_e32 v94, 1.0, v100
	v_rcp_f32_e32 v94, v94
	v_mfma_f32_16x16x32_bf16 v[72:75], v[128:131], v[52:55], v[72:75]
	v_or_b32_e32 v128, s4, v97
	v_lshlrev_b32_e32 v80, 12, v128
	v_mul_f32_e32 v82, v94, v82
	v_mul_f32_e32 v82, v83, v82
	v_lshl_add_u64 v[80:81], s[58:59], 0, v[80:81]
	v_lshl_add_u64 v[92:93], v[142:143], 0, v[112:113]
	v_cvt_pk_bf16_f32 v82, v82, s0
	v_lshl_add_u64 v[98:99], v[80:81], 0, v[110:111]
	global_store_short v[92:93], v82, off offset:1536
	global_load_ushort v129, v[98:99], off offset:3424
	v_mfma_f32_16x16x32_bf16 v[72:75], v[68:71], v[36:39], v[72:75]
	v_mov_b32_e32 v82, v88
	v_mov_b32_e32 v83, v84
	v_mov_b32_e32 v92, v89
	v_mfma_f32_16x16x32_bf16 v[68:71], v[68:71], v[40:43], v[102:105]
	v_mov_b32_e32 v93, v85
	s_nop 2
	v_mov_b32_e32 v94, v72
	v_mov_b32_e32 v100, v73
	v_pk_mul_f32 v[82:83], v[82:83], v[82:83]
	v_pk_mul_f32 v[92:93], v[92:93], v[92:93]
	v_mov_b32_e32 v95, v68
	v_mov_b32_e32 v101, v69
	v_pk_mul_f32 v[94:95], v[94:95], v[94:95]
	v_pk_mul_f32 v[100:101], v[100:101], v[100:101]
	v_mov_b32_e32 v102, v92
	v_mov_b32_e32 v103, v82
	v_mov_b32_e32 v82, v93
	v_mov_b32_e32 v92, v100
	v_mov_b32_e32 v93, v94
	v_pk_add_f32 v[82:83], v[102:103], v[82:83]
	v_mov_b32_e32 v94, v101
	v_pk_add_f32 v[82:83], v[82:83], v[92:93]
	v_lshl_add_u64 v[80:81], v[80:81], 0, v[112:113]
	v_pk_add_f32 v[82:83], v[82:83], v[94:95]
	ds_swizzle_b32 v93, v83 offset:swizzle(SWAP,1)
	ds_swizzle_b32 v92, v82 offset:swizzle(SWAP,1)
	v_mov_b32_e32 v95, v211
	v_lshlrev_b32_e32 v94, 11, v128
	s_waitcnt lgkmcnt(0)
	v_pk_add_f32 v[82:83], v[82:83], v[92:93]
	ds_swizzle_b32 v93, v83 offset:swizzle(SWAP,2)
	ds_swizzle_b32 v92, v82 offset:swizzle(SWAP,2)
	s_waitcnt lgkmcnt(0)
	v_pk_add_f32 v[82:83], v[82:83], v[92:93]
	ds_swizzle_b32 v93, v83 offset:swizzle(SWAP,4)
	ds_swizzle_b32 v92, v82 offset:swizzle(SWAP,4)
	s_waitcnt lgkmcnt(0)
	v_pk_add_f32 v[82:83], v[82:83], v[92:93]
	ds_swizzle_b32 v93, v83 offset:swizzle(SWAP,8)
	ds_swizzle_b32 v92, v82 offset:swizzle(SWAP,8)
	s_waitcnt lgkmcnt(0)
	v_pk_add_f32 v[82:83], v[82:83], v[92:93]
	s_nop 0
	v_pk_fma_f32 v[82:83], v[82:83], s[6:7], v[116:117] op_sel_hi:[1,0,0]
	s_waitcnt vmcnt(0)
	v_lshlrev_b32_e32 v100, 16, v129
	v_mul_f32_e32 v92, 0x4b800000, v83
	v_cmp_gt_f32_e64 s[48:49], s96, v83
	s_nop 1
	v_cndmask_b32_e64 v83, v83, v92, s[48:49]
	v_mul_f32_e32 v92, 0xbfb8aa3b, v100
	v_exp_f32_e32 v101, v92
	v_rsq_f32_e32 v83, v83
	v_lshl_add_u64 v[92:93], s[60:61], 0, v[94:95]
	v_lshl_add_u64 v[94:95], v[92:93], 0, v[110:111]
	v_add_f32_e32 v101, 1.0, v101
	v_rcp_f32_e32 v101, v101
	v_mul_f32_e32 v102, 0x45800000, v83
	v_cndmask_b32_e64 v83, v83, v102, s[48:49]
	v_mul_f32_e32 v88, v88, v83
	v_mul_f32_e32 v88, v115, v88
	v_mul_f32_e32 v100, v101, v100
	v_mul_f32_e32 v88, v100, v88
	v_cvt_pk_bf16_f32 v88, v88, s0
	global_store_short v[94:95], v88, off offset:1536
	global_load_ushort v88, v[98:99], off offset:3456
	v_mul_f32_e32 v84, v84, v83
	v_mul_f32_e32 v84, v161, v84
	v_mul_f32_e32 v72, v72, v83
	v_mul_f32_e32 v72, v160, v72
	v_mul_f32_e32 v68, v68, v83
	v_mul_f32_e32 v68, v159, v68
	v_lshl_add_u64 v[92:93], v[92:93], 0, v[112:113]
	v_cmp_gt_f32_e64 s[48:49], s96, v82
	s_waitcnt vmcnt(0)
	v_lshlrev_b32_e32 v88, 16, v88
	v_mul_f32_e32 v100, 0xbfb8aa3b, v88
	v_exp_f32_e32 v100, v100
	s_nop 0
	v_add_f32_e32 v100, 1.0, v100
	v_rcp_f32_e32 v100, v100
	s_nop 0
	v_mul_f32_e32 v88, v100, v88
	v_mul_f32_e32 v84, v88, v84
	v_cvt_pk_bf16_f32 v84, v84, s0
	global_store_short v[94:95], v84, off offset:1568
	global_load_ushort v84, v[98:99], off offset:3488
	s_waitcnt vmcnt(0)
; __device__ __forceinline__ unsigned cvtpk(float lo, float hi) { f32x2_t v = {lo, hi}; bf16x2_t b = __builtin_convertvector(v, bf16x2_t); return __builtin_bit_cast(unsigned, b); }
; template <int X> __device__ __forceinline__ float swz_xor(float v) { return __int_as_float(__builtin_amdgcn_ds_swizzle(__float_as_int(v), (X << 10) | 0x1F)); }
; __device__ __forceinline__ float silu_f(float g) { return g * __builtin_amdgcn_rcpf(1.0f + __expf(-g)); }
; template <bool GLA>
; __device__ __forceinline__ void chunk_pass_c(const ChunkIn& ci, const float* wgl, int unit, unsigned char* wl, int lane, const float* Sb, const float* ng, bf16_t* omix) {
;     ...
; #pragma unroll
;         for (int r = 0; r < 4; ++r) {
;             ss[r] += swz_xor<1>(ss[r]); ss[r] += swz_xor<2>(ss[r]); ss[r] += swz_xor<4>(ss[r]); ss[r] += swz_xor<8>(ss[r]);
;             const float rs = rsqrtf(ss[r] * (1.0f / 64.0f) + EPS);
;             const int t = t0 + 16 * it + 4 * kq + r;
; #pragma unroll
;             for (int et = 0; et < 4; ++et) {
;                 const int e = 16 * et + row;
;                 const float gt = __uint_as_float((unsigned)ci.proj[(size_t)t * DINP + gcol + e] << 16);
;                 const float val = o[et][r] * rs * gn[et] * pg8::silu_f(gt);
;                 omix[(size_t)t * 1024 + ocol + e] = (bf16_t)(cvtpk(val, 0.f) & 0xffffu);
;             }
;         }
	v_lshlrev_b32_e32 v84, 16, v84
	v_mul_f32_e32 v88, 0xbfb8aa3b, v84
	v_exp_f32_e32 v88, v88
	s_nop 0
	v_add_f32_e32 v88, 1.0, v88
	v_rcp_f32_e32 v88, v88
	s_nop 0
	v_mul_f32_e32 v84, v88, v84
	v_mul_f32_e32 v72, v72, v84
	v_cvt_pk_bf16_f32 v72, v72, s0
	global_store_short v[94:95], v72, off offset:1600
	global_load_ushort v72, v[80:81], off offset:3424
	v_or_b32_e32 v84, 1, v128
	v_mov_b32_e32 v81, v211
	s_waitcnt vmcnt(0)
	v_lshlrev_b32_e32 v72, 16, v72
	v_mul_f32_e32 v80, 0xbfb8aa3b, v72
	v_exp_f32_e32 v88, v80
	v_lshlrev_b32_e32 v80, 12, v84
	v_lshl_add_u64 v[80:81], s[58:59], 0, v[80:81]
	v_lshl_add_u64 v[94:95], v[80:81], 0, v[110:111]
	v_add_f32_e32 v88, 1.0, v88
	v_rcp_f32_e32 v88, v88
	v_lshl_add_u64 v[80:81], v[80:81], 0, v[112:113]
	v_mul_f32_e32 v72, v88, v72
	v_mul_f32_e32 v68, v68, v72
	v_cvt_pk_bf16_f32 v68, v68, s0
	global_store_short v[92:93], v68, off offset:1536
	global_load_ushort v68, v[94:95], off offset:3424
	v_mul_f32_e32 v72, 0x4b800000, v82
	v_cndmask_b32_e64 v72, v82, v72, s[48:49]
	v_lshlrev_b32_e32 v92, 11, v84
	v_rsq_f32_e32 v72, v72
	v_mov_b32_e32 v93, v211
	v_mul_f32_e32 v88, 0x45800000, v72
	v_cndmask_b32_e64 v88, v72, v88, s[48:49]
	v_mul_f32_e32 v72, v89, v88
	v_mul_f32_e32 v72, v115, v72
	v_mul_f32_e32 v73, v73, v88
	v_mul_f32_e32 v73, v160, v73
	v_mul_f32_e32 v69, v69, v88
	v_mul_f32_e32 v69, v159, v69
	v_mov_b32_e32 v89, v71
	s_waitcnt vmcnt(0)
	v_lshlrev_b32_e32 v68, 16, v68
	v_mul_f32_e32 v82, 0xbfb8aa3b, v68
	v_exp_f32_e32 v84, v82
	v_lshl_add_u64 v[82:83], s[60:61], 0, v[92:93]
	v_lshl_add_u64 v[92:93], v[82:83], 0, v[110:111]
	v_add_f32_e32 v84, 1.0, v84
	v_rcp_f32_e32 v84, v84
	s_nop 0
	v_mul_f32_e32 v68, v84, v68
	v_mul_f32_e32 v68, v68, v72
	v_cvt_pk_bf16_f32 v68, v68, s0
	global_store_short v[92:93], v68, off offset:1536
	global_load_ushort v68, v[94:95], off offset:3456
	v_mul_f32_e32 v84, v85, v88
	v_mul_f32_e32 v84, v161, v84
	v_mov_b32_e32 v85, v70
	v_mov_b32_e32 v88, v75
	v_pk_mul_f32 v[88:89], v[88:89], v[88:89]
	s_waitcnt vmcnt(0)
	v_lshlrev_b32_e32 v68, 16, v68
	v_mul_f32_e32 v72, 0xbfb8aa3b, v68
	v_exp_f32_e32 v72, v72
	s_nop 0
	v_add_f32_e32 v72, 1.0, v72
	v_rcp_f32_e32 v72, v72
	s_nop 0
	v_mul_f32_e32 v68, v72, v68
	v_mul_f32_e32 v68, v84, v68
	v_cvt_pk_bf16_f32 v68, v68, s0
	global_store_short v[92:93], v68, off offset:1568
	global_load_ushort v68, v[94:95], off offset:3488
	v_or_b32_e32 v94, 2, v128
	s_waitcnt vmcnt(0)
	v_lshlrev_b32_e32 v68, 16, v68
	v_mul_f32_e32 v72, 0xbfb8aa3b, v68
	v_exp_f32_e32 v72, v72
	s_nop 0
	v_add_f32_e32 v72, 1.0, v72
	v_rcp_f32_e32 v72, v72
	s_nop 0
	v_mul_f32_e32 v68, v72, v68
	v_mul_f32_e32 v68, v73, v68
	v_cvt_pk_bf16_f32 v68, v68, s0
	global_store_short v[92:93], v68, off offset:1600
	global_load_ushort v68, v[80:81], off offset:3424
	v_lshl_add_u64 v[80:81], v[82:83], 0, v[112:113]
	v_mov_b32_e32 v73, v211
	s_waitcnt vmcnt(0)
	v_lshlrev_b32_e32 v68, 16, v68
	v_mul_f32_e32 v72, 0xbfb8aa3b, v68
	v_exp_f32_e32 v84, v72
	v_lshlrev_b32_e32 v72, 12, v94
	v_lshl_add_u64 v[72:73], s[58:59], 0, v[72:73]
	v_add_f32_e32 v82, 1.0, v84
	v_rcp_f32_e32 v84, v82
	v_lshl_add_u64 v[82:83], v[72:73], 0, v[110:111]
	v_lshl_add_u64 v[72:73], v[72:73], 0, v[112:113]
	v_mul_f32_e32 v68, v84, v68
	v_mul_f32_e32 v68, v69, v68
	v_cvt_pk_bf16_f32 v68, v68, s0
	global_store_short v[80:81], v68, off offset:1536
	global_load_ushort v95, v[82:83], off offset:3424
	v_mov_b32_e32 v68, v90
	v_mov_b32_e32 v69, v86
	v_mov_b32_e32 v80, v91
	v_mov_b32_e32 v81, v87
	v_mov_b32_e32 v84, v74
	v_pk_mul_f32 v[68:69], v[68:69], v[68:69]
	v_pk_mul_f32 v[80:81], v[80:81], v[80:81]
	v_pk_mul_f32 v[84:85], v[84:85], v[84:85]
	v_mov_b32_e32 v92, v80
	v_mov_b32_e32 v93, v68
	v_mov_b32_e32 v68, v81
	v_mov_b32_e32 v80, v88
	v_mov_b32_e32 v81, v84
	v_pk_add_f32 v[68:69], v[92:93], v[68:69]
	v_mov_b32_e32 v84, v89
	v_pk_add_f32 v[68:69], v[68:69], v[80:81]
	v_and_b32_e32 v93, 0xffff0000, v107
	v_pk_add_f32 v[68:69], v[68:69], v[84:85]
	ds_swizzle_b32 v81, v69 offset:swizzle(SWAP,1)
	ds_swizzle_b32 v80, v68 offset:swizzle(SWAP,1)
	v_mov_b32_e32 v85, v211
	v_lshlrev_b32_e32 v84, 11, v94
	s_waitcnt lgkmcnt(0)
	v_pk_add_f32 v[68:69], v[68:69], v[80:81]
	ds_swizzle_b32 v81, v69 offset:swizzle(SWAP,2)
	ds_swizzle_b32 v80, v68 offset:swizzle(SWAP,2)
	s_waitcnt lgkmcnt(0)
	v_pk_add_f32 v[68:69], v[68:69], v[80:81]
	ds_swizzle_b32 v81, v69 offset:swizzle(SWAP,4)
	ds_swizzle_b32 v80, v68 offset:swizzle(SWAP,4)
	s_waitcnt lgkmcnt(0)
	v_pk_add_f32 v[68:69], v[68:69], v[80:81]
	ds_swizzle_b32 v81, v69 offset:swizzle(SWAP,8)
	ds_swizzle_b32 v80, v68 offset:swizzle(SWAP,8)
	s_waitcnt lgkmcnt(0)
	v_pk_add_f32 v[68:69], v[68:69], v[80:81]
	s_nop 0
	v_pk_fma_f32 v[68:69], v[68:69], s[6:7], v[116:117] op_sel_hi:[1,0,0]
	s_waitcnt vmcnt(0)
	v_lshlrev_b32_e32 v88, 16, v95
	v_mul_f32_e32 v80, 0x4b800000, v69
	v_cmp_gt_f32_e64 s[48:49], s96, v69
	s_nop 1
	v_cndmask_b32_e64 v69, v69, v80, s[48:49]
	v_mul_f32_e32 v80, 0xbfb8aa3b, v88
	v_exp_f32_e32 v89, v80
	v_rsq_f32_e32 v69, v69
	v_lshl_add_u64 v[80:81], s[60:61], 0, v[84:85]
	v_lshl_add_u64 v[84:85], v[80:81], 0, v[110:111]
	v_add_f32_e32 v89, 1.0, v89
	v_rcp_f32_e32 v89, v89
	v_mul_f32_e32 v92, 0x45800000, v69
	v_cndmask_b32_e64 v69, v69, v92, s[48:49]
	v_mul_f32_e32 v90, v90, v69
	v_mul_f32_e32 v90, v115, v90
	v_mul_f32_e32 v88, v89, v88
	v_mul_f32_e32 v88, v88, v90
	v_cvt_pk_bf16_f32 v88, v88, s0
	global_store_short v[84:85], v88, off offset:1536
	global_load_ushort v88, v[82:83], off offset:3456
	v_mul_f32_e32 v86, v86, v69
	v_mul_f32_e32 v86, v161, v86
	v_mul_f32_e32 v74, v74, v69
	v_mul_f32_e32 v74, v160, v74
	v_mul_f32_e32 v69, v70, v69
	v_mul_f32_e32 v69, v159, v69
	v_lshl_add_u64 v[80:81], v[80:81], 0, v[112:113]
	v_cmp_gt_f32_e64 s[48:49], s96, v68
	v_lshlrev_b32_e32 v90, 16, v109
	v_lshlrev_b32_e32 v92, 16, v107
	s_waitcnt vmcnt(0)
; template <bool GLA>
; __device__ __forceinline__ void chunk_tile(const ChunkRaw& raw, const bf16x8 (&wfr)[2], const f32x4 (&bfr)[2], int h, int it, int row, int kq, float lg, float (&carry)[8], float (&bq)[8], float (&qv)[8], float (&kv)[8]) {
;     ...
; #pragma unroll
;         for (int j = 0; j < 4; ++j) {
;             qv[j] = (q[j] * cc[j] - q[4 + j] * ss[j]) * qs; qv[4 + j] = (q[j] * ss[j] + q[4 + j] * cc[j]) * qs;
;             kv[j] = k[j] * cc[j] - k[4 + j] * ss[j];        kv[4 + j] = k[j] * ss[j] + k[4 + j] * cc[j];
;         }
; #pragma unroll
;         for (int j = 0; j < 8; ++j) { bq[j] = (float)(16 * it + row + 1) * lg; carry[j] = 64.0f * lg; }
; template <bool GLA>
; __device__ __forceinline__ void chunk_pass_c(const ChunkIn& ci, const float* wgl, int unit, unsigned char* wl, int lane, const float* Sb, const float* ng, bf16_t* omix) {
;     ...
;     for (int it = 0; it < 4; ++it) {
;         f32x4 st[4];
; #pragma unroll
;         for (int jt = 0; jt < 4; ++jt) {
;             const f32x4 z = {0.f, 0.f, 0.f, 0.f};
;             if (jt < it) st[jt] = __builtin_amdgcn_mfma_f32_16x16x32_bf16(kf[jt], qf[it], z, 0, 0, 0);
;             else if (jt > it) st[jt] = __builtin_amdgcn_mfma_f32_16x16x32_bf16(kb[jt], qb[it], z, 0, 0, 0);
;             else {
;                 const f32x4 lo = __builtin_amdgcn_mfma_f32_16x16x32_bf16(kf[jt], qf[it], z, 0, 0, 0), up = __builtin_amdgcn_mfma_f32_16x16x32_bf16(kb[jt], qb[it], z, 0, 0, 0);
; #pragma unroll
;                 for (int r = 0; r < 4; ++r) st[jt][r] = (4 * kq + r <= row) ? lo[r] : up[r];
;             }
;         }
;         bf16x8 af[2];
; #pragma unroll
;         for (int p = 0; p < 2; ++p)
;     ...
; #pragma unroll
;         for (int r = 0; r < 4; ++r) {
;             ss[r] += swz_xor<1>(ss[r]); ss[r] += swz_xor<2>(ss[r]); ss[r] += swz_xor<4>(ss[r]); ss[r] += swz_xor<8>(ss[r]);
;             const float rs = rsqrtf(ss[r] * (1.0f / 64.0f) + EPS);
;             const int t = t0 + 16 * it + 4 * kq + r;
; #pragma unroll
;             for (int et = 0; et < 4; ++et) {
;                 const int e = 16 * et + row;
;                 const float gt = __uint_as_float((unsigned)ci.proj[(size_t)t * DINP + gcol + e] << 16);
;                 const float val = o[et][r] * rs * gn[et] * pg8::silu_f(gt);
;                 omix[(size_t)t * 1024 + ocol + e] = (bf16_t)(cvtpk(val, 0.f) & 0xffffu);
;             }
;         }
	v_lshlrev_b32_e32 v88, 16, v88
	v_mul_f32_e32 v89, 0xbfb8aa3b, v88
	v_exp_f32_e32 v89, v89
	s_nop 0
	v_add_f32_e32 v89, 1.0, v89
	v_rcp_f32_e32 v89, v89
	s_nop 0
	v_mul_f32_e32 v88, v89, v88
	v_mul_f32_e32 v86, v86, v88
	v_cvt_pk_bf16_f32 v86, v86, s0
	global_store_short v[84:85], v86, off offset:1568
	global_load_ushort v82, v[82:83], off offset:3488
	s_waitcnt vmcnt(0)
	v_lshlrev_b32_e32 v82, 16, v82
	v_mul_f32_e32 v83, 0xbfb8aa3b, v82
	v_exp_f32_e32 v83, v83
	s_nop 0
	v_add_f32_e32 v83, 1.0, v83
	v_rcp_f32_e32 v83, v83
	s_nop 0
	v_mul_f32_e32 v82, v83, v82
	v_mul_f32_e32 v74, v74, v82
	v_cvt_pk_bf16_f32 v74, v74, s0
	global_store_short v[84:85], v74, off offset:1600
	global_load_ushort v72, v[72:73], off offset:3424
	v_or_b32_e32 v74, 3, v128
	v_mov_b32_e32 v73, v211
	s_waitcnt vmcnt(0)
	v_lshlrev_b32_e32 v82, 16, v72
	v_mul_f32_e32 v72, 0xbfb8aa3b, v82
	v_exp_f32_e32 v83, v72
	v_lshlrev_b32_e32 v72, 12, v74
	v_lshl_add_u64 v[72:73], s[58:59], 0, v[72:73]
	v_lshl_add_u64 v[84:85], v[72:73], 0, v[110:111]
	v_add_f32_e32 v83, 1.0, v83
	v_rcp_f32_e32 v83, v83
	s_nop 0
	v_mul_f32_e32 v70, v83, v82
	v_mul_f32_e32 v69, v69, v70
	v_cvt_pk_bf16_f32 v69, v69, s0
	global_store_short v[80:81], v69, off offset:1536
	global_load_ushort v69, v[84:85], off offset:3424
	v_mul_f32_e32 v70, 0x4b800000, v68
	v_lshlrev_b32_e32 v80, 11, v74
	v_cndmask_b32_e64 v68, v68, v70, s[48:49]
	v_rsq_f32_e32 v70, v68
	v_mov_b32_e32 v81, v211
	v_and_b32_e32 v83, 0xffff0000, v106
	s_waitcnt vmcnt(0)
	v_lshlrev_b32_e32 v74, 16, v69
	v_mul_f32_e32 v68, 0xbfb8aa3b, v74
	v_exp_f32_e32 v82, v68
	v_lshl_add_u64 v[68:69], s[60:61], 0, v[80:81]
	v_mul_f32_e32 v80, 0x45800000, v70
	v_cndmask_b32_e64 v86, v70, v80, s[48:49]
	v_add_f32_e32 v81, 1.0, v82
	v_rcp_f32_e32 v81, v81
	v_mul_f32_e32 v70, v91, v86
	v_mul_f32_e32 v70, v115, v70
	v_lshl_add_u64 v[88:89], v[68:69], 0, v[110:111]
	v_mul_f32_e32 v74, v81, v74
	v_mul_f32_e32 v70, v74, v70
	v_cvt_pk_bf16_f32 v70, v70, s0
	global_store_short v[88:89], v70, off offset:1536
	global_load_ushort v74, v[84:85], off offset:3456
	v_lshlrev_b32_e32 v80, 16, v108
	v_and_b32_e32 v81, 0xffff0000, v108
	v_lshlrev_b32_e32 v82, 16, v106
	v_and_b32_e32 v91, 0xffff0000, v109
	v_pk_mul_f32 v[94:95], v[4:5], v[80:81]
	v_pk_mul_f32 v[4:5], v[4:5], v[82:83]
	v_pk_mul_f32 v[98:99], v[6:7], v[90:91]
	v_pk_mul_f32 v[6:7], v[6:7], v[92:93]
	v_pk_fma_f32 v[82:83], v[0:1], v[82:83], v[94:95]
	v_pk_fma_f32 v[0:1], v[0:1], v[80:81], v[4:5] neg_lo:[0,0,1] neg_hi:[0,0,1]
	v_pk_fma_f32 v[4:5], v[2:3], v[92:93], v[98:99]
	v_pk_fma_f32 v[2:3], v[2:3], v[90:91], v[6:7] neg_lo:[0,0,1] neg_hi:[0,0,1]
	v_mul_f32_e32 v70, 0xbfb8aa3b, v162
	v_pk_mul_f32 v[80:81], v[82:83], s[8:9] op_sel_hi:[1,0]
	v_pk_mul_f32 v[82:83], v[0:1], s[8:9] op_sel_hi:[1,0]
	v_pk_mul_f32 v[94:95], v[4:5], s[8:9] op_sel_hi:[1,0]
	v_pk_mul_f32 v[98:99], v[2:3], s[8:9] op_sel_hi:[1,0]
	v_exp_f32_e32 v70, v70
	v_pk_mul_f32 v[0:1], v[118:119], v[82:83] op_sel_hi:[0,1]
	v_pk_mul_f32 v[2:3], v[118:119], v[80:81] op_sel_hi:[0,1]
	v_pk_mul_f32 v[4:5], v[118:119], v[98:99] op_sel_hi:[0,1]
	v_pk_mul_f32 v[6:7], v[118:119], v[94:95] op_sel_hi:[0,1]
	v_cvt_pk_bf16_f32 v0, v0, v1
	v_cvt_pk_bf16_f32 v1, v4, v5
	v_cvt_pk_bf16_f32 v2, v2, v3
	v_cvt_pk_bf16_f32 v3, v6, v7
	v_pk_mul_f32 v[90:91], v[70:71], v[122:123] op_sel_hi:[0,1]
	v_pk_mul_f32 v[92:93], v[70:71], v[120:121] op_sel_hi:[0,1]
	v_mfma_f32_16x16x32_bf16 v[4:7], v[8:11], v[0:3], 0
	v_mul_f32_e64 v100, v70, v126
	v_mul_f32_e64 v101, v70, v127
	v_pk_mul_f32 v[102:103], v[70:71], v[124:125] op_sel_hi:[0,1]
	v_pk_mul_f32 v[82:83], v[70:71], v[82:83] op_sel_hi:[0,1]
	v_pk_mul_f32 v[104:105], v[70:71], v[80:81] op_sel_hi:[0,1]
	v_cvt_pk_bf16_f32 v8, v90, v91
	v_cvt_pk_bf16_f32 v10, v92, v93
	v_pk_mul_f32 v[90:91], v[70:71], v[98:99] op_sel_hi:[0,1]
	v_pk_mul_f32 v[92:93], v[70:71], v[94:95] op_sel_hi:[0,1]
	v_cvt_pk_bf16_f32 v4, v4, v5
	v_cvt_pk_bf16_f32 v5, v6, v7
	v_mfma_f32_16x16x32_bf16 v[76:79], v[76:79], v[0:3], 0
	v_cvt_pk_bf16_f32 v9, v100, v101
	v_cvt_pk_bf16_f32 v11, v102, v103
	v_cvt_pk_bf16_f32 v80, v82, v83
	v_cvt_pk_bf16_f32 v81, v90, v91
	v_cvt_pk_bf16_f32 v82, v104, v105
	s_nop 2
	v_cvt_pk_bf16_f32 v6, v76, v77
	v_mul_f32_e32 v76, v87, v86
	v_mul_f32_e32 v76, v161, v76
	v_cvt_pk_bf16_f32 v83, v92, v93
	v_mfma_f32_16x16x32_bf16 v[8:11], v[8:11], v[0:3], 0
	s_waitcnt vmcnt(0)
	v_lshlrev_b32_e32 v70, 16, v74
	v_mul_f32_e32 v7, 0xbfb8aa3b, v70
	v_exp_f32_e32 v74, v7
	v_mfma_f32_16x16x32_bf16 v[12:15], v[12:15], v[80:83], 0
	v_cvt_pk_bf16_f32 v7, v78, v79
	v_add_f32_e32 v74, 1.0, v74
	v_rcp_f32_e32 v74, v74
	v_mfma_f32_16x16x32_bf16 v[64:67], v[64:67], v[0:3], 0
	s_nop 3
	v_cndmask_b32_e64 v15, v11, v15, s[46:47]
	v_cndmask_b32_e64 v77, v10, v14, s[44:45]
	v_mul_f32_e32 v70, v74, v70
	v_mul_f32_e32 v70, v76, v70
	v_cvt_pk_bf16_f32 v70, v70, s0
	global_store_short v[88:89], v70, off offset:1568
	global_load_ushort v70, v[84:85], off offset:3488
	v_cndmask_b32_e32 v74, v8, v12, vcc
	v_cndmask_b32_e64 v76, v13, v9, s[42:43]
	v_cvt_pk_bf16_f32 v12, v64, v65
	v_cvt_pk_bf16_f32 v13, v66, v67
	v_cvt_pk_bf16_f32 v14, v74, v76
	v_cvt_pk_bf16_f32 v15, v77, v15
	v_mfma_f32_16x16x32_bf16 v[28:31], v[4:7], v[28:31], 0
	s_nop 0
	v_mfma_f32_16x16x32_bf16 v[28:31], v[12:15], v[20:23], v[28:31]
	s_waitcnt vmcnt(0)
; __device__ __forceinline__ unsigned cvtpk(float lo, float hi) { f32x2_t v = {lo, hi}; bf16x2_t b = __builtin_convertvector(v, bf16x2_t); return __builtin_bit_cast(unsigned, b); }
; template <int X> __device__ __forceinline__ float swz_xor(float v) { return __int_as_float(__builtin_amdgcn_ds_swizzle(__float_as_int(v), (X << 10) | 0x1F)); }
; __device__ __forceinline__ float silu_f(float g) { return g * __builtin_amdgcn_rcpf(1.0f + __expf(-g)); }
; template <bool GLA>
; __device__ __forceinline__ void chunk_pass_c(const ChunkIn& ci, const float* wgl, int unit, unsigned char* wl, int lane, const float* Sb, const float* ng, bf16_t* omix) {
;     ...
;             f32x4 acc = {0.f, 0.f, 0.f, 0.f};
;             acc = __builtin_amdgcn_mfma_f32_16x16x32_bf16(af[0], vfr[et][0], acc, 0, 0, 0);
;             acc = __builtin_amdgcn_mfma_f32_16x16x32_bf16(af[1], vfr[et][1], acc, 0, 0, 0);
;             acc = __builtin_amdgcn_mfma_f32_16x16x32_bf16(qf[it], sfr[et], acc, 0, 0, 0);
;             o[et] = acc;
; #pragma unroll
;             for (int r = 0; r < 4; ++r) ss[r] += acc[r] * acc[r];
;         }
; #pragma unroll
;         for (int r = 0; r < 4; ++r) {
;             ss[r] += swz_xor<1>(ss[r]); ss[r] += swz_xor<2>(ss[r]); ss[r] += swz_xor<4>(ss[r]); ss[r] += swz_xor<8>(ss[r]);
;             const float rs = rsqrtf(ss[r] * (1.0f / 64.0f) + EPS);
;             const int t = t0 + 16 * it + 4 * kq + r;
; #pragma unroll
;             for (int et = 0; et < 4; ++et) {
;                 const int e = 16 * et + row;
;                 const float gt = __uint_as_float((unsigned)ci.proj[(size_t)t * DINP + gcol + e] << 16);
;                 const float val = o[et][r] * rs * gn[et] * pg8::silu_f(gt);
;                 omix[(size_t)t * 1024 + ocol + e] = (bf16_t)(cvtpk(val, 0.f) & 0xffffu);
;             }
;         }
	v_lshlrev_b32_e32 v22, 16, v70
	v_mul_f32_e32 v20, 0xbfb8aa3b, v22
	v_exp_f32_e32 v23, v20
	v_mfma_f32_16x16x32_bf16 v[44:47], v[4:7], v[44:47], 0
	v_lshl_add_u64 v[20:21], v[72:73], 0, v[112:113]
	v_add_f32_e32 v23, 1.0, v23
	v_mfma_f32_16x16x32_bf16 v[8:11], v[4:7], v[56:59], 0
	v_rcp_f32_e32 v23, v23
	v_mfma_f32_16x16x32_bf16 v[32:35], v[12:15], v[32:35], v[44:47]
	v_mfma_f32_16x16x32_bf16 v[44:47], v[12:15], v[52:55], v[8:11]
	s_nop 4
	v_mul_f32_e32 v8, v75, v86
	v_mul_f32_e32 v8, v160, v8
	v_mul_f32_e32 v9, v23, v22
	v_mul_f32_e32 v8, v8, v9
	v_cvt_pk_bf16_f32 v8, v8, s0
	global_store_short v[88:89], v8, off offset:1600
	global_load_ushort v8, v[20:21], off offset:3424
	v_mfma_f32_16x16x32_bf16 v[4:7], v[4:7], v[60:63], 0
	v_mov_b32_e32 v21, v211
	v_or_b32_e32 v20, s3, v97
	v_mfma_f32_16x16x32_bf16 v[48:51], v[12:15], v[48:51], v[4:7]
	v_mfma_f32_16x16x32_bf16 v[12:15], v[0:3], v[24:27], v[28:31]
	s_nop 3
	v_lshlrev_b64 v[4:5], 12, v[20:21]
	v_lshl_add_u64 v[22:23], s[58:59], 0, v[4:5]
	v_lshl_add_u64 v[24:25], v[22:23], 0, v[110:111]
	v_lshl_add_u64 v[22:23], v[22:23], 0, v[112:113]
	s_waitcnt vmcnt(0)
	v_lshlrev_b32_e32 v26, 16, v8
	v_mul_f32_e32 v4, 0xbfb8aa3b, v26
	v_exp_f32_e32 v4, v4
	v_mfma_f32_16x16x32_bf16 v[8:11], v[0:3], v[16:19], v[32:35]
	v_mul_f32_e32 v19, v71, v86
	v_mul_f32_e32 v19, v159, v19
	v_add_f32_e32 v4, 1.0, v4
	v_rcp_f32_e32 v18, v4
	v_lshl_add_u64 v[16:17], v[68:69], 0, v[112:113]
	v_mfma_f32_16x16x32_bf16 v[4:7], v[0:3], v[36:39], v[44:47]
	v_mul_f32_e32 v18, v18, v26
	v_mul_f32_e32 v18, v19, v18
	v_cvt_pk_bf16_f32 v18, v18, s0
	global_store_short v[16:17], v18, off offset:1536
	global_load_ushort v32, v[24:25], off offset:3424
	v_mfma_f32_16x16x32_bf16 v[0:3], v[0:3], v[40:43], v[48:51]
	v_mov_b32_e32 v16, v12
	v_mov_b32_e32 v17, v8
	v_mov_b32_e32 v18, v13
	v_mov_b32_e32 v19, v9
	v_mov_b32_e32 v26, v4
	s_nop 2
	v_mov_b32_e32 v27, v0
	v_mov_b32_e32 v28, v5
	v_mov_b32_e32 v29, v1
	v_pk_mul_f32 v[16:17], v[16:17], v[16:17]
	v_pk_mul_f32 v[18:19], v[18:19], v[18:19]
	v_pk_mul_f32 v[26:27], v[26:27], v[26:27]
	v_pk_mul_f32 v[28:29], v[28:29], v[28:29]
	v_mov_b32_e32 v30, v18
	v_mov_b32_e32 v31, v16
	v_mov_b32_e32 v16, v19
	v_mov_b32_e32 v18, v28
	v_mov_b32_e32 v19, v26
	v_pk_add_f32 v[16:17], v[30:31], v[16:17]
	v_mov_b32_e32 v26, v29
	v_pk_add_f32 v[16:17], v[16:17], v[18:19]
	s_nop 0
	v_pk_add_f32 v[16:17], v[16:17], v[26:27]
	ds_swizzle_b32 v19, v17 offset:swizzle(SWAP,1)
	ds_swizzle_b32 v18, v16 offset:swizzle(SWAP,1)
	v_lshlrev_b64 v[26:27], 11, v[20:21]
	s_waitcnt lgkmcnt(0)
	v_pk_add_f32 v[16:17], v[16:17], v[18:19]
	ds_swizzle_b32 v19, v17 offset:swizzle(SWAP,2)
	ds_swizzle_b32 v18, v16 offset:swizzle(SWAP,2)
	s_waitcnt lgkmcnt(0)
	v_pk_add_f32 v[16:17], v[16:17], v[18:19]
	ds_swizzle_b32 v19, v17 offset:swizzle(SWAP,4)
	ds_swizzle_b32 v18, v16 offset:swizzle(SWAP,4)
	s_waitcnt lgkmcnt(0)
	v_pk_add_f32 v[16:17], v[16:17], v[18:19]
	ds_swizzle_b32 v19, v17 offset:swizzle(SWAP,8)
	ds_swizzle_b32 v18, v16 offset:swizzle(SWAP,8)
	s_waitcnt lgkmcnt(0)
	v_pk_add_f32 v[16:17], v[16:17], v[18:19]
	s_nop 0
	v_pk_fma_f32 v[16:17], v[16:17], s[6:7], v[116:117] op_sel_hi:[1,0,0]
	s_waitcnt vmcnt(0)
	v_lshlrev_b32_e32 v21, 16, v32
	v_mul_f32_e32 v18, 0x4b800000, v17
	v_cmp_gt_f32_e32 vcc, s96, v17
	s_nop 1
	v_cndmask_b32_e32 v17, v17, v18, vcc
	v_mul_f32_e32 v18, 0xbfb8aa3b, v21
	v_exp_f32_e32 v28, v18
	v_rsq_f32_e32 v17, v17
	v_lshl_add_u64 v[18:19], s[60:61], 0, v[26:27]
	v_lshl_add_u64 v[26:27], v[18:19], 0, v[110:111]
	v_add_f32_e32 v28, 1.0, v28
	v_rcp_f32_e32 v28, v28
	v_mul_f32_e32 v29, 0x45800000, v17
	v_cndmask_b32_e32 v17, v17, v29, vcc
	v_mul_f32_e32 v12, v12, v17
	v_mul_f32_e32 v12, v115, v12
	v_mul_f32_e32 v21, v28, v21
	v_mul_f32_e32 v12, v21, v12
	v_cvt_pk_bf16_f32 v12, v12, s0
	global_store_short v[26:27], v12, off offset:1536
	global_load_ushort v12, v[24:25], off offset:3456
	v_mul_f32_e32 v8, v8, v17
	v_mul_f32_e32 v8, v161, v8
	v_mul_f32_e32 v4, v4, v17
	v_mul_f32_e32 v4, v160, v4
	v_mul_f32_e32 v0, v0, v17
	v_mul_f32_e32 v0, v159, v0
	v_lshl_add_u64 v[18:19], v[18:19], 0, v[112:113]
	v_cmp_gt_f32_e32 vcc, s96, v16
	s_waitcnt vmcnt(0)
	v_lshlrev_b32_e32 v12, 16, v12
	v_mul_f32_e32 v21, 0xbfb8aa3b, v12
	v_exp_f32_e32 v21, v21
	s_nop 0
	v_add_f32_e32 v21, 1.0, v21
	v_rcp_f32_e32 v21, v21
	s_nop 0
	v_mul_f32_e32 v12, v21, v12
	v_mul_f32_e32 v8, v12, v8
	v_cvt_pk_bf16_f32 v8, v8, s0
	global_store_short v[26:27], v8, off offset:1568
	global_load_ushort v8, v[24:25], off offset:3488
	s_waitcnt vmcnt(0)
	v_lshlrev_b32_e32 v8, 16, v8
	v_mul_f32_e32 v12, 0xbfb8aa3b, v8
	v_exp_f32_e32 v12, v12
	s_nop 0
	v_add_f32_e32 v12, 1.0, v12
	v_rcp_f32_e32 v12, v12
	s_nop 0
	v_mul_f32_e32 v8, v12, v8
	v_mul_f32_e32 v4, v4, v8
	v_cvt_pk_bf16_f32 v4, v4, s0
	global_store_short v[26:27], v4, off offset:1600
	global_load_ushort v4, v[22:23], off offset:3424
	v_mov_b32_e32 v23, v211
	v_or_b32_e32 v22, 1, v20
	v_lshlrev_b64 v[24:25], 12, v[22:23]
	v_lshl_add_u64 v[24:25], s[58:59], 0, v[24:25]
	v_lshl_add_u64 v[26:27], v[24:25], 0, v[110:111]
	s_waitcnt vmcnt(0)
	v_lshlrev_b32_e32 v4, 16, v4
	v_mul_f32_e32 v8, 0xbfb8aa3b, v4
	v_exp_f32_e32 v8, v8
	s_nop 0
	v_add_f32_e32 v8, 1.0, v8
	v_rcp_f32_e32 v8, v8
	s_nop 0
	v_mul_f32_e32 v4, v8, v4
	v_mul_f32_e32 v0, v0, v4
	v_cvt_pk_bf16_f32 v0, v0, s0
	global_store_short v[18:19], v0, off offset:1536
	global_load_ushort v0, v[26:27], off offset:3424
	v_mul_f32_e32 v4, 0x4b800000, v16
	v_cndmask_b32_e32 v4, v16, v4, vcc
	v_rsq_f32_e32 v4, v4
	v_lshlrev_b64 v[18:19], 11, v[22:23]
	v_lshl_add_u64 v[16:17], s[60:61], 0, v[18:19]
	v_lshl_add_u64 v[18:19], v[16:17], 0, v[110:111]
	v_mul_f32_e32 v12, 0x45800000, v4
	v_cndmask_b32_e32 v21, v4, v12, vcc
	v_mul_f32_e32 v4, v13, v21
	v_mul_f32_e32 v4, v115, v4
	v_mul_f32_e32 v5, v5, v21
	v_mul_f32_e32 v5, v160, v5
	v_lshl_add_u64 v[12:13], v[16:17], 0, v[112:113]
	v_mul_f32_e32 v1, v1, v21
	v_mul_f32_e32 v1, v159, v1
	v_mov_b32_e32 v22, v7
	v_mov_b32_e32 v23, v3
	v_pk_mul_f32 v[22:23], v[22:23], v[22:23]
	s_waitcnt vmcnt(0)
; __device__ __forceinline__ unsigned cvtpk(float lo, float hi) { f32x2_t v = {lo, hi}; bf16x2_t b = __builtin_convertvector(v, bf16x2_t); return __builtin_bit_cast(unsigned, b); }
; template <int X> __device__ __forceinline__ float swz_xor(float v) { return __int_as_float(__builtin_amdgcn_ds_swizzle(__float_as_int(v), (X << 10) | 0x1F)); }
; __device__ __forceinline__ float silu_f(float g) { return g * __builtin_amdgcn_rcpf(1.0f + __expf(-g)); }
; template <bool GLA>
; __device__ __forceinline__ void chunk_pass_c(const ChunkIn& ci, const float* wgl, int unit, unsigned char* wl, int lane, const float* Sb, const float* ng, bf16_t* omix) {
;     ...
; #pragma unroll
;         for (int r = 0; r < 4; ++r) {
;             ss[r] += swz_xor<1>(ss[r]); ss[r] += swz_xor<2>(ss[r]); ss[r] += swz_xor<4>(ss[r]); ss[r] += swz_xor<8>(ss[r]);
;             const float rs = rsqrtf(ss[r] * (1.0f / 64.0f) + EPS);
;             const int t = t0 + 16 * it + 4 * kq + r;
; #pragma unroll
;             for (int et = 0; et < 4; ++et) {
;                 const int e = 16 * et + row;
;                 const float gt = __uint_as_float((unsigned)ci.proj[(size_t)t * DINP + gcol + e] << 16);
;                 const float val = o[et][r] * rs * gn[et] * pg8::silu_f(gt);
;                 omix[(size_t)t * 1024 + ocol + e] = (bf16_t)(cvtpk(val, 0.f) & 0xffffu);
;             }
;         }
	v_lshlrev_b32_e32 v0, 16, v0
	v_mul_f32_e32 v8, 0xbfb8aa3b, v0
	v_exp_f32_e32 v8, v8
	s_nop 0
	v_add_f32_e32 v8, 1.0, v8
	v_rcp_f32_e32 v8, v8
	s_nop 0
	v_mul_f32_e32 v0, v8, v0
	v_mul_f32_e32 v0, v0, v4
	v_cvt_pk_bf16_f32 v0, v0, s0
	global_store_short v[18:19], v0, off offset:1536
	global_load_ushort v0, v[26:27], off offset:3456
	v_mul_f32_e32 v8, v9, v21
	v_mul_f32_e32 v8, v161, v8
	s_waitcnt vmcnt(0)
	v_lshlrev_b32_e32 v0, 16, v0
	v_mul_f32_e32 v4, 0xbfb8aa3b, v0
	v_exp_f32_e32 v4, v4
	s_nop 0
	v_add_f32_e32 v4, 1.0, v4
	v_rcp_f32_e32 v4, v4
	s_nop 0
	v_mul_f32_e32 v0, v4, v0
	v_mul_f32_e32 v0, v8, v0
	v_cvt_pk_bf16_f32 v0, v0, s0
	global_store_short v[18:19], v0, off offset:1568
	global_load_ushort v0, v[26:27], off offset:3488
	v_lshl_add_u64 v[8:9], v[24:25], 0, v[112:113]
	s_waitcnt vmcnt(0)
	v_lshlrev_b32_e32 v0, 16, v0
	v_mul_f32_e32 v4, 0xbfb8aa3b, v0
	v_exp_f32_e32 v4, v4
	s_nop 0
	v_add_f32_e32 v4, 1.0, v4
	v_rcp_f32_e32 v4, v4
	s_nop 0
	v_mul_f32_e32 v0, v4, v0
	v_mul_f32_e32 v0, v5, v0
	v_cvt_pk_bf16_f32 v0, v0, s0
	global_store_short v[18:19], v0, off offset:1600
	global_load_ushort v0, v[8:9], off offset:3424
	v_mov_b32_e32 v5, v211
	v_or_b32_e32 v4, 2, v20
	v_mov_b32_e32 v19, v2
	s_waitcnt vmcnt(0)
	v_lshlrev_b32_e32 v0, 16, v0
	v_mul_f32_e32 v8, 0xbfb8aa3b, v0
	v_exp_f32_e32 v18, v8
	v_lshlrev_b64 v[8:9], 12, v[4:5]
	v_lshl_add_u64 v[8:9], s[58:59], 0, v[8:9]
	v_lshlrev_b64 v[4:5], 11, v[4:5]
	v_add_f32_e32 v16, 1.0, v18
	v_rcp_f32_e32 v18, v16
	v_lshl_add_u64 v[16:17], v[8:9], 0, v[110:111]
	v_lshl_add_u64 v[4:5], s[60:61], 0, v[4:5]
	v_lshl_add_u64 v[8:9], v[8:9], 0, v[112:113]
	v_mul_f32_e32 v0, v18, v0
	v_mul_f32_e32 v0, v1, v0
	v_cvt_pk_bf16_f32 v0, v0, s0
	global_store_short v[12:13], v0, off offset:1536
	global_load_ushort v21, v[16:17], off offset:3424
	v_mov_b32_e32 v0, v14
	v_mov_b32_e32 v1, v10
	v_mov_b32_e32 v12, v15
	v_mov_b32_e32 v13, v11
	v_mov_b32_e32 v18, v6
	v_pk_mul_f32 v[0:1], v[0:1], v[0:1]
	v_pk_mul_f32 v[12:13], v[12:13], v[12:13]
	v_pk_mul_f32 v[18:19], v[18:19], v[18:19]
	v_mov_b32_e32 v24, v12
	v_mov_b32_e32 v25, v0
	v_mov_b32_e32 v0, v13
	v_mov_b32_e32 v12, v22
	v_mov_b32_e32 v13, v18
	v_pk_add_f32 v[0:1], v[24:25], v[0:1]
	v_mov_b32_e32 v18, v23
	v_pk_add_f32 v[0:1], v[0:1], v[12:13]
	s_nop 0
	v_pk_add_f32 v[0:1], v[0:1], v[18:19]
	ds_swizzle_b32 v13, v1 offset:swizzle(SWAP,1)
	ds_swizzle_b32 v12, v0 offset:swizzle(SWAP,1)
	s_waitcnt lgkmcnt(0)
	v_pk_add_f32 v[0:1], v[0:1], v[12:13]
	ds_swizzle_b32 v13, v1 offset:swizzle(SWAP,2)
	ds_swizzle_b32 v12, v0 offset:swizzle(SWAP,2)
	s_waitcnt lgkmcnt(0)
	v_pk_add_f32 v[0:1], v[0:1], v[12:13]
	ds_swizzle_b32 v13, v1 offset:swizzle(SWAP,4)
	ds_swizzle_b32 v12, v0 offset:swizzle(SWAP,4)
	s_waitcnt lgkmcnt(0)
	v_pk_add_f32 v[0:1], v[0:1], v[12:13]
	ds_swizzle_b32 v13, v1 offset:swizzle(SWAP,8)
	ds_swizzle_b32 v12, v0 offset:swizzle(SWAP,8)
	s_waitcnt lgkmcnt(0)
	v_pk_add_f32 v[0:1], v[0:1], v[12:13]
	s_nop 0
	v_pk_fma_f32 v[0:1], v[0:1], s[6:7], v[116:117] op_sel_hi:[1,0,0]
	s_mov_b64 s[6:7], 0
	v_mul_f32_e32 v12, 0x4b800000, v1
	v_cmp_gt_f32_e32 vcc, s96, v1
	s_waitcnt vmcnt(0)
	v_lshlrev_b32_e32 v18, 16, v21
	v_cndmask_b32_e32 v1, v1, v12, vcc
	v_mul_f32_e32 v12, 0xbfb8aa3b, v18
	v_exp_f32_e32 v19, v12
	v_rsq_f32_e32 v1, v1
	v_lshl_add_u64 v[12:13], v[4:5], 0, v[110:111]
	v_lshl_add_u64 v[4:5], v[4:5], 0, v[112:113]
	v_add_f32_e32 v19, 1.0, v19
	v_rcp_f32_e32 v19, v19
	v_mul_f32_e32 v21, 0x45800000, v1
	v_cndmask_b32_e32 v1, v1, v21, vcc
	v_mul_f32_e32 v14, v14, v1
	v_mul_f32_e32 v14, v115, v14
	v_mul_f32_e32 v18, v19, v18
	v_mul_f32_e32 v14, v18, v14
	v_cvt_pk_bf16_f32 v14, v14, s0
	global_store_short v[12:13], v14, off offset:1536
	global_load_ushort v14, v[16:17], off offset:3456
	v_mul_f32_e32 v10, v10, v1
	v_mul_f32_e32 v10, v161, v10
	v_mul_f32_e32 v6, v6, v1
	v_mul_f32_e32 v6, v160, v6
	v_mul_f32_e32 v1, v2, v1
	v_mul_f32_e32 v1, v159, v1
	v_cmp_gt_f32_e32 vcc, s96, v0
	s_waitcnt vmcnt(0)
; __device__ __forceinline__ unsigned cvtpk(float lo, float hi) { f32x2_t v = {lo, hi}; bf16x2_t b = __builtin_convertvector(v, bf16x2_t); return __builtin_bit_cast(unsigned, b); }
; __device__ __forceinline__ float silu_f(float g) { return g * __builtin_amdgcn_rcpf(1.0f + __expf(-g)); }
; template <bool GLA>
; __device__ __forceinline__ void chunk_pass_c(const ChunkIn& ci, const float* wgl, int unit, unsigned char* wl, int lane, const float* Sb, const float* ng, bf16_t* omix) {
;     ...
;                 const float gt = __uint_as_float((unsigned)ci.proj[(size_t)t * DINP + gcol + e] << 16);
;                 const float val = o[et][r] * rs * gn[et] * pg8::silu_f(gt);
;                 omix[(size_t)t * 1024 + ocol + e] = (bf16_t)(cvtpk(val, 0.f) & 0xffffu);
;             }
;         }
;     }
;     __builtin_amdgcn_s_waitcnt(0); asm volatile("" ::: "memory");
	v_lshlrev_b32_e32 v14, 16, v14
	v_mul_f32_e32 v18, 0xbfb8aa3b, v14
	v_exp_f32_e32 v18, v18
	s_nop 0
	v_add_f32_e32 v18, 1.0, v18
	v_rcp_f32_e32 v18, v18
	s_nop 0
	v_mul_f32_e32 v14, v18, v14
	v_mul_f32_e32 v10, v10, v14
	v_cvt_pk_bf16_f32 v10, v10, s0
	global_store_short v[12:13], v10, off offset:1568
	global_load_ushort v10, v[16:17], off offset:3488
	s_waitcnt vmcnt(0)
	v_lshlrev_b32_e32 v10, 16, v10
	v_mul_f32_e32 v14, 0xbfb8aa3b, v10
	v_exp_f32_e32 v14, v14
	s_nop 0
	v_add_f32_e32 v14, 1.0, v14
	v_rcp_f32_e32 v14, v14
	s_nop 0
	v_mul_f32_e32 v10, v14, v10
	v_mul_f32_e32 v6, v6, v10
	v_cvt_pk_bf16_f32 v6, v6, s0
	global_store_short v[12:13], v6, off offset:1600
	global_load_ushort v6, v[8:9], off offset:3424
	v_mov_b32_e32 v9, v211
	v_or_b32_e32 v8, 3, v20
	v_lshlrev_b64 v[12:13], 12, v[8:9]
	v_lshl_add_u64 v[12:13], s[58:59], 0, v[12:13]
	v_lshl_add_u64 v[16:17], v[12:13], 0, v[110:111]
	s_waitcnt vmcnt(0)
	v_lshlrev_b32_e32 v6, 16, v6
	v_mul_f32_e32 v10, 0xbfb8aa3b, v6
	v_exp_f32_e32 v10, v10
	s_nop 0
	v_add_f32_e32 v10, 1.0, v10
	v_rcp_f32_e32 v10, v10
	s_nop 0
	v_mul_f32_e32 v2, v10, v6
	v_mul_f32_e32 v1, v1, v2
	v_cvt_pk_bf16_f32 v1, v1, s0
	global_store_short v[4:5], v1, off offset:1536
	global_load_ushort v1, v[16:17], off offset:3424
	v_mul_f32_e32 v2, 0x4b800000, v0
	v_cndmask_b32_e32 v0, v0, v2, vcc
	v_rsq_f32_e32 v2, v0
	v_lshlrev_b64 v[4:5], 11, v[8:9]
	v_mul_f32_e32 v9, 0x45800000, v2
	v_cndmask_b32_e32 v2, v2, v9, vcc
	v_mul_f32_e32 v9, v15, v2
	v_mul_f32_e32 v9, v115, v9
	v_mul_f32_e32 v7, v7, v2
	v_mul_f32_e32 v7, v160, v7
	s_waitcnt vmcnt(0)
	v_lshlrev_b32_e32 v6, 16, v1
	v_mul_f32_e32 v0, 0xbfb8aa3b, v6
	v_exp_f32_e32 v8, v0
	v_lshl_add_u64 v[0:1], s[60:61], 0, v[4:5]
	v_lshl_add_u64 v[4:5], v[0:1], 0, v[110:111]
	v_lshl_add_u64 v[0:1], v[0:1], 0, v[112:113]
	v_add_f32_e32 v8, 1.0, v8
	v_rcp_f32_e32 v8, v8
	s_nop 0
	v_mul_f32_e32 v6, v8, v6
	v_mul_f32_e32 v6, v6, v9
	v_cvt_pk_bf16_f32 v6, v6, s0
	global_store_short v[4:5], v6, off offset:1536
	global_load_ushort v6, v[16:17], off offset:3456
	v_mul_f32_e32 v9, v11, v2
	v_mul_f32_e32 v9, v161, v9
	v_mul_f32_e32 v2, v3, v2
	v_mul_f32_e32 v2, v159, v2
	s_waitcnt vmcnt(0)
	v_lshlrev_b32_e32 v6, 16, v6
	v_mul_f32_e32 v8, 0xbfb8aa3b, v6
	v_exp_f32_e32 v8, v8
	s_nop 0
	v_add_f32_e32 v8, 1.0, v8
	v_rcp_f32_e32 v8, v8
	s_nop 0
	v_mul_f32_e32 v6, v8, v6
	v_mul_f32_e32 v6, v9, v6
	v_cvt_pk_bf16_f32 v6, v6, s0
	global_store_short v[4:5], v6, off offset:1568
	global_load_ushort v6, v[16:17], off offset:3488
	s_waitcnt vmcnt(0)
	v_lshlrev_b32_e32 v6, 16, v6
	v_mul_f32_e32 v8, 0xbfb8aa3b, v6
	v_exp_f32_e32 v8, v8
	s_nop 0
	v_add_f32_e32 v8, 1.0, v8
	v_rcp_f32_e32 v10, v8
	v_lshl_add_u64 v[8:9], v[12:13], 0, v[112:113]
	v_mul_f32_e32 v6, v10, v6
	v_mul_f32_e32 v6, v7, v6
	v_cvt_pk_bf16_f32 v6, v6, s0
	global_store_short v[4:5], v6, off offset:1600
	global_load_ushort v4, v[8:9], off offset:3424
	s_waitcnt vmcnt(0)
	v_lshlrev_b32_e32 v4, 16, v4
	v_mul_f32_e32 v5, 0xbfb8aa3b, v4
	v_exp_f32_e32 v5, v5
	s_nop 0
	v_add_f32_e32 v5, 1.0, v5
	v_rcp_f32_e32 v5, v5
	s_nop 0
	v_mul_f32_e32 v3, v5, v4
	v_mul_f32_e32 v2, v2, v3
	v_cvt_pk_bf16_f32 v2, v2, s0
	global_store_short v[0:1], v2, off offset:1536
	s_waitcnt lgkmcnt(0)

; template <bool GLA>
; __device__ __forceinline__ void chunk_pass_a(const ChunkIn& ci, const float* wgl, int unit, unsigned char* wl, int lane, float* dS, float* dec) {
;     ...
;     if (row == 0) {
; #pragma unroll
;         for (int j = 0; j < 8; ++j) { const int d = (j < 4) ? (4 * kq + j) : (16 + 4 * kq + (j - 4)); dec[(size_t)unit * 32 + d] = __expf(carry[j]); }
;     }
;     __builtin_amdgcn_s_waitcnt(0); asm volatile("" ::: "memory");
.LBB0_567:
	s_or_b64 exec, exec, s[6:7]
	s_waitcnt lgkmcnt(0)
	s_mov_b64 s[6:7], 0
